# static s_setprio 1 for waves 4-7 before each GEMM K-loop, per-MFMA-block priority flips deleted
# baseline (speedup 1.0000x reference)
.LBB0_164:
	s_lshl_b32 s26, s8, 6
	v_ashrrev_i32_e32 v14, 6, v144
	s_lshl_b32 s8, s8, 13
	v_lshl_add_u32 v16, v14, 10, s8
	s_lshl_b32 s8, s88, 5
	s_and_b32 s20, s8, 0x60
	s_lshr_b32 s8, s20, 3
	v_add_lshl_u32 v14, v14, s8, 10
	s_mov_b64 s[8:9], 0x80
	s_add_i32 m0, s23, 0x18000
	v_lshl_add_u64 v[6:7], v[6:7], 0, s[8:9]
	s_waitcnt vmcnt(2)
	s_barrier
	global_load_lds_dwordx4 v[6:7], off
	v_lshl_add_u64 v[4:5], v[4:5], 0, s[8:9]
	s_add_i32 m0, s23, 0x1a000
	s_add_i32 s30, s23, 0x8000
	s_add_i32 s31, s23, 0xa000
	global_load_lds_dwordx4 v[4:5], off
	v_lshl_add_u64 v[2:3], v[2:3], 0, s[8:9]
	s_mov_b32 m0, s30
	s_add_u32 s16, s2, 0x80080
	global_load_lds_dwordx4 v[2:3], off
	v_lshl_add_u64 v[0:1], v[0:1], 0, s[8:9]
	s_mov_b32 m0, s31
	s_addc_u32 s17, s3, 0
	global_load_lds_dwordx4 v[0:1], off
	s_add_i32 m0, s23, 0x1c000
	v_lshl_add_u64 v[0:1], s[16:17], 0, v[130:131]
	global_load_lds_dwordx4 v[0:1], off
	v_lshl_add_u64 v[0:1], s[16:17], 0, v[134:135]
	s_add_i32 m0, s23, 0x1e000
	s_add_u32 s10, s94, s10
	global_load_lds_dwordx4 v[0:1], off
	v_lshlrev_b32_e32 v0, 15, v8
	v_and_b32_e32 v0, 0xffff0000, v0
	v_lshl_add_u32 v0, v9, 12, v0
	v_and_b32_e32 v1, 1, v8
	v_lshl_or_b32 v0, v1, 6, v0
	s_addc_u32 s11, s95, 0
	v_lshl_add_u32 v0, v10, 1, v0
	v_mov_b32_e32 v1, v131
	v_lshl_add_u64 v[0:1], s[10:11], 0, v[0:1]
	s_mov_b64 s[16:17], 0x11280080
	v_lshl_add_u64 v[136:137], v[0:1], 0, s[16:17]
	v_lshlrev_b32_e32 v0, 15, v11
	v_and_b32_e32 v0, 0xffff0000, v0
	v_lshl_add_u32 v0, v12, 12, v0
	v_and_b32_e32 v1, 1, v11
	v_lshl_or_b32 v0, v1, 6, v0
	v_lshl_add_u32 v0, v13, 1, v0
	v_mov_b32_e32 v1, v131
	v_lshl_add_u64 v[0:1], s[10:11], 0, v[0:1]
	v_lshl_add_u64 v[138:139], v[0:1], 0, s[16:17]
	s_lshl_b32 s15, s49, 18
	s_lshl_b32 s16, s62, 16
	s_and_b32 s15, s15, 0xe00000
	s_and_b32 s16, s16, 0x100000
	s_or_b32 s15, s15, s16
	s_add_u32 s12, s12, s15
	s_addc_u32 s13, s13, 0
	s_add_u32 s12, s94, s12
	v_and_b32_e32 v140, 15, v144
	v_and_b32_e32 v15, 48, v144
	v_lshlrev_b32_e32 v17, 2, v144
	s_addc_u32 s13, s95, s13
	v_lshl_or_b32 v15, v140, 6, v15
	v_and_b32_e32 v17, 32, v17
	s_add_u32 s34, s12, 0x4200100
	v_bitop3_b32 v14, v15, v14, v17 bitop3:0xde
	s_waitcnt vmcnt(6)
	s_addc_u32 s35, s13, 0
	s_add_i32 s39, 0, 0x10000
	s_add_i32 s41, 0, 0x14000
	s_add_i32 s43, 0, 0x18000
	s_add_i32 s45, 0, 0x1c000
	v_bitop3_b32 v16, v15, v16, v17 bitop3:0xde
	v_add_u32_e32 v141, s39, v14
	v_add_u32_e32 v142, s41, v14
	s_add_i32 s39, s39, s14
	s_add_i32 s41, s41, s14
	v_add_u32_e32 v145, s43, v14
	v_add_u32_e32 v146, s45, v14
	s_add_i32 s43, s43, s14
	s_add_i32 s45, s45, s14
	s_mov_b32 s36, -2
	s_mov_b64 s[12:13], 0
	v_add_u32_e32 v143, 0, v16
	s_add_i32 s37, s23, 0xc000
	s_add_i32 s38, s23, 0xe000
	s_add_i32 s40, s39, 0x2000
	s_add_i32 s42, s41, 0x2000
	s_add_i32 s44, s43, 0x2000
	s_add_i32 s46, s45, 0x2000
	v_mov_b32_e32 v0, v131
	v_mov_b32_e32 v1, v131
	v_mov_b32_e32 v2, v131
	v_mov_b32_e32 v3, v131
	v_mov_b32_e32 v4, v131
	v_mov_b32_e32 v5, v131
	v_mov_b32_e32 v6, v131
	v_mov_b32_e32 v7, v131
	v_mov_b32_e32 v16, v131
	v_mov_b32_e32 v17, v131
	v_mov_b32_e32 v18, v131
	v_mov_b32_e32 v19, v131
	v_mov_b32_e32 v20, v131
	v_mov_b32_e32 v21, v131
	v_mov_b32_e32 v22, v131
	v_mov_b32_e32 v23, v131
	v_mov_b32_e32 v32, v131
	v_mov_b32_e32 v33, v131
	v_mov_b32_e32 v34, v131
	v_mov_b32_e32 v35, v131
	v_mov_b32_e32 v36, v131
	v_mov_b32_e32 v37, v131
	v_mov_b32_e32 v38, v131
	v_mov_b32_e32 v39, v131
	v_mov_b32_e32 v48, v131
	v_mov_b32_e32 v49, v131
	v_mov_b32_e32 v50, v131
	v_mov_b32_e32 v51, v131
	v_mov_b32_e32 v52, v131
	v_mov_b32_e32 v53, v131
	v_mov_b32_e32 v54, v131
	v_mov_b32_e32 v55, v131
	v_mov_b32_e32 v8, v131
	v_mov_b32_e32 v9, v131
	v_mov_b32_e32 v10, v131
	v_mov_b32_e32 v11, v131
	v_mov_b32_e32 v12, v131
	v_mov_b32_e32 v13, v131
	v_mov_b32_e32 v14, v131
	v_mov_b32_e32 v15, v131
	v_mov_b32_e32 v24, v131
	v_mov_b32_e32 v25, v131
	v_mov_b32_e32 v26, v131
	v_mov_b32_e32 v27, v131
	v_mov_b32_e32 v28, v131
	v_mov_b32_e32 v29, v131
	v_mov_b32_e32 v30, v131
	v_mov_b32_e32 v31, v131
	v_mov_b32_e32 v40, v131
	v_mov_b32_e32 v41, v131
	v_mov_b32_e32 v42, v131
	v_mov_b32_e32 v43, v131
	v_mov_b32_e32 v44, v131
	v_mov_b32_e32 v45, v131
	v_mov_b32_e32 v46, v131
	v_mov_b32_e32 v47, v131
	v_mov_b32_e32 v56, v131
	v_mov_b32_e32 v57, v131
	v_mov_b32_e32 v58, v131
	v_mov_b32_e32 v59, v131
	v_mov_b32_e32 v60, v131
	v_mov_b32_e32 v61, v131
	v_mov_b32_e32 v62, v131
	v_mov_b32_e32 v63, v131
	v_mov_b32_e32 v64, v131
	v_mov_b32_e32 v65, v131
	v_mov_b32_e32 v66, v131
	v_mov_b32_e32 v67, v131
	v_mov_b32_e32 v68, v131
	v_mov_b32_e32 v69, v131
	v_mov_b32_e32 v70, v131
	v_mov_b32_e32 v71, v131
	v_mov_b32_e32 v80, v131
	v_mov_b32_e32 v81, v131
	v_mov_b32_e32 v82, v131
	v_mov_b32_e32 v83, v131
	v_mov_b32_e32 v84, v131
	v_mov_b32_e32 v85, v131
	v_mov_b32_e32 v86, v131
	v_mov_b32_e32 v87, v131
	v_mov_b32_e32 v96, v131
	v_mov_b32_e32 v97, v131
	v_mov_b32_e32 v98, v131
	v_mov_b32_e32 v99, v131
	v_mov_b32_e32 v100, v131
	v_mov_b32_e32 v101, v131
	v_mov_b32_e32 v102, v131
	v_mov_b32_e32 v103, v131
	v_mov_b32_e32 v112, v131
	v_mov_b32_e32 v113, v131
	v_mov_b32_e32 v114, v131
	v_mov_b32_e32 v115, v131
	v_mov_b32_e32 v116, v131
	v_mov_b32_e32 v117, v131
	v_mov_b32_e32 v118, v131
	v_mov_b32_e32 v119, v131
	v_mov_b32_e32 v72, v131
	v_mov_b32_e32 v73, v131
	v_mov_b32_e32 v74, v131
	v_mov_b32_e32 v75, v131
	v_mov_b32_e32 v76, v131
	v_mov_b32_e32 v77, v131
	v_mov_b32_e32 v78, v131
	v_mov_b32_e32 v79, v131
	v_mov_b32_e32 v88, v131
	v_mov_b32_e32 v89, v131
	v_mov_b32_e32 v90, v131
	v_mov_b32_e32 v91, v131
	v_mov_b32_e32 v92, v131
	v_mov_b32_e32 v93, v131
	v_mov_b32_e32 v94, v131
	v_mov_b32_e32 v95, v131
	v_mov_b32_e32 v104, v131
	v_mov_b32_e32 v105, v131
	v_mov_b32_e32 v106, v131
	v_mov_b32_e32 v107, v131
	v_mov_b32_e32 v108, v131
	v_mov_b32_e32 v109, v131
	v_mov_b32_e32 v110, v131
	v_mov_b32_e32 v111, v131
	v_mov_b32_e32 v120, v131
	v_mov_b32_e32 v121, v131
	v_mov_b32_e32 v122, v131
	v_mov_b32_e32 v123, v131
	v_mov_b32_e32 v124, v131
	v_mov_b32_e32 v125, v131
	v_mov_b32_e32 v126, v131
	v_mov_b32_e32 v127, v131
	s_barrier
	s_lshr_b32 s101, s88, 2
	s_cmp_lg_u32 s101, 1
	s_cbranch_scc1 .Lprio_skip0
	s_setprio 1
.Lprio_skip0:
.LBB0_165:
	ds_read_b128 v[148:151], v141
	ds_read_b128 v[152:155], v141 offset:1024
	ds_read_b128 v[156:159], v141 offset:2048
	ds_read_b128 v[160:163], v141 offset:3072
	ds_read_b128 v[164:167], v142
	ds_read_b128 v[168:171], v142 offset:1024
	ds_read_b128 v[172:175], v142 offset:2048
	ds_read_b128 v[176:179], v142 offset:3072
	s_add_u32 s14, s10, s12
	s_addc_u32 s15, s11, s13
	s_add_u32 s14, s14, 0x11200100
	s_addc_u32 s15, s15, 0
	s_add_u32 s47, s34, s12
	s_addc_u32 s50, s35, s13
	s_cmpk_eq_i32 s12, 0xf00
	s_cselect_b32 s17, s7, s15
	s_cselect_b32 s16, s6, s14
	s_cselect_b32 s15, s3, s50
	s_cselect_b32 s14, s2, s47
	s_mov_b32 m0, s37
	v_lshl_add_u64 v[212:213], v[136:137], 0, s[12:13]
	ds_read_b128 v[180:183], v143
	ds_read_b128 v[184:187], v143 offset:1024
	ds_read_b128 v[188:191], v143 offset:2048
	ds_read_b128 v[192:195], v143 offset:3072
	ds_read_b128 v[196:199], v143 offset:4096
	ds_read_b128 v[200:203], v143 offset:5120
	ds_read_b128 v[204:207], v143 offset:6144
	ds_read_b128 v[208:211], v143 offset:7168
	global_load_lds_dwordx4 v[212:213], off
	v_lshl_add_u64 v[212:213], v[138:139], 0, s[12:13]
	s_mov_b32 m0, s38
	s_nop 0
	global_load_lds_dwordx4 v[212:213], off
	s_waitcnt vmcnt(8)
	s_waitcnt lgkmcnt(0)
	s_barrier
	s_waitcnt lgkmcnt(0)
	v_mfma_f32_16x16x32_bf16 v[124:127], v[148:151], v[180:183], v[124:127]
	v_mfma_f32_16x16x32_bf16 v[120:123], v[156:159], v[180:183], v[120:123]
	v_mfma_f32_16x16x32_bf16 v[108:111], v[148:151], v[188:191], v[108:111]
	v_mfma_f32_16x16x32_bf16 v[104:107], v[156:159], v[188:191], v[104:107]
	v_mfma_f32_16x16x32_bf16 v[92:95], v[148:151], v[196:199], v[92:95]
	v_mfma_f32_16x16x32_bf16 v[88:91], v[156:159], v[196:199], v[88:91]
	v_mfma_f32_16x16x32_bf16 v[76:79], v[148:151], v[204:207], v[76:79]
	v_mfma_f32_16x16x32_bf16 v[72:75], v[156:159], v[204:207], v[72:75]
	v_mfma_f32_16x16x32_bf16 v[124:127], v[152:155], v[184:187], v[124:127]
	v_mfma_f32_16x16x32_bf16 v[120:123], v[160:163], v[184:187], v[120:123]
	v_mfma_f32_16x16x32_bf16 v[108:111], v[152:155], v[192:195], v[108:111]
	v_mfma_f32_16x16x32_bf16 v[104:107], v[160:163], v[192:195], v[104:107]
	v_mfma_f32_16x16x32_bf16 v[92:95], v[152:155], v[200:203], v[92:95]
	v_mfma_f32_16x16x32_bf16 v[88:91], v[160:163], v[200:203], v[88:91]
	v_mfma_f32_16x16x32_bf16 v[76:79], v[152:155], v[208:211], v[76:79]
	v_mfma_f32_16x16x32_bf16 v[72:75], v[160:163], v[208:211], v[72:75]
	v_mfma_f32_16x16x32_bf16 v[116:119], v[164:167], v[180:183], v[116:119]
	v_mfma_f32_16x16x32_bf16 v[112:115], v[172:175], v[180:183], v[112:115]
	v_mfma_f32_16x16x32_bf16 v[100:103], v[164:167], v[188:191], v[100:103]
	v_mfma_f32_16x16x32_bf16 v[96:99], v[172:175], v[188:191], v[96:99]
	v_mfma_f32_16x16x32_bf16 v[84:87], v[164:167], v[196:199], v[84:87]
	v_mfma_f32_16x16x32_bf16 v[80:83], v[172:175], v[196:199], v[80:83]
	v_mfma_f32_16x16x32_bf16 v[68:71], v[164:167], v[204:207], v[68:71]
	v_mfma_f32_16x16x32_bf16 v[64:67], v[172:175], v[204:207], v[64:67]
	v_mfma_f32_16x16x32_bf16 v[116:119], v[168:171], v[184:187], v[116:119]
	v_mfma_f32_16x16x32_bf16 v[112:115], v[176:179], v[184:187], v[112:115]
	v_mfma_f32_16x16x32_bf16 v[100:103], v[168:171], v[192:195], v[100:103]
	v_mfma_f32_16x16x32_bf16 v[96:99], v[176:179], v[192:195], v[96:99]
	v_mfma_f32_16x16x32_bf16 v[84:87], v[168:171], v[200:203], v[84:87]
	v_mfma_f32_16x16x32_bf16 v[80:83], v[176:179], v[200:203], v[80:83]
	v_mfma_f32_16x16x32_bf16 v[68:71], v[168:171], v[208:211], v[68:71]
	v_mfma_f32_16x16x32_bf16 v[64:67], v[176:179], v[208:211], v[64:67]
	s_barrier
	s_mov_b32 m0, s39
	v_lshl_add_u64 v[212:213], s[14:15], 0, v[130:131]
	s_add_u32 s50, s14, 0x80000
	ds_read_b128 v[180:183], v143 offset:16384
	ds_read_b128 v[184:187], v143 offset:17408
	ds_read_b128 v[188:191], v143 offset:18432
	ds_read_b128 v[192:195], v143 offset:19456
	ds_read_b128 v[196:199], v143 offset:20480
	ds_read_b128 v[200:203], v143 offset:21504
	ds_read_b128 v[204:207], v143 offset:22528
	ds_read_b128 v[208:211], v143 offset:23552
	global_load_lds_dwordx4 v[212:213], off
	v_lshl_add_u64 v[214:215], s[14:15], 0, v[134:135]
	s_mov_b32 m0, s40
	s_addc_u32 s51, s15, 0
	global_load_lds_dwordx4 v[214:215], off
	v_lshl_add_u64 v[216:217], s[50:51], 0, v[130:131]
	s_mov_b32 m0, s41
	v_lshl_add_u64 v[218:219], s[16:17], 0, v[132:133]
	global_load_lds_dwordx4 v[216:217], off
	v_lshl_add_u64 v[216:217], s[50:51], 0, v[134:135]
	s_mov_b32 m0, s42
	s_nop 0
	global_load_lds_dwordx4 v[216:217], off
	v_lshl_add_u64 v[216:217], s[16:17], 0, v[128:129]
	s_mov_b32 m0, s23
	s_nop 0
	global_load_lds_dwordx4 v[216:217], off
	s_mov_b32 m0, s27
	s_nop 0
	global_load_lds_dwordx4 v[218:219], off
	s_waitcnt vmcnt(8)
	s_waitcnt lgkmcnt(0)
	s_barrier
	s_waitcnt lgkmcnt(0)
	v_mfma_f32_16x16x32_bf16 v[60:63], v[148:151], v[180:183], v[60:63]
	v_mfma_f32_16x16x32_bf16 v[56:59], v[156:159], v[180:183], v[56:59]
	v_mfma_f32_16x16x32_bf16 v[44:47], v[148:151], v[188:191], v[44:47]
	v_mfma_f32_16x16x32_bf16 v[40:43], v[156:159], v[188:191], v[40:43]
	v_mfma_f32_16x16x32_bf16 v[28:31], v[148:151], v[196:199], v[28:31]
	v_mfma_f32_16x16x32_bf16 v[24:27], v[156:159], v[196:199], v[24:27]
	v_mfma_f32_16x16x32_bf16 v[12:15], v[148:151], v[204:207], v[12:15]
	v_mfma_f32_16x16x32_bf16 v[8:11], v[156:159], v[204:207], v[8:11]
	v_mfma_f32_16x16x32_bf16 v[60:63], v[152:155], v[184:187], v[60:63]
	v_mfma_f32_16x16x32_bf16 v[56:59], v[160:163], v[184:187], v[56:59]
	v_mfma_f32_16x16x32_bf16 v[44:47], v[152:155], v[192:195], v[44:47]
	v_mfma_f32_16x16x32_bf16 v[40:43], v[160:163], v[192:195], v[40:43]
	v_mfma_f32_16x16x32_bf16 v[28:31], v[152:155], v[200:203], v[28:31]
	v_mfma_f32_16x16x32_bf16 v[24:27], v[160:163], v[200:203], v[24:27]
	v_mfma_f32_16x16x32_bf16 v[12:15], v[152:155], v[208:211], v[12:15]
	v_mfma_f32_16x16x32_bf16 v[8:11], v[160:163], v[208:211], v[8:11]
	v_mfma_f32_16x16x32_bf16 v[52:55], v[164:167], v[180:183], v[52:55]
	v_mfma_f32_16x16x32_bf16 v[48:51], v[172:175], v[180:183], v[48:51]
	v_mfma_f32_16x16x32_bf16 v[36:39], v[164:167], v[188:191], v[36:39]
	v_mfma_f32_16x16x32_bf16 v[32:35], v[172:175], v[188:191], v[32:35]
	v_mfma_f32_16x16x32_bf16 v[20:23], v[164:167], v[196:199], v[20:23]
	v_mfma_f32_16x16x32_bf16 v[16:19], v[172:175], v[196:199], v[16:19]
	v_mfma_f32_16x16x32_bf16 v[4:7], v[164:167], v[204:207], v[4:7]
	v_mfma_f32_16x16x32_bf16 v[0:3], v[172:175], v[204:207], v[0:3]
	v_mfma_f32_16x16x32_bf16 v[52:55], v[168:171], v[184:187], v[52:55]
	v_mfma_f32_16x16x32_bf16 v[48:51], v[176:179], v[184:187], v[48:51]
	v_mfma_f32_16x16x32_bf16 v[36:39], v[168:171], v[192:195], v[36:39]
	v_mfma_f32_16x16x32_bf16 v[32:35], v[176:179], v[192:195], v[32:35]
	v_mfma_f32_16x16x32_bf16 v[20:23], v[168:171], v[200:203], v[20:23]
	v_mfma_f32_16x16x32_bf16 v[16:19], v[176:179], v[200:203], v[16:19]
	v_mfma_f32_16x16x32_bf16 v[4:7], v[168:171], v[208:211], v[4:7]
	v_mfma_f32_16x16x32_bf16 v[0:3], v[176:179], v[208:211], v[0:3]
	s_barrier
	ds_read_b128 v[148:151], v145
	ds_read_b128 v[152:155], v145 offset:1024
	ds_read_b128 v[156:159], v145 offset:2048
	ds_read_b128 v[160:163], v145 offset:3072
	ds_read_b128 v[164:167], v146
	ds_read_b128 v[168:171], v146 offset:1024
	ds_read_b128 v[172:175], v146 offset:2048
	ds_read_b128 v[176:179], v146 offset:3072
	s_add_u32 s16, s16, 0x80000
	s_addc_u32 s17, s17, 0
	s_mov_b32 m0, s28
	v_lshl_add_u64 v[220:221], s[16:17], 0, v[128:129]
	ds_read_b128 v[180:183], v143 offset:32768
	ds_read_b128 v[184:187], v143 offset:33792
	ds_read_b128 v[188:191], v143 offset:34816
	ds_read_b128 v[192:195], v143 offset:35840
	ds_read_b128 v[196:199], v143 offset:36864
	ds_read_b128 v[200:203], v143 offset:37888
	ds_read_b128 v[204:207], v143 offset:38912
	ds_read_b128 v[208:211], v143 offset:39936
	global_load_lds_dwordx4 v[220:221], off
	v_lshl_add_u64 v[220:221], s[16:17], 0, v[132:133]
	s_mov_b32 m0, s29
	s_nop 0
	global_load_lds_dwordx4 v[220:221], off
	s_waitcnt vmcnt(8)
	s_waitcnt lgkmcnt(0)
	s_barrier
	s_waitcnt lgkmcnt(0)
	v_mfma_f32_16x16x32_bf16 v[124:127], v[148:151], v[180:183], v[124:127]
	v_mfma_f32_16x16x32_bf16 v[120:123], v[156:159], v[180:183], v[120:123]
	v_mfma_f32_16x16x32_bf16 v[108:111], v[148:151], v[188:191], v[108:111]
	v_mfma_f32_16x16x32_bf16 v[104:107], v[156:159], v[188:191], v[104:107]
	v_mfma_f32_16x16x32_bf16 v[92:95], v[148:151], v[196:199], v[92:95]
	v_mfma_f32_16x16x32_bf16 v[88:91], v[156:159], v[196:199], v[88:91]
	v_mfma_f32_16x16x32_bf16 v[76:79], v[148:151], v[204:207], v[76:79]
	v_mfma_f32_16x16x32_bf16 v[72:75], v[156:159], v[204:207], v[72:75]
	v_mfma_f32_16x16x32_bf16 v[124:127], v[152:155], v[184:187], v[124:127]
	v_mfma_f32_16x16x32_bf16 v[120:123], v[160:163], v[184:187], v[120:123]
	v_mfma_f32_16x16x32_bf16 v[108:111], v[152:155], v[192:195], v[108:111]
	v_mfma_f32_16x16x32_bf16 v[104:107], v[160:163], v[192:195], v[104:107]
	v_mfma_f32_16x16x32_bf16 v[92:95], v[152:155], v[200:203], v[92:95]
	v_mfma_f32_16x16x32_bf16 v[88:91], v[160:163], v[200:203], v[88:91]
	v_mfma_f32_16x16x32_bf16 v[76:79], v[152:155], v[208:211], v[76:79]
	v_mfma_f32_16x16x32_bf16 v[72:75], v[160:163], v[208:211], v[72:75]
	v_mfma_f32_16x16x32_bf16 v[116:119], v[164:167], v[180:183], v[116:119]
	v_mfma_f32_16x16x32_bf16 v[112:115], v[172:175], v[180:183], v[112:115]
	v_mfma_f32_16x16x32_bf16 v[100:103], v[164:167], v[188:191], v[100:103]
	v_mfma_f32_16x16x32_bf16 v[96:99], v[172:175], v[188:191], v[96:99]
	v_mfma_f32_16x16x32_bf16 v[84:87], v[164:167], v[196:199], v[84:87]
	v_mfma_f32_16x16x32_bf16 v[80:83], v[172:175], v[196:199], v[80:83]
	v_mfma_f32_16x16x32_bf16 v[68:71], v[164:167], v[204:207], v[68:71]
	v_mfma_f32_16x16x32_bf16 v[64:67], v[172:175], v[204:207], v[64:67]
	v_mfma_f32_16x16x32_bf16 v[116:119], v[168:171], v[184:187], v[116:119]
	v_mfma_f32_16x16x32_bf16 v[112:115], v[176:179], v[184:187], v[112:115]
	v_mfma_f32_16x16x32_bf16 v[100:103], v[168:171], v[192:195], v[100:103]
	v_mfma_f32_16x16x32_bf16 v[96:99], v[176:179], v[192:195], v[96:99]
	v_mfma_f32_16x16x32_bf16 v[84:87], v[168:171], v[200:203], v[84:87]
	v_mfma_f32_16x16x32_bf16 v[80:83], v[176:179], v[200:203], v[80:83]
	v_mfma_f32_16x16x32_bf16 v[68:71], v[168:171], v[208:211], v[68:71]
	v_mfma_f32_16x16x32_bf16 v[64:67], v[176:179], v[208:211], v[64:67]
	s_barrier
	s_mov_b32 m0, s43
	v_lshl_add_u64 v[212:213], v[212:213], 0, s[8:9]
	s_add_u32 s14, s14, 0x80080
	ds_read_b128 v[180:183], v143 offset:49152
	ds_read_b128 v[184:187], v143 offset:50176
	ds_read_b128 v[188:191], v143 offset:51200
	ds_read_b128 v[192:195], v143 offset:52224
	ds_read_b128 v[196:199], v143 offset:53248
	ds_read_b128 v[200:203], v143 offset:54272
	ds_read_b128 v[204:207], v143 offset:55296
	ds_read_b128 v[208:211], v143 offset:56320
	global_load_lds_dwordx4 v[212:213], off
	v_lshl_add_u64 v[212:213], v[214:215], 0, s[8:9]
	s_mov_b32 m0, s44
	s_addc_u32 s15, s15, 0
	global_load_lds_dwordx4 v[212:213], off
	v_lshl_add_u64 v[212:213], s[14:15], 0, v[130:131]
	s_mov_b32 m0, s45
	s_nop 0
	global_load_lds_dwordx4 v[212:213], off
	v_lshl_add_u64 v[212:213], s[14:15], 0, v[134:135]
	s_mov_b32 m0, s46
	s_nop 0
	global_load_lds_dwordx4 v[212:213], off
	v_lshl_add_u64 v[212:213], v[216:217], 0, s[8:9]
	s_mov_b32 m0, s30
	s_nop 0
	global_load_lds_dwordx4 v[212:213], off
	v_lshl_add_u64 v[212:213], v[218:219], 0, s[8:9]
	s_mov_b32 m0, s31
	s_nop 0
	global_load_lds_dwordx4 v[212:213], off
	s_waitcnt vmcnt(8)
	s_waitcnt lgkmcnt(0)
	s_barrier
	s_waitcnt lgkmcnt(0)
	v_mfma_f32_16x16x32_bf16 v[60:63], v[148:151], v[180:183], v[60:63]
	v_mfma_f32_16x16x32_bf16 v[56:59], v[156:159], v[180:183], v[56:59]
	v_mfma_f32_16x16x32_bf16 v[44:47], v[148:151], v[188:191], v[44:47]
	v_mfma_f32_16x16x32_bf16 v[40:43], v[156:159], v[188:191], v[40:43]
	v_mfma_f32_16x16x32_bf16 v[28:31], v[148:151], v[196:199], v[28:31]
	v_mfma_f32_16x16x32_bf16 v[24:27], v[156:159], v[196:199], v[24:27]
	v_mfma_f32_16x16x32_bf16 v[12:15], v[148:151], v[204:207], v[12:15]
	v_mfma_f32_16x16x32_bf16 v[8:11], v[156:159], v[204:207], v[8:11]
	v_mfma_f32_16x16x32_bf16 v[60:63], v[152:155], v[184:187], v[60:63]
	v_mfma_f32_16x16x32_bf16 v[56:59], v[160:163], v[184:187], v[56:59]
	v_mfma_f32_16x16x32_bf16 v[44:47], v[152:155], v[192:195], v[44:47]
	v_mfma_f32_16x16x32_bf16 v[40:43], v[160:163], v[192:195], v[40:43]
	v_mfma_f32_16x16x32_bf16 v[28:31], v[152:155], v[200:203], v[28:31]
	v_mfma_f32_16x16x32_bf16 v[24:27], v[160:163], v[200:203], v[24:27]
	v_mfma_f32_16x16x32_bf16 v[12:15], v[152:155], v[208:211], v[12:15]
	v_mfma_f32_16x16x32_bf16 v[8:11], v[160:163], v[208:211], v[8:11]
	v_mfma_f32_16x16x32_bf16 v[52:55], v[164:167], v[180:183], v[52:55]
	v_mfma_f32_16x16x32_bf16 v[48:51], v[172:175], v[180:183], v[48:51]
	v_mfma_f32_16x16x32_bf16 v[36:39], v[164:167], v[188:191], v[36:39]
	v_mfma_f32_16x16x32_bf16 v[32:35], v[172:175], v[188:191], v[32:35]
	v_mfma_f32_16x16x32_bf16 v[20:23], v[164:167], v[196:199], v[20:23]
	v_mfma_f32_16x16x32_bf16 v[16:19], v[172:175], v[196:199], v[16:19]
	v_mfma_f32_16x16x32_bf16 v[4:7], v[164:167], v[204:207], v[4:7]
	v_mfma_f32_16x16x32_bf16 v[0:3], v[172:175], v[204:207], v[0:3]
	v_mfma_f32_16x16x32_bf16 v[52:55], v[168:171], v[184:187], v[52:55]
	v_mfma_f32_16x16x32_bf16 v[48:51], v[176:179], v[184:187], v[48:51]
	v_mfma_f32_16x16x32_bf16 v[36:39], v[168:171], v[192:195], v[36:39]
	v_mfma_f32_16x16x32_bf16 v[32:35], v[176:179], v[192:195], v[32:35]
	v_mfma_f32_16x16x32_bf16 v[20:23], v[168:171], v[200:203], v[20:23]
	v_mfma_f32_16x16x32_bf16 v[16:19], v[176:179], v[200:203], v[16:19]
	v_mfma_f32_16x16x32_bf16 v[4:7], v[168:171], v[208:211], v[4:7]
	v_mfma_f32_16x16x32_bf16 v[0:3], v[176:179], v[208:211], v[0:3]
	s_barrier
	s_add_i32 s36, s36, 2
	s_add_u32 s12, s12, 0x100
	s_addc_u32 s13, s13, 0
	s_cmp_gt_u32 s36, 29
	s_cbranch_scc0 .LBB0_165
	s_setprio 0
	s_cmpk_lt_u32 s33, 0x100
	s_cbranch_scc0 .LBB0_168
	s_barrier

.LBB0_253:
	s_add_i32 s54, s54, 1
	s_mov_b64 s[2:3], s[10:11]
	s_mov_b32 s60, s6
	s_mov_b32 s10, s6
	s_lshl_b32 s6, s54, 5
	s_add_i32 s6, s6, s63
	s_cmp_lt_i32 s6, 64
	s_cselect_b64 s[44:45], -1, 0
	s_ashr_i32 s6, s6, 2
	s_mov_b64 s[0:1], s[8:9]
	s_and_b64 s[8:9], s[44:45], exec
	s_cselect_b32 s8, s35, s35
	s_cselect_b32 s10, s6, s10
	s_ashr_i32 s9, s8, 31
	s_lshl_b64 s[8:9], s[8:9], 20
	s_add_u32 s8, s21, s8
	s_addc_u32 s9, s23, s9
	s_and_b64 s[46:47], s[44:45], exec
	s_cselect_b32 s61, s9, s1
	s_cselect_b32 s72, s8, s0
	s_ashr_i32 s11, s10, 31
	s_lshl_b64 s[10:11], s[10:11], 20
	s_add_u32 s10, s70, s10
	s_addc_u32 s11, s71, s11
	s_and_b64 s[46:47], s[44:45], exec
	s_cselect_b32 s73, s11, s3
	s_cselect_b32 s74, s10, s2
	s_add_u32 s0, s0, 0x80080
	s_addc_u32 s1, s1, 0
	s_add_u32 s75, s2, 0x100
	s_addc_u32 s76, s3, 0
	s_mov_b32 s77, -2
	v_mov_b32_e32 v0, 0
	v_mov_b32_e32 v1, v158
	s_waitcnt lgkmcnt(0)
	v_mov_b32_e32 v2, v158
	v_mov_b32_e32 v3, v158
	v_mov_b32_e32 v4, 0
	v_mov_b32_e32 v5, v158
	v_mov_b32_e32 v6, v158
	v_mov_b32_e32 v7, v158
	v_mov_b32_e32 v16, 0
	v_mov_b32_e32 v17, v158
	v_mov_b32_e32 v18, v158
	v_mov_b32_e32 v19, v158
	v_mov_b32_e32 v20, 0
	v_mov_b32_e32 v21, v158
	v_mov_b32_e32 v22, v158
	v_mov_b32_e32 v23, v158
	v_mov_b32_e32 v32, 0
	v_mov_b32_e32 v33, v158
	v_mov_b32_e32 v34, v158
	v_mov_b32_e32 v35, v158
	v_mov_b32_e32 v36, 0
	v_mov_b32_e32 v37, v158
	v_mov_b32_e32 v38, v158
	v_mov_b32_e32 v39, v158
	v_mov_b32_e32 v64, 0
	v_mov_b32_e32 v65, v158
	v_mov_b32_e32 v66, v158
	v_mov_b32_e32 v67, v158
	v_mov_b32_e32 v68, 0
	v_mov_b32_e32 v69, v158
	v_mov_b32_e32 v70, v158
	v_mov_b32_e32 v71, v158
	v_mov_b32_e32 v8, 0
	v_mov_b32_e32 v9, v158
	v_mov_b32_e32 v10, v158
	v_mov_b32_e32 v11, v158
	v_mov_b32_e32 v12, 0
	v_mov_b32_e32 v13, v158
	v_mov_b32_e32 v14, v158
	v_mov_b32_e32 v15, v158
	v_mov_b32_e32 v24, 0
	v_mov_b32_e32 v25, v158
	v_mov_b32_e32 v26, v158
	v_mov_b32_e32 v27, v158
	v_mov_b32_e32 v28, 0
	v_mov_b32_e32 v29, v158
	v_mov_b32_e32 v30, v158
	v_mov_b32_e32 v31, v158
	v_mov_b32_e32 v56, 0
	v_mov_b32_e32 v57, v158
	v_mov_b32_e32 v58, v158
	v_mov_b32_e32 v59, v158
	v_mov_b32_e32 v60, 0
	v_mov_b32_e32 v61, v158
	v_mov_b32_e32 v62, v158
	v_mov_b32_e32 v63, v158
	v_mov_b32_e32 v72, 0
	v_mov_b32_e32 v73, v158
	v_mov_b32_e32 v74, v158
	v_mov_b32_e32 v75, v158
	v_mov_b32_e32 v76, 0
	v_mov_b32_e32 v77, v158
	v_mov_b32_e32 v78, v158
	v_mov_b32_e32 v79, v158
	v_mov_b32_e32 v80, 0
	v_mov_b32_e32 v81, v158
	v_mov_b32_e32 v82, v158
	v_mov_b32_e32 v83, v158
	v_mov_b32_e32 v84, 0
	v_mov_b32_e32 v85, v158
	v_mov_b32_e32 v86, v158
	v_mov_b32_e32 v87, v158
	v_mov_b32_e32 v96, 0
	v_mov_b32_e32 v97, v158
	v_mov_b32_e32 v98, v158
	v_mov_b32_e32 v99, v158
	v_mov_b32_e32 v100, 0
	v_mov_b32_e32 v101, v158
	v_mov_b32_e32 v102, v158
	v_mov_b32_e32 v103, v158
	v_mov_b32_e32 v112, 0
	v_mov_b32_e32 v113, v158
	v_mov_b32_e32 v114, v158
	v_mov_b32_e32 v115, v158
	v_mov_b32_e32 v116, 0
	v_mov_b32_e32 v117, v158
	v_mov_b32_e32 v118, v158
	v_mov_b32_e32 v119, v158
	v_mov_b32_e32 v128, 0
	v_mov_b32_e32 v129, v158
	v_mov_b32_e32 v130, v158
	v_mov_b32_e32 v131, v158
	v_mov_b32_e32 v132, 0
	v_mov_b32_e32 v133, v158
	v_mov_b32_e32 v134, v158
	v_mov_b32_e32 v135, v158
	v_mov_b32_e32 v88, 0
	v_mov_b32_e32 v89, v158
	v_mov_b32_e32 v90, v158
	v_mov_b32_e32 v91, v158
	v_mov_b32_e32 v92, 0
	v_mov_b32_e32 v93, v158
	v_mov_b32_e32 v94, v158
	v_mov_b32_e32 v95, v158
	v_mov_b32_e32 v104, 0
	v_mov_b32_e32 v105, v158
	v_mov_b32_e32 v106, v158
	v_mov_b32_e32 v107, v158
	v_mov_b32_e32 v108, 0
	v_mov_b32_e32 v109, v158
	v_mov_b32_e32 v110, v158
	v_mov_b32_e32 v111, v158
	v_mov_b32_e32 v120, 0
	v_mov_b32_e32 v121, v158
	v_mov_b32_e32 v122, v158
	v_mov_b32_e32 v123, v158
	v_mov_b32_e32 v124, 0
	v_mov_b32_e32 v125, v158
	v_mov_b32_e32 v126, v158
	v_mov_b32_e32 v127, v158
	v_mov_b32_e32 v136, 0
	v_mov_b32_e32 v137, v158
	v_mov_b32_e32 v138, v158
	v_mov_b32_e32 v139, v158
	v_mov_b32_e32 v140, 0
	v_mov_b32_e32 v141, v158
	v_mov_b32_e32 v142, v158
	v_mov_b32_e32 v143, v158
	s_lshr_b32 s101, s88, 2
	s_cmp_lg_u32 s101, 1
	s_cbranch_scc1 .Lprio_skip1
	s_setprio 1
.Lprio_skip1:
.LBB0_254:
	ds_read_b128 v[40:43], v176
	ds_read_b128 v[44:47], v176 offset:1024
	ds_read_b128 v[48:51], v176 offset:2048
	ds_read_b128 v[52:55], v176 offset:3072
	ds_read_b128 v[162:165], v177
	ds_read_b128 v[166:169], v177 offset:1024
	ds_read_b128 v[170:173], v177 offset:2048
	ds_read_b128 v[194:197], v177 offset:3072
	s_add_u32 s2, s0, 0xfff80080
	s_addc_u32 s3, s1, -1
	s_cmp_eq_u32 s77, 28
	s_cselect_b32 s47, s61, s3
	s_cselect_b32 s46, s72, s2
	s_cselect_b32 s3, s73, s76
	s_cselect_b32 s2, s74, s75
	v_lshl_add_u64 v[174:175], s[0:1], 0, v[156:157]
	s_add_i32 m0, s7, 0xc000
	ds_read_b128 v[198:201], v178
	ds_read_b128 v[202:205], v178 offset:1024
	ds_read_b128 v[206:209], v178 offset:2048
	ds_read_b128 v[210:213], v178 offset:3072
	ds_read_b128 v[214:217], v178 offset:4096
	ds_read_b128 v[218:221], v178 offset:5120
	ds_read_b128 v[222:225], v178 offset:6144
	ds_read_b128 v[226:229], v178 offset:7168
	global_load_lds_dwordx4 v[174:175], off
	v_lshl_add_u64 v[174:175], s[0:1], 0, v[160:161]
	s_add_i32 m0, s7, 0xe000
	s_nop 0
	global_load_lds_dwordx4 v[174:175], off
	s_waitcnt vmcnt(8)
	s_waitcnt lgkmcnt(0)
	s_barrier
	s_waitcnt lgkmcnt(0)
	v_mfma_f32_16x16x32_bf16 v[140:143], v[40:43], v[198:201], v[140:143]
	v_mfma_f32_16x16x32_bf16 v[136:139], v[48:51], v[198:201], v[136:139]
	v_mfma_f32_16x16x32_bf16 v[124:127], v[40:43], v[206:209], v[124:127]
	v_mfma_f32_16x16x32_bf16 v[120:123], v[48:51], v[206:209], v[120:123]
	v_mfma_f32_16x16x32_bf16 v[108:111], v[40:43], v[214:217], v[108:111]
	v_mfma_f32_16x16x32_bf16 v[104:107], v[48:51], v[214:217], v[104:107]
	v_mfma_f32_16x16x32_bf16 v[92:95], v[40:43], v[222:225], v[92:95]
	v_mfma_f32_16x16x32_bf16 v[88:91], v[48:51], v[222:225], v[88:91]
	v_mfma_f32_16x16x32_bf16 v[140:143], v[44:47], v[202:205], v[140:143]
	v_mfma_f32_16x16x32_bf16 v[136:139], v[52:55], v[202:205], v[136:139]
	v_mfma_f32_16x16x32_bf16 v[124:127], v[44:47], v[210:213], v[124:127]
	v_mfma_f32_16x16x32_bf16 v[120:123], v[52:55], v[210:213], v[120:123]
	v_mfma_f32_16x16x32_bf16 v[108:111], v[44:47], v[218:221], v[108:111]
	v_mfma_f32_16x16x32_bf16 v[104:107], v[52:55], v[218:221], v[104:107]
	v_mfma_f32_16x16x32_bf16 v[92:95], v[44:47], v[226:229], v[92:95]
	v_mfma_f32_16x16x32_bf16 v[88:91], v[52:55], v[226:229], v[88:91]
	v_mfma_f32_16x16x32_bf16 v[132:135], v[162:165], v[198:201], v[132:135]
	v_mfma_f32_16x16x32_bf16 v[128:131], v[170:173], v[198:201], v[128:131]
	v_mfma_f32_16x16x32_bf16 v[116:119], v[162:165], v[206:209], v[116:119]
	v_mfma_f32_16x16x32_bf16 v[112:115], v[170:173], v[206:209], v[112:115]
	v_mfma_f32_16x16x32_bf16 v[100:103], v[162:165], v[214:217], v[100:103]
	v_mfma_f32_16x16x32_bf16 v[96:99], v[170:173], v[214:217], v[96:99]
	v_mfma_f32_16x16x32_bf16 v[84:87], v[162:165], v[222:225], v[84:87]
	v_mfma_f32_16x16x32_bf16 v[80:83], v[170:173], v[222:225], v[80:83]
	v_mfma_f32_16x16x32_bf16 v[132:135], v[166:169], v[202:205], v[132:135]
	v_mfma_f32_16x16x32_bf16 v[128:131], v[194:197], v[202:205], v[128:131]
	v_mfma_f32_16x16x32_bf16 v[116:119], v[166:169], v[210:213], v[116:119]
	v_mfma_f32_16x16x32_bf16 v[112:115], v[194:197], v[210:213], v[112:115]
	v_mfma_f32_16x16x32_bf16 v[100:103], v[166:169], v[218:221], v[100:103]
	v_mfma_f32_16x16x32_bf16 v[96:99], v[194:197], v[218:221], v[96:99]
	v_mfma_f32_16x16x32_bf16 v[84:87], v[166:169], v[226:229], v[84:87]
	v_mfma_f32_16x16x32_bf16 v[80:83], v[194:197], v[226:229], v[80:83]
	s_barrier
	s_add_i32 s78, s56, s66
	v_lshl_add_u64 v[174:175], s[2:3], 0, v[150:151]
	s_mov_b32 m0, s78
	ds_read_b128 v[198:201], v178 offset:16384
	ds_read_b128 v[202:205], v178 offset:17408
	ds_read_b128 v[206:209], v178 offset:18432
	ds_read_b128 v[210:213], v178 offset:19456
	ds_read_b128 v[214:217], v178 offset:20480
	ds_read_b128 v[218:221], v178 offset:21504
	ds_read_b128 v[222:225], v178 offset:22528
	ds_read_b128 v[226:229], v178 offset:23552
	global_load_lds_dwordx4 v[174:175], off
	s_add_i32 m0, s78, 0x2000
	s_add_u32 s78, s2, 0x80000
	v_lshl_add_u64 v[182:183], s[2:3], 0, v[154:155]
	s_addc_u32 s79, s3, 0
	s_add_i32 s80, s57, s66
	global_load_lds_dwordx4 v[182:183], off
	v_lshl_add_u64 v[230:231], s[78:79], 0, v[150:151]
	s_mov_b32 m0, s80
	v_lshl_add_u64 v[232:233], s[46:47], 0, v[152:153]
	global_load_lds_dwordx4 v[230:231], off
	v_lshl_add_u64 v[230:231], s[78:79], 0, v[154:155]
	s_add_i32 m0, s80, 0x2000
	s_nop 0
	global_load_lds_dwordx4 v[230:231], off
	v_lshl_add_u64 v[230:231], s[46:47], 0, v[148:149]
	s_mov_b32 m0, s7
	s_nop 0
	global_load_lds_dwordx4 v[230:231], off
	s_mov_b32 m0, s39
	s_nop 0
	global_load_lds_dwordx4 v[232:233], off
	s_waitcnt vmcnt(8)
	s_waitcnt lgkmcnt(0)
	s_barrier
	s_waitcnt lgkmcnt(0)
	v_mfma_f32_16x16x32_bf16 v[76:79], v[40:43], v[198:201], v[76:79]
	v_mfma_f32_16x16x32_bf16 v[72:75], v[48:51], v[198:201], v[72:75]
	v_mfma_f32_16x16x32_bf16 v[60:63], v[40:43], v[206:209], v[60:63]
	v_mfma_f32_16x16x32_bf16 v[56:59], v[48:51], v[206:209], v[56:59]
	v_mfma_f32_16x16x32_bf16 v[28:31], v[40:43], v[214:217], v[28:31]
	v_mfma_f32_16x16x32_bf16 v[24:27], v[48:51], v[214:217], v[24:27]
	v_mfma_f32_16x16x32_bf16 v[12:15], v[40:43], v[222:225], v[12:15]
	v_mfma_f32_16x16x32_bf16 v[8:11], v[48:51], v[222:225], v[8:11]
	v_mfma_f32_16x16x32_bf16 v[76:79], v[44:47], v[202:205], v[76:79]
	v_mfma_f32_16x16x32_bf16 v[72:75], v[52:55], v[202:205], v[72:75]
	v_mfma_f32_16x16x32_bf16 v[60:63], v[44:47], v[210:213], v[60:63]
	v_mfma_f32_16x16x32_bf16 v[56:59], v[52:55], v[210:213], v[56:59]
	v_mfma_f32_16x16x32_bf16 v[28:31], v[44:47], v[218:221], v[28:31]
	v_mfma_f32_16x16x32_bf16 v[24:27], v[52:55], v[218:221], v[24:27]
	v_mfma_f32_16x16x32_bf16 v[12:15], v[44:47], v[226:229], v[12:15]
	v_mfma_f32_16x16x32_bf16 v[8:11], v[52:55], v[226:229], v[8:11]
	v_mfma_f32_16x16x32_bf16 v[36:39], v[162:165], v[206:209], v[36:39]
	v_mfma_f32_16x16x32_bf16 v[32:35], v[170:173], v[206:209], v[32:35]
	v_mfma_f32_16x16x32_bf16 v[20:23], v[162:165], v[214:217], v[20:23]
	v_mfma_f32_16x16x32_bf16 v[16:19], v[170:173], v[214:217], v[16:19]
	v_mfma_f32_16x16x32_bf16 v[4:7], v[162:165], v[222:225], v[4:7]
	v_mfma_f32_16x16x32_bf16 v[0:3], v[170:173], v[222:225], v[0:3]
	v_mfma_f32_16x16x32_bf16 v[40:43], v[162:165], v[198:201], v[68:71]
	v_mfma_f32_16x16x32_bf16 v[44:47], v[170:173], v[198:201], v[64:67]
	v_mfma_f32_16x16x32_bf16 v[36:39], v[166:169], v[210:213], v[36:39]
	v_mfma_f32_16x16x32_bf16 v[32:35], v[194:197], v[210:213], v[32:35]
	v_mfma_f32_16x16x32_bf16 v[20:23], v[166:169], v[218:221], v[20:23]
	v_mfma_f32_16x16x32_bf16 v[16:19], v[194:197], v[218:221], v[16:19]
	v_mfma_f32_16x16x32_bf16 v[4:7], v[166:169], v[226:229], v[4:7]
	v_mfma_f32_16x16x32_bf16 v[0:3], v[194:197], v[226:229], v[0:3]
	v_mfma_f32_16x16x32_bf16 v[40:43], v[166:169], v[202:205], v[40:43]
	v_mfma_f32_16x16x32_bf16 v[44:47], v[194:197], v[202:205], v[44:47]
	s_barrier
	ds_read_b128 v[48:51], v179
	ds_read_b128 v[52:55], v179 offset:1024
	ds_read_b128 v[64:67], v179 offset:2048
	ds_read_b128 v[68:71], v179 offset:3072
	ds_read_b128 v[162:165], v180
	ds_read_b128 v[166:169], v180 offset:1024
	ds_read_b128 v[170:173], v180 offset:2048
	ds_read_b128 v[194:197], v180 offset:3072
	s_add_u32 s46, s46, 0x80000
	s_addc_u32 s47, s47, 0
	s_mov_b32 m0, s41
	v_lshl_add_u64 v[234:235], s[46:47], 0, v[148:149]
	ds_read_b128 v[198:201], v178 offset:32768
	ds_read_b128 v[202:205], v178 offset:33792
	ds_read_b128 v[206:209], v178 offset:34816
	ds_read_b128 v[210:213], v178 offset:35840
	ds_read_b128 v[214:217], v178 offset:36864
	ds_read_b128 v[218:221], v178 offset:37888
	ds_read_b128 v[222:225], v178 offset:38912
	ds_read_b128 v[226:229], v178 offset:39936
	global_load_lds_dwordx4 v[234:235], off
	v_lshl_add_u64 v[234:235], s[46:47], 0, v[152:153]
	s_mov_b32 m0, s50
	s_nop 0
	global_load_lds_dwordx4 v[234:235], off
	s_waitcnt vmcnt(8)
	s_waitcnt lgkmcnt(0)
	s_barrier
	s_waitcnt lgkmcnt(0)
	v_mfma_f32_16x16x32_bf16 v[140:143], v[48:51], v[198:201], v[140:143]
	v_mfma_f32_16x16x32_bf16 v[136:139], v[64:67], v[198:201], v[136:139]
	v_mfma_f32_16x16x32_bf16 v[124:127], v[48:51], v[206:209], v[124:127]
	v_mfma_f32_16x16x32_bf16 v[120:123], v[64:67], v[206:209], v[120:123]
	v_mfma_f32_16x16x32_bf16 v[108:111], v[48:51], v[214:217], v[108:111]
	v_mfma_f32_16x16x32_bf16 v[104:107], v[64:67], v[214:217], v[104:107]
	v_mfma_f32_16x16x32_bf16 v[92:95], v[48:51], v[222:225], v[92:95]
	v_mfma_f32_16x16x32_bf16 v[88:91], v[64:67], v[222:225], v[88:91]
	v_mfma_f32_16x16x32_bf16 v[140:143], v[52:55], v[202:205], v[140:143]
	v_mfma_f32_16x16x32_bf16 v[136:139], v[68:71], v[202:205], v[136:139]
	v_mfma_f32_16x16x32_bf16 v[124:127], v[52:55], v[210:213], v[124:127]
	v_mfma_f32_16x16x32_bf16 v[120:123], v[68:71], v[210:213], v[120:123]
	v_mfma_f32_16x16x32_bf16 v[108:111], v[52:55], v[218:221], v[108:111]
	v_mfma_f32_16x16x32_bf16 v[104:107], v[68:71], v[218:221], v[104:107]
	v_mfma_f32_16x16x32_bf16 v[92:95], v[52:55], v[226:229], v[92:95]
	v_mfma_f32_16x16x32_bf16 v[88:91], v[68:71], v[226:229], v[88:91]
	v_mfma_f32_16x16x32_bf16 v[132:135], v[162:165], v[198:201], v[132:135]
	v_mfma_f32_16x16x32_bf16 v[128:131], v[170:173], v[198:201], v[128:131]
	v_mfma_f32_16x16x32_bf16 v[116:119], v[162:165], v[206:209], v[116:119]
	v_mfma_f32_16x16x32_bf16 v[112:115], v[170:173], v[206:209], v[112:115]
	v_mfma_f32_16x16x32_bf16 v[100:103], v[162:165], v[214:217], v[100:103]
	v_mfma_f32_16x16x32_bf16 v[96:99], v[170:173], v[214:217], v[96:99]
	v_mfma_f32_16x16x32_bf16 v[84:87], v[162:165], v[222:225], v[84:87]
	v_mfma_f32_16x16x32_bf16 v[80:83], v[170:173], v[222:225], v[80:83]
	v_mfma_f32_16x16x32_bf16 v[132:135], v[166:169], v[202:205], v[132:135]
	v_mfma_f32_16x16x32_bf16 v[128:131], v[194:197], v[202:205], v[128:131]
	v_mfma_f32_16x16x32_bf16 v[116:119], v[166:169], v[210:213], v[116:119]
	v_mfma_f32_16x16x32_bf16 v[112:115], v[194:197], v[210:213], v[112:115]
	v_mfma_f32_16x16x32_bf16 v[100:103], v[166:169], v[218:221], v[100:103]
	v_mfma_f32_16x16x32_bf16 v[96:99], v[194:197], v[218:221], v[96:99]
	v_mfma_f32_16x16x32_bf16 v[84:87], v[166:169], v[226:229], v[84:87]
	v_mfma_f32_16x16x32_bf16 v[80:83], v[194:197], v[226:229], v[80:83]
	s_barrier
	s_add_i32 s46, s58, s66
	v_lshl_add_u64 v[174:175], v[174:175], 0, s[14:15]
	s_mov_b32 m0, s46
	ds_read_b128 v[198:201], v178 offset:49152
	ds_read_b128 v[202:205], v178 offset:50176
	ds_read_b128 v[206:209], v178 offset:51200
	ds_read_b128 v[210:213], v178 offset:52224
	ds_read_b128 v[214:217], v178 offset:53248
	ds_read_b128 v[218:221], v178 offset:54272
	ds_read_b128 v[222:225], v178 offset:55296
	ds_read_b128 v[226:229], v178 offset:56320
	global_load_lds_dwordx4 v[174:175], off
	s_add_i32 m0, s46, 0x2000
	s_add_u32 s2, s2, 0x80080
	v_lshl_add_u64 v[174:175], v[182:183], 0, s[14:15]
	s_addc_u32 s3, s3, 0
	s_add_i32 s46, s59, s66
	global_load_lds_dwordx4 v[174:175], off
	v_lshl_add_u64 v[174:175], s[2:3], 0, v[150:151]
	s_mov_b32 m0, s46
	s_nop 0
	global_load_lds_dwordx4 v[174:175], off
	v_lshl_add_u64 v[174:175], s[2:3], 0, v[154:155]
	s_add_i32 m0, s46, 0x2000
	s_nop 0
	global_load_lds_dwordx4 v[174:175], off
	v_lshl_add_u64 v[174:175], v[230:231], 0, s[14:15]
	s_mov_b32 m0, s51
	s_nop 0
	global_load_lds_dwordx4 v[174:175], off
	v_lshl_add_u64 v[174:175], v[232:233], 0, s[14:15]
	s_mov_b32 m0, s52
	s_nop 0
	global_load_lds_dwordx4 v[174:175], off
	s_waitcnt vmcnt(8)
	s_waitcnt lgkmcnt(0)
	s_barrier
	s_waitcnt lgkmcnt(0)
	v_mfma_f32_16x16x32_bf16 v[76:79], v[48:51], v[198:201], v[76:79]
	v_mfma_f32_16x16x32_bf16 v[72:75], v[64:67], v[198:201], v[72:75]
	v_mfma_f32_16x16x32_bf16 v[60:63], v[48:51], v[206:209], v[60:63]
	v_mfma_f32_16x16x32_bf16 v[56:59], v[64:67], v[206:209], v[56:59]
	v_mfma_f32_16x16x32_bf16 v[28:31], v[48:51], v[214:217], v[28:31]
	v_mfma_f32_16x16x32_bf16 v[24:27], v[64:67], v[214:217], v[24:27]
	v_mfma_f32_16x16x32_bf16 v[12:15], v[48:51], v[222:225], v[12:15]
	v_mfma_f32_16x16x32_bf16 v[8:11], v[64:67], v[222:225], v[8:11]
	v_mfma_f32_16x16x32_bf16 v[76:79], v[52:55], v[202:205], v[76:79]
	v_mfma_f32_16x16x32_bf16 v[72:75], v[68:71], v[202:205], v[72:75]
	v_mfma_f32_16x16x32_bf16 v[60:63], v[52:55], v[210:213], v[60:63]
	v_mfma_f32_16x16x32_bf16 v[56:59], v[68:71], v[210:213], v[56:59]
	v_mfma_f32_16x16x32_bf16 v[28:31], v[52:55], v[218:221], v[28:31]
	v_mfma_f32_16x16x32_bf16 v[24:27], v[68:71], v[218:221], v[24:27]
	v_mfma_f32_16x16x32_bf16 v[12:15], v[52:55], v[226:229], v[12:15]
	v_mfma_f32_16x16x32_bf16 v[8:11], v[68:71], v[226:229], v[8:11]
	v_mfma_f32_16x16x32_bf16 v[40:43], v[162:165], v[198:201], v[40:43]
	v_mfma_f32_16x16x32_bf16 v[68:71], v[166:169], v[202:205], v[40:43]
	v_mfma_f32_16x16x32_bf16 v[40:43], v[170:173], v[198:201], v[44:47]
	v_mfma_f32_16x16x32_bf16 v[36:39], v[162:165], v[206:209], v[36:39]
	v_mfma_f32_16x16x32_bf16 v[32:35], v[170:173], v[206:209], v[32:35]
	v_mfma_f32_16x16x32_bf16 v[20:23], v[162:165], v[214:217], v[20:23]
	v_mfma_f32_16x16x32_bf16 v[16:19], v[170:173], v[214:217], v[16:19]
	v_mfma_f32_16x16x32_bf16 v[4:7], v[162:165], v[222:225], v[4:7]
	v_mfma_f32_16x16x32_bf16 v[0:3], v[170:173], v[222:225], v[0:3]
	v_mfma_f32_16x16x32_bf16 v[64:67], v[194:197], v[202:205], v[40:43]
	v_mfma_f32_16x16x32_bf16 v[36:39], v[166:169], v[210:213], v[36:39]
	v_mfma_f32_16x16x32_bf16 v[32:35], v[194:197], v[210:213], v[32:35]
	v_mfma_f32_16x16x32_bf16 v[20:23], v[166:169], v[218:221], v[20:23]
	v_mfma_f32_16x16x32_bf16 v[16:19], v[194:197], v[218:221], v[16:19]
	v_mfma_f32_16x16x32_bf16 v[4:7], v[166:169], v[226:229], v[4:7]
	v_mfma_f32_16x16x32_bf16 v[0:3], v[194:197], v[226:229], v[0:3]
	s_barrier
	s_add_i32 s77, s77, 2
	s_add_u32 s0, s0, 0x100
	s_addc_u32 s1, s1, 0
	s_add_u32 s75, s75, 0x100
	s_addc_u32 s76, s76, 0
	s_cmp_gt_u32 s77, 29
	s_cbranch_scc0 .LBB0_254
	s_setprio 0
	s_and_b64 vcc, exec, s[16:17]
	s_cbranch_vccz .LBB0_257
	s_barrier

.LBB0_294:
	s_or_b64 exec, exec, s[6:7]
	v_lshlrev_b32_e32 v0, 15, v186
	s_lshl_b32 s6, s64, 22
	s_lshl_b32 s7, s75, 20
	v_and_b32_e32 v0, 0xffff0000, v0
	s_or_b32 s6, s6, s7
	v_lshl_add_u32 v0, v187, 12, v0
	v_and_b32_e32 v1, 1, v186
	s_add_u32 s6, s94, s6
	v_lshl_or_b32 v0, v1, 6, v0
	s_addc_u32 s7, s95, 0
	v_lshl_add_u32 v0, v188, 1, v0
	v_mov_b32_e32 v1, 0
	v_lshl_add_u64 v[2:3], s[6:7], 0, v[0:1]
	v_lshlrev_b32_e32 v0, 15, v189
	s_mov_b64 s[10:11], 0xf280080
	v_and_b32_e32 v0, 0xffff0000, v0
	s_add_u32 s8, s94, s8
	v_lshl_add_u64 v[40:41], v[2:3], 0, s[10:11]
	v_lshl_add_u32 v0, v190, 12, v0
	v_and_b32_e32 v2, 1, v189
	s_addc_u32 s9, s95, 0
	v_lshl_or_b32 v0, v2, 6, v0
	s_add_u32 s21, s8, 0x200100
	v_lshl_add_u32 v0, v191, 1, v0
	s_addc_u32 s22, s9, 0
	s_add_i32 s44, 0, 0x10000
	s_add_i32 s46, 0, 0x14000
	s_add_i32 s49, 0, 0x18000
	s_add_i32 s51, 0, 0x1c000
	v_lshl_add_u64 v[2:3], s[6:7], 0, v[0:1]
	v_add_u32_e32 v44, s44, v192
	v_add_u32_e32 v45, s46, v192
	s_add_i32 s44, s44, s66
	s_add_i32 s46, s46, s66
	v_add_u32_e32 v47, s49, v192
	v_add_u32_e32 v48, s51, v192
	s_add_i32 s49, s49, s66
	s_add_i32 s51, s51, s66
	v_lshl_add_u64 v[42:43], v[2:3], 0, s[10:11]
	s_mov_b32 s23, -2
	s_mov_b64 s[8:9], 0
	v_add_u32_e32 v46, 0, v193
	s_add_i32 s42, s14, 0xc000
	s_add_i32 s43, s14, 0xe000
	s_add_i32 s45, s44, 0x2000
	s_add_i32 s47, s46, 0x2000
	s_add_i32 s50, s49, 0x2000
	s_add_i32 s52, s51, 0x2000
	v_mov_b32_e32 v0, v1
	v_mov_b32_e32 v2, v1
	v_mov_b32_e32 v3, v1
	v_mov_b32_e32 v4, v1
	v_mov_b32_e32 v5, v1
	v_mov_b32_e32 v6, v1
	v_mov_b32_e32 v7, v1
	v_mov_b32_e32 v16, v1
	v_mov_b32_e32 v17, v1
	v_mov_b32_e32 v18, v1
	v_mov_b32_e32 v19, v1
	v_mov_b32_e32 v20, v1
	v_mov_b32_e32 v21, v1
	v_mov_b32_e32 v22, v1
	v_mov_b32_e32 v23, v1
	v_mov_b32_e32 v32, v1
	v_mov_b32_e32 v33, v1
	v_mov_b32_e32 v34, v1
	v_mov_b32_e32 v35, v1
	v_mov_b32_e32 v36, v1
	v_mov_b32_e32 v37, v1
	v_mov_b32_e32 v38, v1
	v_mov_b32_e32 v39, v1
	v_mov_b32_e32 v64, v1
	v_mov_b32_e32 v65, v1
	v_mov_b32_e32 v66, v1
	v_mov_b32_e32 v67, v1
	v_mov_b32_e32 v68, v1
	v_mov_b32_e32 v69, v1
	v_mov_b32_e32 v70, v1
	v_mov_b32_e32 v71, v1
	v_mov_b32_e32 v8, v1
	v_mov_b32_e32 v9, v1
	v_mov_b32_e32 v10, v1
	v_mov_b32_e32 v11, v1
	v_mov_b32_e32 v12, v1
	v_mov_b32_e32 v13, v1
	v_mov_b32_e32 v14, v1
	v_mov_b32_e32 v15, v1
	v_mov_b32_e32 v24, v1
	v_mov_b32_e32 v25, v1
	v_mov_b32_e32 v26, v1
	v_mov_b32_e32 v27, v1
	v_mov_b32_e32 v28, v1
	v_mov_b32_e32 v29, v1
	v_mov_b32_e32 v30, v1
	v_mov_b32_e32 v31, v1
	v_mov_b32_e32 v56, v1
	v_mov_b32_e32 v57, v1
	v_mov_b32_e32 v58, v1
	v_mov_b32_e32 v59, v1
	v_mov_b32_e32 v60, v1
	v_mov_b32_e32 v61, v1
	v_mov_b32_e32 v62, v1
	v_mov_b32_e32 v63, v1
	v_mov_b32_e32 v72, v1
	v_mov_b32_e32 v73, v1
	v_mov_b32_e32 v74, v1
	v_mov_b32_e32 v75, v1
	v_mov_b32_e32 v76, v1
	v_mov_b32_e32 v77, v1
	v_mov_b32_e32 v78, v1
	v_mov_b32_e32 v79, v1
	v_mov_b32_e32 v80, v1
	v_mov_b32_e32 v81, v1
	v_mov_b32_e32 v82, v1
	v_mov_b32_e32 v83, v1
	v_mov_b32_e32 v84, v1
	v_mov_b32_e32 v85, v1
	v_mov_b32_e32 v86, v1
	v_mov_b32_e32 v87, v1
	v_mov_b32_e32 v96, v1
	v_mov_b32_e32 v97, v1
	v_mov_b32_e32 v98, v1
	v_mov_b32_e32 v99, v1
	v_mov_b32_e32 v100, v1
	v_mov_b32_e32 v101, v1
	v_mov_b32_e32 v102, v1
	v_mov_b32_e32 v103, v1
	v_mov_b32_e32 v112, v1
	v_mov_b32_e32 v113, v1
	v_mov_b32_e32 v114, v1
	v_mov_b32_e32 v115, v1
	v_mov_b32_e32 v116, v1
	v_mov_b32_e32 v117, v1
	v_mov_b32_e32 v118, v1
	v_mov_b32_e32 v119, v1
	v_mov_b32_e32 v128, v1
	v_mov_b32_e32 v129, v1
	v_mov_b32_e32 v130, v1
	v_mov_b32_e32 v131, v1
	v_mov_b32_e32 v132, v1
	v_mov_b32_e32 v133, v1
	v_mov_b32_e32 v134, v1
	v_mov_b32_e32 v135, v1
	v_mov_b32_e32 v88, v1
	v_mov_b32_e32 v89, v1
	v_mov_b32_e32 v90, v1
	v_mov_b32_e32 v91, v1
	v_mov_b32_e32 v92, v1
	v_mov_b32_e32 v93, v1
	v_mov_b32_e32 v94, v1
	v_mov_b32_e32 v95, v1
	v_mov_b32_e32 v104, v1
	v_mov_b32_e32 v105, v1
	v_mov_b32_e32 v106, v1
	v_mov_b32_e32 v107, v1
	v_mov_b32_e32 v108, v1
	v_mov_b32_e32 v109, v1
	v_mov_b32_e32 v110, v1
	v_mov_b32_e32 v111, v1
	v_mov_b32_e32 v120, v1
	v_mov_b32_e32 v121, v1
	v_mov_b32_e32 v122, v1
	v_mov_b32_e32 v123, v1
	v_mov_b32_e32 v124, v1
	v_mov_b32_e32 v125, v1
	v_mov_b32_e32 v126, v1
	v_mov_b32_e32 v127, v1
	v_mov_b32_e32 v136, v1
	v_mov_b32_e32 v137, v1
	v_mov_b32_e32 v138, v1
	v_mov_b32_e32 v139, v1
	v_mov_b32_e32 v140, v1
	v_mov_b32_e32 v141, v1
	v_mov_b32_e32 v142, v1
	v_mov_b32_e32 v143, v1
	s_lshr_b32 s101, s88, 2
	s_cmp_lg_u32 s101, 1
	s_cbranch_scc1 .Lprio_skip2
	s_setprio 1
.Lprio_skip2:
.LBB0_295:
	ds_read_b128 v[50:53], v44
	ds_read_b128 v[170:173], v44 offset:1024
	ds_read_b128 v[174:177], v44 offset:2048
	ds_read_b128 v[178:181], v44 offset:3072
	ds_read_b128 v[196:199], v45
	ds_read_b128 v[200:203], v45 offset:1024
	ds_read_b128 v[204:207], v45 offset:2048
	ds_read_b128 v[208:211], v45 offset:3072
	s_add_u32 s10, s6, s8
	s_addc_u32 s11, s7, s9
	s_add_u32 s10, s10, 0xf200100
	s_addc_u32 s11, s11, 0
	s_add_u32 s53, s21, s8
	s_addc_u32 s54, s22, s9
	s_cmpk_eq_i32 s8, 0xf00
	s_cselect_b32 s13, s35, s11
	s_cselect_b32 s12, s34, s10
	s_cselect_b32 s11, s1, s54
	s_cselect_b32 s10, s0, s53
	s_mov_b32 m0, s42
	v_lshl_add_u64 v[54:55], v[40:41], 0, s[8:9]
	ds_read_b128 v[212:215], v46
	ds_read_b128 v[216:219], v46 offset:1024
	ds_read_b128 v[220:223], v46 offset:2048
	ds_read_b128 v[224:227], v46 offset:3072
	ds_read_b128 v[228:231], v46 offset:4096
	ds_read_b128 v[232:235], v46 offset:5120
	ds_read_b128 v[236:239], v46 offset:6144
	ds_read_b128 v[240:243], v46 offset:7168
	global_load_lds_dwordx4 v[54:55], off
	v_lshl_add_u64 v[54:55], v[42:43], 0, s[8:9]
	s_mov_b32 m0, s43
	s_nop 0
	global_load_lds_dwordx4 v[54:55], off
	s_waitcnt vmcnt(8)
	s_waitcnt lgkmcnt(0)
	s_barrier
	s_waitcnt lgkmcnt(0)
	v_mfma_f32_16x16x32_bf16 v[140:143], v[50:53], v[212:215], v[140:143]
	v_mfma_f32_16x16x32_bf16 v[136:139], v[174:177], v[212:215], v[136:139]
	v_mfma_f32_16x16x32_bf16 v[124:127], v[50:53], v[220:223], v[124:127]
	v_mfma_f32_16x16x32_bf16 v[120:123], v[174:177], v[220:223], v[120:123]
	v_mfma_f32_16x16x32_bf16 v[108:111], v[50:53], v[228:231], v[108:111]
	v_mfma_f32_16x16x32_bf16 v[104:107], v[174:177], v[228:231], v[104:107]
	v_mfma_f32_16x16x32_bf16 v[92:95], v[50:53], v[236:239], v[92:95]
	v_mfma_f32_16x16x32_bf16 v[88:91], v[174:177], v[236:239], v[88:91]
	v_mfma_f32_16x16x32_bf16 v[140:143], v[170:173], v[216:219], v[140:143]
	v_mfma_f32_16x16x32_bf16 v[136:139], v[178:181], v[216:219], v[136:139]
	v_mfma_f32_16x16x32_bf16 v[124:127], v[170:173], v[224:227], v[124:127]
	v_mfma_f32_16x16x32_bf16 v[120:123], v[178:181], v[224:227], v[120:123]
	v_mfma_f32_16x16x32_bf16 v[108:111], v[170:173], v[232:235], v[108:111]
	v_mfma_f32_16x16x32_bf16 v[104:107], v[178:181], v[232:235], v[104:107]
	v_mfma_f32_16x16x32_bf16 v[92:95], v[170:173], v[240:243], v[92:95]
	v_mfma_f32_16x16x32_bf16 v[88:91], v[178:181], v[240:243], v[88:91]
	v_mfma_f32_16x16x32_bf16 v[132:135], v[196:199], v[212:215], v[132:135]
	v_mfma_f32_16x16x32_bf16 v[128:131], v[204:207], v[212:215], v[128:131]
	v_mfma_f32_16x16x32_bf16 v[116:119], v[196:199], v[220:223], v[116:119]
	v_mfma_f32_16x16x32_bf16 v[112:115], v[204:207], v[220:223], v[112:115]
	v_mfma_f32_16x16x32_bf16 v[100:103], v[196:199], v[228:231], v[100:103]
	v_mfma_f32_16x16x32_bf16 v[96:99], v[204:207], v[228:231], v[96:99]
	v_mfma_f32_16x16x32_bf16 v[84:87], v[196:199], v[236:239], v[84:87]
	v_mfma_f32_16x16x32_bf16 v[80:83], v[204:207], v[236:239], v[80:83]
	v_mfma_f32_16x16x32_bf16 v[132:135], v[200:203], v[216:219], v[132:135]
	v_mfma_f32_16x16x32_bf16 v[128:131], v[208:211], v[216:219], v[128:131]
	v_mfma_f32_16x16x32_bf16 v[116:119], v[200:203], v[224:227], v[116:119]
	v_mfma_f32_16x16x32_bf16 v[112:115], v[208:211], v[224:227], v[112:115]
	v_mfma_f32_16x16x32_bf16 v[100:103], v[200:203], v[232:235], v[100:103]
	v_mfma_f32_16x16x32_bf16 v[96:99], v[208:211], v[232:235], v[96:99]
	v_mfma_f32_16x16x32_bf16 v[84:87], v[200:203], v[240:243], v[84:87]
	v_mfma_f32_16x16x32_bf16 v[80:83], v[208:211], v[240:243], v[80:83]
	s_barrier
	s_mov_b32 m0, s44
	v_lshl_add_u64 v[182:183], s[10:11], 0, v[150:151]
	s_add_u32 s54, s10, 0x80000
	ds_read_b128 v[212:215], v46 offset:16384
	ds_read_b128 v[216:219], v46 offset:17408
	ds_read_b128 v[220:223], v46 offset:18432
	ds_read_b128 v[224:227], v46 offset:19456
	ds_read_b128 v[228:231], v46 offset:20480
	ds_read_b128 v[232:235], v46 offset:21504
	ds_read_b128 v[236:239], v46 offset:22528
	ds_read_b128 v[240:243], v46 offset:23552
	global_load_lds_dwordx4 v[182:183], off
	v_lshl_add_u64 v[244:245], s[10:11], 0, v[154:155]
	s_mov_b32 m0, s45
	s_addc_u32 s55, s11, 0
	global_load_lds_dwordx4 v[244:245], off
	v_lshl_add_u64 v[54:55], s[54:55], 0, v[150:151]
	s_mov_b32 m0, s46
	v_lshl_add_u64 v[246:247], s[12:13], 0, v[148:149]
	global_load_lds_dwordx4 v[54:55], off
	v_lshl_add_u64 v[54:55], s[54:55], 0, v[154:155]
	s_mov_b32 m0, s47
	v_lshl_add_u64 v[248:249], s[12:13], 0, v[152:153]
	global_load_lds_dwordx4 v[54:55], off
	s_mov_b32 m0, s14
	s_nop 0
	global_load_lds_dwordx4 v[246:247], off
	s_mov_b32 m0, s16
	s_nop 0
	global_load_lds_dwordx4 v[248:249], off
	s_waitcnt vmcnt(8)
	s_waitcnt lgkmcnt(0)
	s_barrier
	s_waitcnt lgkmcnt(0)
	v_mfma_f32_16x16x32_bf16 v[76:79], v[50:53], v[212:215], v[76:79]
	v_mfma_f32_16x16x32_bf16 v[72:75], v[174:177], v[212:215], v[72:75]
	v_mfma_f32_16x16x32_bf16 v[60:63], v[50:53], v[220:223], v[60:63]
	v_mfma_f32_16x16x32_bf16 v[54:57], v[174:177], v[220:223], v[56:59]
	v_mfma_f32_16x16x32_bf16 v[28:31], v[50:53], v[228:231], v[28:31]
	v_mfma_f32_16x16x32_bf16 v[24:27], v[174:177], v[228:231], v[24:27]
	v_mfma_f32_16x16x32_bf16 v[12:15], v[50:53], v[236:239], v[12:15]
	v_mfma_f32_16x16x32_bf16 v[8:11], v[174:177], v[236:239], v[8:11]
	v_mfma_f32_16x16x32_bf16 v[76:79], v[170:173], v[216:219], v[76:79]
	v_mfma_f32_16x16x32_bf16 v[72:75], v[178:181], v[216:219], v[72:75]
	v_mfma_f32_16x16x32_bf16 v[60:63], v[170:173], v[224:227], v[60:63]
	v_mfma_f32_16x16x32_bf16 v[54:57], v[178:181], v[224:227], v[54:57]
	v_mfma_f32_16x16x32_bf16 v[28:31], v[170:173], v[232:235], v[28:31]
	v_mfma_f32_16x16x32_bf16 v[24:27], v[178:181], v[232:235], v[24:27]
	v_mfma_f32_16x16x32_bf16 v[12:15], v[170:173], v[240:243], v[12:15]
	v_mfma_f32_16x16x32_bf16 v[8:11], v[178:181], v[240:243], v[8:11]
	v_mfma_f32_16x16x32_bf16 v[64:67], v[204:207], v[212:215], v[64:67]
	v_mfma_f32_16x16x32_bf16 v[36:39], v[196:199], v[220:223], v[36:39]
	v_mfma_f32_16x16x32_bf16 v[32:35], v[204:207], v[220:223], v[32:35]
	v_mfma_f32_16x16x32_bf16 v[20:23], v[196:199], v[228:231], v[20:23]
	v_mfma_f32_16x16x32_bf16 v[16:19], v[204:207], v[228:231], v[16:19]
	v_mfma_f32_16x16x32_bf16 v[4:7], v[196:199], v[236:239], v[4:7]
	v_mfma_f32_16x16x32_bf16 v[0:3], v[204:207], v[236:239], v[0:3]
	v_mfma_f32_16x16x32_bf16 v[50:53], v[196:199], v[212:215], v[68:71]
	v_mfma_f32_16x16x32_bf16 v[64:67], v[208:211], v[216:219], v[64:67]
	v_mfma_f32_16x16x32_bf16 v[36:39], v[200:203], v[224:227], v[36:39]
	v_mfma_f32_16x16x32_bf16 v[32:35], v[208:211], v[224:227], v[32:35]
	v_mfma_f32_16x16x32_bf16 v[20:23], v[200:203], v[232:235], v[20:23]
	v_mfma_f32_16x16x32_bf16 v[16:19], v[208:211], v[232:235], v[16:19]
	v_mfma_f32_16x16x32_bf16 v[4:7], v[200:203], v[240:243], v[4:7]
	v_mfma_f32_16x16x32_bf16 v[0:3], v[208:211], v[240:243], v[0:3]
	v_mfma_f32_16x16x32_bf16 v[50:53], v[200:203], v[216:219], v[50:53]
	s_barrier
	ds_read_b128 v[68:71], v47
	ds_read_b128 v[170:173], v47 offset:1024
	ds_read_b128 v[174:177], v47 offset:2048
	ds_read_b128 v[178:181], v47 offset:3072
	ds_read_b128 v[196:199], v48
	ds_read_b128 v[200:203], v48 offset:1024
	ds_read_b128 v[204:207], v48 offset:2048
	ds_read_b128 v[208:211], v48 offset:3072
	s_add_u32 s12, s12, 0x80000
	s_addc_u32 s13, s13, 0
	s_mov_b32 m0, s17
	v_lshl_add_u64 v[58:59], s[12:13], 0, v[148:149]
	ds_read_b128 v[212:215], v46 offset:32768
	ds_read_b128 v[216:219], v46 offset:33792
	ds_read_b128 v[220:223], v46 offset:34816
	ds_read_b128 v[224:227], v46 offset:35840
	ds_read_b128 v[228:231], v46 offset:36864
	ds_read_b128 v[232:235], v46 offset:37888
	ds_read_b128 v[236:239], v46 offset:38912
	ds_read_b128 v[240:243], v46 offset:39936
	global_load_lds_dwordx4 v[58:59], off
	v_lshl_add_u64 v[58:59], s[12:13], 0, v[152:153]
	s_mov_b32 m0, s18
	s_nop 0
	global_load_lds_dwordx4 v[58:59], off
	s_waitcnt vmcnt(8)
	s_waitcnt lgkmcnt(0)
	s_barrier
	s_waitcnt lgkmcnt(0)
	v_mfma_f32_16x16x32_bf16 v[140:143], v[68:71], v[212:215], v[140:143]
	v_mfma_f32_16x16x32_bf16 v[136:139], v[174:177], v[212:215], v[136:139]
	v_mfma_f32_16x16x32_bf16 v[124:127], v[68:71], v[220:223], v[124:127]
	v_mfma_f32_16x16x32_bf16 v[120:123], v[174:177], v[220:223], v[120:123]
	v_mfma_f32_16x16x32_bf16 v[108:111], v[68:71], v[228:231], v[108:111]
	v_mfma_f32_16x16x32_bf16 v[104:107], v[174:177], v[228:231], v[104:107]
	v_mfma_f32_16x16x32_bf16 v[92:95], v[68:71], v[236:239], v[92:95]
	v_mfma_f32_16x16x32_bf16 v[88:91], v[174:177], v[236:239], v[88:91]
	v_mfma_f32_16x16x32_bf16 v[140:143], v[170:173], v[216:219], v[140:143]
	v_mfma_f32_16x16x32_bf16 v[136:139], v[178:181], v[216:219], v[136:139]
	v_mfma_f32_16x16x32_bf16 v[124:127], v[170:173], v[224:227], v[124:127]
	v_mfma_f32_16x16x32_bf16 v[120:123], v[178:181], v[224:227], v[120:123]
	v_mfma_f32_16x16x32_bf16 v[108:111], v[170:173], v[232:235], v[108:111]
	v_mfma_f32_16x16x32_bf16 v[104:107], v[178:181], v[232:235], v[104:107]
	v_mfma_f32_16x16x32_bf16 v[92:95], v[170:173], v[240:243], v[92:95]
	v_mfma_f32_16x16x32_bf16 v[88:91], v[178:181], v[240:243], v[88:91]
	v_mfma_f32_16x16x32_bf16 v[132:135], v[196:199], v[212:215], v[132:135]
	v_mfma_f32_16x16x32_bf16 v[128:131], v[204:207], v[212:215], v[128:131]
	v_mfma_f32_16x16x32_bf16 v[116:119], v[196:199], v[220:223], v[116:119]
	v_mfma_f32_16x16x32_bf16 v[112:115], v[204:207], v[220:223], v[112:115]
	v_mfma_f32_16x16x32_bf16 v[100:103], v[196:199], v[228:231], v[100:103]
	v_mfma_f32_16x16x32_bf16 v[96:99], v[204:207], v[228:231], v[96:99]
	v_mfma_f32_16x16x32_bf16 v[84:87], v[196:199], v[236:239], v[84:87]
	v_mfma_f32_16x16x32_bf16 v[80:83], v[204:207], v[236:239], v[80:83]
	v_mfma_f32_16x16x32_bf16 v[132:135], v[200:203], v[216:219], v[132:135]
	v_mfma_f32_16x16x32_bf16 v[128:131], v[208:211], v[216:219], v[128:131]
	v_mfma_f32_16x16x32_bf16 v[116:119], v[200:203], v[224:227], v[116:119]
	v_mfma_f32_16x16x32_bf16 v[112:115], v[208:211], v[224:227], v[112:115]
	v_mfma_f32_16x16x32_bf16 v[100:103], v[200:203], v[232:235], v[100:103]
	v_mfma_f32_16x16x32_bf16 v[96:99], v[208:211], v[232:235], v[96:99]
	v_mfma_f32_16x16x32_bf16 v[84:87], v[200:203], v[240:243], v[84:87]
	v_mfma_f32_16x16x32_bf16 v[80:83], v[208:211], v[240:243], v[80:83]
	s_barrier
	s_mov_b32 m0, s49
	v_lshl_add_u64 v[58:59], v[182:183], 0, s[4:5]
	s_add_u32 s10, s10, 0x80080
	ds_read_b128 v[212:215], v46 offset:49152
	ds_read_b128 v[216:219], v46 offset:50176
	ds_read_b128 v[220:223], v46 offset:51200
	ds_read_b128 v[224:227], v46 offset:52224
	ds_read_b128 v[228:231], v46 offset:53248
	ds_read_b128 v[232:235], v46 offset:54272
	ds_read_b128 v[236:239], v46 offset:55296
	ds_read_b128 v[240:243], v46 offset:56320
	global_load_lds_dwordx4 v[58:59], off
	v_lshl_add_u64 v[58:59], v[244:245], 0, s[4:5]
	s_mov_b32 m0, s50
	s_addc_u32 s11, s11, 0
	global_load_lds_dwordx4 v[58:59], off
	v_lshl_add_u64 v[58:59], s[10:11], 0, v[150:151]
	s_mov_b32 m0, s51
	s_nop 0
	global_load_lds_dwordx4 v[58:59], off
	v_lshl_add_u64 v[58:59], s[10:11], 0, v[154:155]
	s_mov_b32 m0, s52
	s_nop 0
	global_load_lds_dwordx4 v[58:59], off
	v_lshl_add_u64 v[58:59], v[246:247], 0, s[4:5]
	s_mov_b32 m0, s19
	s_nop 0
	global_load_lds_dwordx4 v[58:59], off
	v_lshl_add_u64 v[58:59], v[248:249], 0, s[4:5]
	s_mov_b32 m0, s20
	s_nop 0
	global_load_lds_dwordx4 v[58:59], off
	s_waitcnt vmcnt(8)
	s_waitcnt lgkmcnt(0)
	s_barrier
	s_waitcnt lgkmcnt(0)
	v_mfma_f32_16x16x32_bf16 v[76:79], v[68:71], v[212:215], v[76:79]
	v_mfma_f32_16x16x32_bf16 v[72:75], v[174:177], v[212:215], v[72:75]
	v_mfma_f32_16x16x32_bf16 v[58:61], v[68:71], v[220:223], v[60:63]
	v_mfma_f32_16x16x32_bf16 v[54:57], v[174:177], v[220:223], v[54:57]
	v_mfma_f32_16x16x32_bf16 v[28:31], v[68:71], v[228:231], v[28:31]
	v_mfma_f32_16x16x32_bf16 v[24:27], v[174:177], v[228:231], v[24:27]
	v_mfma_f32_16x16x32_bf16 v[12:15], v[68:71], v[236:239], v[12:15]
	v_mfma_f32_16x16x32_bf16 v[8:11], v[174:177], v[236:239], v[8:11]
	v_mfma_f32_16x16x32_bf16 v[76:79], v[170:173], v[216:219], v[76:79]
	v_mfma_f32_16x16x32_bf16 v[72:75], v[178:181], v[216:219], v[72:75]
	v_mfma_f32_16x16x32_bf16 v[60:63], v[170:173], v[224:227], v[58:61]
	v_mfma_f32_16x16x32_bf16 v[56:59], v[178:181], v[224:227], v[54:57]
	v_mfma_f32_16x16x32_bf16 v[28:31], v[170:173], v[232:235], v[28:31]
	v_mfma_f32_16x16x32_bf16 v[24:27], v[178:181], v[232:235], v[24:27]
	v_mfma_f32_16x16x32_bf16 v[12:15], v[170:173], v[240:243], v[12:15]
	v_mfma_f32_16x16x32_bf16 v[8:11], v[178:181], v[240:243], v[8:11]
	v_mfma_f32_16x16x32_bf16 v[50:53], v[196:199], v[212:215], v[50:53]
	v_mfma_f32_16x16x32_bf16 v[68:71], v[200:203], v[216:219], v[50:53]
	v_mfma_f32_16x16x32_bf16 v[50:53], v[204:207], v[212:215], v[64:67]
	v_mfma_f32_16x16x32_bf16 v[36:39], v[196:199], v[220:223], v[36:39]
	v_mfma_f32_16x16x32_bf16 v[32:35], v[204:207], v[220:223], v[32:35]
	v_mfma_f32_16x16x32_bf16 v[20:23], v[196:199], v[228:231], v[20:23]
	v_mfma_f32_16x16x32_bf16 v[16:19], v[204:207], v[228:231], v[16:19]
	v_mfma_f32_16x16x32_bf16 v[4:7], v[196:199], v[236:239], v[4:7]
	v_mfma_f32_16x16x32_bf16 v[0:3], v[204:207], v[236:239], v[0:3]
	v_mfma_f32_16x16x32_bf16 v[64:67], v[208:211], v[216:219], v[50:53]
	v_mfma_f32_16x16x32_bf16 v[36:39], v[200:203], v[224:227], v[36:39]
	v_mfma_f32_16x16x32_bf16 v[32:35], v[208:211], v[224:227], v[32:35]
	v_mfma_f32_16x16x32_bf16 v[20:23], v[200:203], v[232:235], v[20:23]
	v_mfma_f32_16x16x32_bf16 v[16:19], v[208:211], v[232:235], v[16:19]
	v_mfma_f32_16x16x32_bf16 v[4:7], v[200:203], v[240:243], v[4:7]
	v_mfma_f32_16x16x32_bf16 v[0:3], v[208:211], v[240:243], v[0:3]
	s_barrier
	s_add_i32 s23, s23, 2
	s_add_u32 s8, s8, 0x100
	s_addc_u32 s9, s9, 0
	s_cmp_gt_u32 s23, 29
	s_cbranch_scc0 .LBB0_295
	s_setprio 0
	s_and_b64 vcc, exec, s[38:39]
	s_cbranch_vccz .LBB0_298
	s_barrier

.LBB0_337:
	s_or_b64 exec, exec, s[6:7]
	s_waitcnt vmcnt(0)
	v_lshlrev_b32_e32 v0, 15, v186
	s_lshl_b32 s2, s64, 22
	s_lshl_b32 s3, s75, 20
	v_and_b32_e32 v0, 0xffff0000, v0
	s_or_b32 s2, s2, s3
	v_lshl_add_u32 v0, v187, 12, v0
	v_and_b32_e32 v1, 1, v186
	s_add_u32 s2, s94, s2
	v_lshl_or_b32 v0, v1, 6, v0
	s_addc_u32 s3, s95, 0
	v_lshl_add_u32 v0, v188, 1, v0
	v_mov_b32_e32 v1, 0
	v_lshl_add_u64 v[2:3], s[2:3], 0, v[0:1]
	v_lshlrev_b32_e32 v0, 15, v189
	s_mov_b64 s[6:7], 0xf280080
	v_and_b32_e32 v0, 0xffff0000, v0
	v_lshl_add_u64 v[40:41], v[2:3], 0, s[6:7]
	v_lshl_add_u32 v0, v190, 12, v0
	v_and_b32_e32 v2, 1, v189
	v_lshl_or_b32 v0, v2, 6, v0
	v_lshl_add_u32 v0, v191, 1, v0
	v_lshl_add_u64 v[2:3], s[2:3], 0, v[0:1]
	v_lshl_add_u64 v[42:43], v[2:3], 0, s[6:7]
	s_add_u32 s6, s94, s8
	s_addc_u32 s7, s95, 0
	s_add_u32 s19, s6, 0x200100
	s_addc_u32 s20, s7, 0
	s_add_i32 s40, 0, 0x10000
	s_add_i32 s42, 0, 0x14000
	s_add_i32 s44, 0, 0x18000
	s_add_i32 s46, 0, 0x1c000
	v_add_u32_e32 v44, s40, v192
	v_add_u32_e32 v45, s42, v192
	s_add_i32 s40, s40, s66
	s_add_i32 s42, s42, s66
	v_add_u32_e32 v47, s44, v192
	v_add_u32_e32 v48, s46, v192
	s_add_i32 s44, s44, s66
	s_add_i32 s46, s46, s66
	s_mov_b32 s21, -2
	s_mov_b64 s[6:7], 0
	v_add_u32_e32 v46, 0, v193
	s_add_i32 s22, s12, 0xc000
	s_add_i32 s23, s12, 0xe000
	s_add_i32 s41, s40, 0x2000
	s_add_i32 s43, s42, 0x2000
	s_add_i32 s45, s44, 0x2000
	s_add_i32 s47, s46, 0x2000
	v_mov_b32_e32 v0, v1
	v_mov_b32_e32 v2, v1
	v_mov_b32_e32 v3, v1
	v_mov_b32_e32 v4, v1
	v_mov_b32_e32 v5, v1
	v_mov_b32_e32 v6, v1
	v_mov_b32_e32 v7, v1
	v_mov_b32_e32 v16, v1
	v_mov_b32_e32 v17, v1
	v_mov_b32_e32 v18, v1
	v_mov_b32_e32 v19, v1
	v_mov_b32_e32 v20, v1
	v_mov_b32_e32 v21, v1
	v_mov_b32_e32 v22, v1
	v_mov_b32_e32 v23, v1
	v_mov_b32_e32 v32, v1
	v_mov_b32_e32 v33, v1
	v_mov_b32_e32 v34, v1
	v_mov_b32_e32 v35, v1
	v_mov_b32_e32 v36, v1
	v_mov_b32_e32 v37, v1
	v_mov_b32_e32 v38, v1
	v_mov_b32_e32 v39, v1
	v_mov_b32_e32 v64, v1
	v_mov_b32_e32 v65, v1
	v_mov_b32_e32 v66, v1
	v_mov_b32_e32 v67, v1
	v_mov_b32_e32 v68, v1
	v_mov_b32_e32 v69, v1
	v_mov_b32_e32 v70, v1
	v_mov_b32_e32 v71, v1
	v_mov_b32_e32 v8, v1
	v_mov_b32_e32 v9, v1
	v_mov_b32_e32 v10, v1
	v_mov_b32_e32 v11, v1
	v_mov_b32_e32 v12, v1
	v_mov_b32_e32 v13, v1
	v_mov_b32_e32 v14, v1
	v_mov_b32_e32 v15, v1
	v_mov_b32_e32 v24, v1
	v_mov_b32_e32 v25, v1
	v_mov_b32_e32 v26, v1
	v_mov_b32_e32 v27, v1
	v_mov_b32_e32 v28, v1
	v_mov_b32_e32 v29, v1
	v_mov_b32_e32 v30, v1
	v_mov_b32_e32 v31, v1
	v_mov_b32_e32 v56, v1
	v_mov_b32_e32 v57, v1
	v_mov_b32_e32 v58, v1
	v_mov_b32_e32 v59, v1
	v_mov_b32_e32 v60, v1
	v_mov_b32_e32 v61, v1
	v_mov_b32_e32 v62, v1
	v_mov_b32_e32 v63, v1
	v_mov_b32_e32 v72, v1
	v_mov_b32_e32 v73, v1
	v_mov_b32_e32 v74, v1
	v_mov_b32_e32 v75, v1
	v_mov_b32_e32 v76, v1
	v_mov_b32_e32 v77, v1
	v_mov_b32_e32 v78, v1
	v_mov_b32_e32 v79, v1
	v_mov_b32_e32 v80, v1
	v_mov_b32_e32 v81, v1
	v_mov_b32_e32 v82, v1
	v_mov_b32_e32 v83, v1
	v_mov_b32_e32 v84, v1
	v_mov_b32_e32 v85, v1
	v_mov_b32_e32 v86, v1
	v_mov_b32_e32 v87, v1
	v_mov_b32_e32 v96, v1
	v_mov_b32_e32 v97, v1
	v_mov_b32_e32 v98, v1
	v_mov_b32_e32 v99, v1
	v_mov_b32_e32 v100, v1
	v_mov_b32_e32 v101, v1
	v_mov_b32_e32 v102, v1
	v_mov_b32_e32 v103, v1
	v_mov_b32_e32 v112, v1
	v_mov_b32_e32 v113, v1
	v_mov_b32_e32 v114, v1
	v_mov_b32_e32 v115, v1
	v_mov_b32_e32 v116, v1
	v_mov_b32_e32 v117, v1
	v_mov_b32_e32 v118, v1
	v_mov_b32_e32 v119, v1
	v_mov_b32_e32 v128, v1
	v_mov_b32_e32 v129, v1
	v_mov_b32_e32 v130, v1
	v_mov_b32_e32 v131, v1
	v_mov_b32_e32 v132, v1
	v_mov_b32_e32 v133, v1
	v_mov_b32_e32 v134, v1
	v_mov_b32_e32 v135, v1
	v_mov_b32_e32 v88, v1
	v_mov_b32_e32 v89, v1
	v_mov_b32_e32 v90, v1
	v_mov_b32_e32 v91, v1
	v_mov_b32_e32 v92, v1
	v_mov_b32_e32 v93, v1
	v_mov_b32_e32 v94, v1
	v_mov_b32_e32 v95, v1
	v_mov_b32_e32 v104, v1
	v_mov_b32_e32 v105, v1
	v_mov_b32_e32 v106, v1
	v_mov_b32_e32 v107, v1
	v_mov_b32_e32 v108, v1
	v_mov_b32_e32 v109, v1
	v_mov_b32_e32 v110, v1
	v_mov_b32_e32 v111, v1
	v_mov_b32_e32 v120, v1
	v_mov_b32_e32 v121, v1
	v_mov_b32_e32 v122, v1
	v_mov_b32_e32 v123, v1
	v_mov_b32_e32 v124, v1
	v_mov_b32_e32 v125, v1
	v_mov_b32_e32 v126, v1
	v_mov_b32_e32 v127, v1
	v_mov_b32_e32 v136, v1
	v_mov_b32_e32 v137, v1
	v_mov_b32_e32 v138, v1
	v_mov_b32_e32 v139, v1
	v_mov_b32_e32 v140, v1
	v_mov_b32_e32 v141, v1
	v_mov_b32_e32 v142, v1
	v_mov_b32_e32 v143, v1
	s_lshr_b32 s101, s88, 2
	s_cmp_lg_u32 s101, 1
	s_cbranch_scc1 .Lprio_skip3
	s_setprio 1
.Lprio_skip3:
.LBB0_338:
	ds_read_b128 v[50:53], v44
	ds_read_b128 v[156:159], v44 offset:1024
	ds_read_b128 v[160:163], v44 offset:2048
	ds_read_b128 v[164:167], v44 offset:3072
	ds_read_b128 v[168:171], v45
	ds_read_b128 v[172:175], v45 offset:1024
	ds_read_b128 v[176:179], v45 offset:2048
	ds_read_b128 v[180:183], v45 offset:3072
	s_add_u32 s8, s2, s6
	s_addc_u32 s9, s3, s7
	s_add_u32 s8, s8, 0xf200100
	s_addc_u32 s9, s9, 0
	s_add_u32 s48, s19, s6
	s_addc_u32 s49, s20, s7
	s_cmpk_eq_i32 s6, 0xf00
	s_cselect_b32 s11, s35, s9
	s_cselect_b32 s10, s34, s8
	s_cselect_b32 s9, s1, s49
	s_cselect_b32 s8, s0, s48
	s_mov_b32 m0, s22
	v_lshl_add_u64 v[54:55], v[40:41], 0, s[6:7]
	ds_read_b128 v[186:189], v46
	ds_read_b128 v[190:193], v46 offset:1024
	ds_read_b128 v[194:197], v46 offset:2048
	ds_read_b128 v[198:201], v46 offset:3072
	ds_read_b128 v[202:205], v46 offset:4096
	ds_read_b128 v[206:209], v46 offset:5120
	ds_read_b128 v[210:213], v46 offset:6144
	ds_read_b128 v[214:217], v46 offset:7168
	global_load_lds_dwordx4 v[54:55], off
	v_lshl_add_u64 v[54:55], v[42:43], 0, s[6:7]
	s_mov_b32 m0, s23
	s_nop 0
	global_load_lds_dwordx4 v[54:55], off
	s_waitcnt vmcnt(8)
	s_waitcnt lgkmcnt(0)
	s_barrier
	s_waitcnt lgkmcnt(0)
	v_mfma_f32_16x16x32_bf16 v[140:143], v[50:53], v[186:189], v[140:143]
	v_mfma_f32_16x16x32_bf16 v[136:139], v[160:163], v[186:189], v[136:139]
	v_mfma_f32_16x16x32_bf16 v[124:127], v[50:53], v[194:197], v[124:127]
	v_mfma_f32_16x16x32_bf16 v[120:123], v[160:163], v[194:197], v[120:123]
	v_mfma_f32_16x16x32_bf16 v[108:111], v[50:53], v[202:205], v[108:111]
	v_mfma_f32_16x16x32_bf16 v[104:107], v[160:163], v[202:205], v[104:107]
	v_mfma_f32_16x16x32_bf16 v[92:95], v[50:53], v[210:213], v[92:95]
	v_mfma_f32_16x16x32_bf16 v[88:91], v[160:163], v[210:213], v[88:91]
	v_mfma_f32_16x16x32_bf16 v[140:143], v[156:159], v[190:193], v[140:143]
	v_mfma_f32_16x16x32_bf16 v[136:139], v[164:167], v[190:193], v[136:139]
	v_mfma_f32_16x16x32_bf16 v[124:127], v[156:159], v[198:201], v[124:127]
	v_mfma_f32_16x16x32_bf16 v[120:123], v[164:167], v[198:201], v[120:123]
	v_mfma_f32_16x16x32_bf16 v[108:111], v[156:159], v[206:209], v[108:111]
	v_mfma_f32_16x16x32_bf16 v[104:107], v[164:167], v[206:209], v[104:107]
	v_mfma_f32_16x16x32_bf16 v[92:95], v[156:159], v[214:217], v[92:95]
	v_mfma_f32_16x16x32_bf16 v[88:91], v[164:167], v[214:217], v[88:91]
	v_mfma_f32_16x16x32_bf16 v[132:135], v[168:171], v[186:189], v[132:135]
	v_mfma_f32_16x16x32_bf16 v[128:131], v[176:179], v[186:189], v[128:131]
	v_mfma_f32_16x16x32_bf16 v[116:119], v[168:171], v[194:197], v[116:119]
	v_mfma_f32_16x16x32_bf16 v[112:115], v[176:179], v[194:197], v[112:115]
	v_mfma_f32_16x16x32_bf16 v[100:103], v[168:171], v[202:205], v[100:103]
	v_mfma_f32_16x16x32_bf16 v[96:99], v[176:179], v[202:205], v[96:99]
	v_mfma_f32_16x16x32_bf16 v[84:87], v[168:171], v[210:213], v[84:87]
	v_mfma_f32_16x16x32_bf16 v[80:83], v[176:179], v[210:213], v[80:83]
	v_mfma_f32_16x16x32_bf16 v[132:135], v[172:175], v[190:193], v[132:135]
	v_mfma_f32_16x16x32_bf16 v[128:131], v[180:183], v[190:193], v[128:131]
	v_mfma_f32_16x16x32_bf16 v[116:119], v[172:175], v[198:201], v[116:119]
	v_mfma_f32_16x16x32_bf16 v[112:115], v[180:183], v[198:201], v[112:115]
	v_mfma_f32_16x16x32_bf16 v[100:103], v[172:175], v[206:209], v[100:103]
	v_mfma_f32_16x16x32_bf16 v[96:99], v[180:183], v[206:209], v[96:99]
	v_mfma_f32_16x16x32_bf16 v[84:87], v[172:175], v[214:217], v[84:87]
	v_mfma_f32_16x16x32_bf16 v[80:83], v[180:183], v[214:217], v[80:83]
	s_barrier
	s_mov_b32 m0, s40
	v_lshl_add_u64 v[218:219], s[8:9], 0, v[150:151]
	s_add_u32 s48, s8, 0x80000
	ds_read_b128 v[186:189], v46 offset:16384
	ds_read_b128 v[190:193], v46 offset:17408
	ds_read_b128 v[194:197], v46 offset:18432
	ds_read_b128 v[198:201], v46 offset:19456
	ds_read_b128 v[202:205], v46 offset:20480
	ds_read_b128 v[206:209], v46 offset:21504
	ds_read_b128 v[210:213], v46 offset:22528
	ds_read_b128 v[214:217], v46 offset:23552
	global_load_lds_dwordx4 v[218:219], off
	v_lshl_add_u64 v[220:221], s[8:9], 0, v[154:155]
	s_mov_b32 m0, s41
	s_addc_u32 s49, s9, 0
	global_load_lds_dwordx4 v[220:221], off
	v_lshl_add_u64 v[54:55], s[48:49], 0, v[150:151]
	s_mov_b32 m0, s42
	v_lshl_add_u64 v[222:223], s[10:11], 0, v[148:149]
	global_load_lds_dwordx4 v[54:55], off
	v_lshl_add_u64 v[54:55], s[48:49], 0, v[154:155]
	s_mov_b32 m0, s43
	v_lshl_add_u64 v[224:225], s[10:11], 0, v[152:153]
	global_load_lds_dwordx4 v[54:55], off
	s_mov_b32 m0, s12
	s_nop 0
	global_load_lds_dwordx4 v[222:223], off
	s_mov_b32 m0, s14
	s_nop 0
	global_load_lds_dwordx4 v[224:225], off
	s_waitcnt vmcnt(8)
	s_waitcnt lgkmcnt(0)
	s_barrier
	s_waitcnt lgkmcnt(0)
	v_mfma_f32_16x16x32_bf16 v[76:79], v[50:53], v[186:189], v[76:79]
	v_mfma_f32_16x16x32_bf16 v[72:75], v[160:163], v[186:189], v[72:75]
	v_mfma_f32_16x16x32_bf16 v[60:63], v[50:53], v[194:197], v[60:63]
	v_mfma_f32_16x16x32_bf16 v[54:57], v[160:163], v[194:197], v[56:59]
	v_mfma_f32_16x16x32_bf16 v[28:31], v[50:53], v[202:205], v[28:31]
	v_mfma_f32_16x16x32_bf16 v[24:27], v[160:163], v[202:205], v[24:27]
	v_mfma_f32_16x16x32_bf16 v[12:15], v[50:53], v[210:213], v[12:15]
	v_mfma_f32_16x16x32_bf16 v[8:11], v[160:163], v[210:213], v[8:11]
	v_mfma_f32_16x16x32_bf16 v[76:79], v[156:159], v[190:193], v[76:79]
	v_mfma_f32_16x16x32_bf16 v[72:75], v[164:167], v[190:193], v[72:75]
	v_mfma_f32_16x16x32_bf16 v[60:63], v[156:159], v[198:201], v[60:63]
	v_mfma_f32_16x16x32_bf16 v[54:57], v[164:167], v[198:201], v[54:57]
	v_mfma_f32_16x16x32_bf16 v[28:31], v[156:159], v[206:209], v[28:31]
	v_mfma_f32_16x16x32_bf16 v[24:27], v[164:167], v[206:209], v[24:27]
	v_mfma_f32_16x16x32_bf16 v[12:15], v[156:159], v[214:217], v[12:15]
	v_mfma_f32_16x16x32_bf16 v[8:11], v[164:167], v[214:217], v[8:11]
	v_mfma_f32_16x16x32_bf16 v[64:67], v[176:179], v[186:189], v[64:67]
	v_mfma_f32_16x16x32_bf16 v[36:39], v[168:171], v[194:197], v[36:39]
	v_mfma_f32_16x16x32_bf16 v[32:35], v[176:179], v[194:197], v[32:35]
	v_mfma_f32_16x16x32_bf16 v[20:23], v[168:171], v[202:205], v[20:23]
	v_mfma_f32_16x16x32_bf16 v[16:19], v[176:179], v[202:205], v[16:19]
	v_mfma_f32_16x16x32_bf16 v[4:7], v[168:171], v[210:213], v[4:7]
	v_mfma_f32_16x16x32_bf16 v[0:3], v[176:179], v[210:213], v[0:3]
	v_mfma_f32_16x16x32_bf16 v[50:53], v[168:171], v[186:189], v[68:71]
	v_mfma_f32_16x16x32_bf16 v[64:67], v[180:183], v[190:193], v[64:67]
	v_mfma_f32_16x16x32_bf16 v[36:39], v[172:175], v[198:201], v[36:39]
	v_mfma_f32_16x16x32_bf16 v[32:35], v[180:183], v[198:201], v[32:35]
	v_mfma_f32_16x16x32_bf16 v[20:23], v[172:175], v[206:209], v[20:23]
	v_mfma_f32_16x16x32_bf16 v[16:19], v[180:183], v[206:209], v[16:19]
	v_mfma_f32_16x16x32_bf16 v[4:7], v[172:175], v[214:217], v[4:7]
	v_mfma_f32_16x16x32_bf16 v[0:3], v[180:183], v[214:217], v[0:3]
	v_mfma_f32_16x16x32_bf16 v[50:53], v[172:175], v[190:193], v[50:53]
	s_barrier
	ds_read_b128 v[68:71], v47
	ds_read_b128 v[156:159], v47 offset:1024
	ds_read_b128 v[160:163], v47 offset:2048
	ds_read_b128 v[164:167], v47 offset:3072
	ds_read_b128 v[168:171], v48
	ds_read_b128 v[172:175], v48 offset:1024
	ds_read_b128 v[176:179], v48 offset:2048
	ds_read_b128 v[180:183], v48 offset:3072
	s_add_u32 s10, s10, 0x80000
	s_addc_u32 s11, s11, 0
	s_mov_b32 m0, s15
	v_lshl_add_u64 v[58:59], s[10:11], 0, v[148:149]
	ds_read_b128 v[186:189], v46 offset:32768
	ds_read_b128 v[190:193], v46 offset:33792
	ds_read_b128 v[194:197], v46 offset:34816
	ds_read_b128 v[198:201], v46 offset:35840
	ds_read_b128 v[202:205], v46 offset:36864
	ds_read_b128 v[206:209], v46 offset:37888
	ds_read_b128 v[210:213], v46 offset:38912
	ds_read_b128 v[214:217], v46 offset:39936
	global_load_lds_dwordx4 v[58:59], off
	v_lshl_add_u64 v[58:59], s[10:11], 0, v[152:153]
	s_mov_b32 m0, s16
	s_nop 0
	global_load_lds_dwordx4 v[58:59], off
	s_waitcnt vmcnt(8)
	s_waitcnt lgkmcnt(0)
	s_barrier
	s_waitcnt lgkmcnt(0)
	v_mfma_f32_16x16x32_bf16 v[140:143], v[68:71], v[186:189], v[140:143]
	v_mfma_f32_16x16x32_bf16 v[136:139], v[160:163], v[186:189], v[136:139]
	v_mfma_f32_16x16x32_bf16 v[124:127], v[68:71], v[194:197], v[124:127]
	v_mfma_f32_16x16x32_bf16 v[120:123], v[160:163], v[194:197], v[120:123]
	v_mfma_f32_16x16x32_bf16 v[108:111], v[68:71], v[202:205], v[108:111]
	v_mfma_f32_16x16x32_bf16 v[104:107], v[160:163], v[202:205], v[104:107]
	v_mfma_f32_16x16x32_bf16 v[92:95], v[68:71], v[210:213], v[92:95]
	v_mfma_f32_16x16x32_bf16 v[88:91], v[160:163], v[210:213], v[88:91]
	v_mfma_f32_16x16x32_bf16 v[140:143], v[156:159], v[190:193], v[140:143]
	v_mfma_f32_16x16x32_bf16 v[136:139], v[164:167], v[190:193], v[136:139]
	v_mfma_f32_16x16x32_bf16 v[124:127], v[156:159], v[198:201], v[124:127]
	v_mfma_f32_16x16x32_bf16 v[120:123], v[164:167], v[198:201], v[120:123]
	v_mfma_f32_16x16x32_bf16 v[108:111], v[156:159], v[206:209], v[108:111]
	v_mfma_f32_16x16x32_bf16 v[104:107], v[164:167], v[206:209], v[104:107]
	v_mfma_f32_16x16x32_bf16 v[92:95], v[156:159], v[214:217], v[92:95]
	v_mfma_f32_16x16x32_bf16 v[88:91], v[164:167], v[214:217], v[88:91]
	v_mfma_f32_16x16x32_bf16 v[132:135], v[168:171], v[186:189], v[132:135]
	v_mfma_f32_16x16x32_bf16 v[128:131], v[176:179], v[186:189], v[128:131]
	v_mfma_f32_16x16x32_bf16 v[116:119], v[168:171], v[194:197], v[116:119]
	v_mfma_f32_16x16x32_bf16 v[112:115], v[176:179], v[194:197], v[112:115]
	v_mfma_f32_16x16x32_bf16 v[100:103], v[168:171], v[202:205], v[100:103]
	v_mfma_f32_16x16x32_bf16 v[96:99], v[176:179], v[202:205], v[96:99]
	v_mfma_f32_16x16x32_bf16 v[84:87], v[168:171], v[210:213], v[84:87]
	v_mfma_f32_16x16x32_bf16 v[80:83], v[176:179], v[210:213], v[80:83]
	v_mfma_f32_16x16x32_bf16 v[132:135], v[172:175], v[190:193], v[132:135]
	v_mfma_f32_16x16x32_bf16 v[128:131], v[180:183], v[190:193], v[128:131]
	v_mfma_f32_16x16x32_bf16 v[116:119], v[172:175], v[198:201], v[116:119]
	v_mfma_f32_16x16x32_bf16 v[112:115], v[180:183], v[198:201], v[112:115]
	v_mfma_f32_16x16x32_bf16 v[100:103], v[172:175], v[206:209], v[100:103]
	v_mfma_f32_16x16x32_bf16 v[96:99], v[180:183], v[206:209], v[96:99]
	v_mfma_f32_16x16x32_bf16 v[84:87], v[172:175], v[214:217], v[84:87]
	v_mfma_f32_16x16x32_bf16 v[80:83], v[180:183], v[214:217], v[80:83]
	s_barrier
	s_mov_b32 m0, s44
	v_lshl_add_u64 v[58:59], v[218:219], 0, s[4:5]
	s_add_u32 s8, s8, 0x80080
	ds_read_b128 v[186:189], v46 offset:49152
	ds_read_b128 v[190:193], v46 offset:50176
	ds_read_b128 v[194:197], v46 offset:51200
	ds_read_b128 v[198:201], v46 offset:52224
	ds_read_b128 v[202:205], v46 offset:53248
	ds_read_b128 v[206:209], v46 offset:54272
	ds_read_b128 v[210:213], v46 offset:55296
	ds_read_b128 v[214:217], v46 offset:56320
	global_load_lds_dwordx4 v[58:59], off
	v_lshl_add_u64 v[58:59], v[220:221], 0, s[4:5]
	s_mov_b32 m0, s45
	s_addc_u32 s9, s9, 0
	global_load_lds_dwordx4 v[58:59], off
	v_lshl_add_u64 v[58:59], s[8:9], 0, v[150:151]
	s_mov_b32 m0, s46
	s_nop 0
	global_load_lds_dwordx4 v[58:59], off
	v_lshl_add_u64 v[58:59], s[8:9], 0, v[154:155]
	s_mov_b32 m0, s47
	s_nop 0
	global_load_lds_dwordx4 v[58:59], off
	v_lshl_add_u64 v[58:59], v[222:223], 0, s[4:5]
	s_mov_b32 m0, s17
	s_nop 0
	global_load_lds_dwordx4 v[58:59], off
	v_lshl_add_u64 v[58:59], v[224:225], 0, s[4:5]
	s_mov_b32 m0, s18
	s_nop 0
	global_load_lds_dwordx4 v[58:59], off
	s_waitcnt vmcnt(8)
	s_waitcnt lgkmcnt(0)
	s_barrier
	s_waitcnt lgkmcnt(0)
	v_mfma_f32_16x16x32_bf16 v[76:79], v[68:71], v[186:189], v[76:79]
	v_mfma_f32_16x16x32_bf16 v[72:75], v[160:163], v[186:189], v[72:75]
	v_mfma_f32_16x16x32_bf16 v[58:61], v[68:71], v[194:197], v[60:63]
	v_mfma_f32_16x16x32_bf16 v[54:57], v[160:163], v[194:197], v[54:57]
	v_mfma_f32_16x16x32_bf16 v[28:31], v[68:71], v[202:205], v[28:31]
	v_mfma_f32_16x16x32_bf16 v[24:27], v[160:163], v[202:205], v[24:27]
	v_mfma_f32_16x16x32_bf16 v[12:15], v[68:71], v[210:213], v[12:15]
	v_mfma_f32_16x16x32_bf16 v[8:11], v[160:163], v[210:213], v[8:11]
	v_mfma_f32_16x16x32_bf16 v[76:79], v[156:159], v[190:193], v[76:79]
	v_mfma_f32_16x16x32_bf16 v[72:75], v[164:167], v[190:193], v[72:75]
	v_mfma_f32_16x16x32_bf16 v[60:63], v[156:159], v[198:201], v[58:61]
	v_mfma_f32_16x16x32_bf16 v[56:59], v[164:167], v[198:201], v[54:57]
	v_mfma_f32_16x16x32_bf16 v[28:31], v[156:159], v[206:209], v[28:31]
	v_mfma_f32_16x16x32_bf16 v[24:27], v[164:167], v[206:209], v[24:27]
	v_mfma_f32_16x16x32_bf16 v[12:15], v[156:159], v[214:217], v[12:15]
	v_mfma_f32_16x16x32_bf16 v[8:11], v[164:167], v[214:217], v[8:11]
	v_mfma_f32_16x16x32_bf16 v[50:53], v[168:171], v[186:189], v[50:53]
	v_mfma_f32_16x16x32_bf16 v[68:71], v[172:175], v[190:193], v[50:53]
	v_mfma_f32_16x16x32_bf16 v[50:53], v[176:179], v[186:189], v[64:67]
	v_mfma_f32_16x16x32_bf16 v[36:39], v[168:171], v[194:197], v[36:39]
	v_mfma_f32_16x16x32_bf16 v[32:35], v[176:179], v[194:197], v[32:35]
	v_mfma_f32_16x16x32_bf16 v[20:23], v[168:171], v[202:205], v[20:23]
	v_mfma_f32_16x16x32_bf16 v[16:19], v[176:179], v[202:205], v[16:19]
	v_mfma_f32_16x16x32_bf16 v[4:7], v[168:171], v[210:213], v[4:7]
	v_mfma_f32_16x16x32_bf16 v[0:3], v[176:179], v[210:213], v[0:3]
	v_mfma_f32_16x16x32_bf16 v[64:67], v[180:183], v[190:193], v[50:53]
	v_mfma_f32_16x16x32_bf16 v[36:39], v[172:175], v[198:201], v[36:39]
	v_mfma_f32_16x16x32_bf16 v[32:35], v[180:183], v[198:201], v[32:35]
	v_mfma_f32_16x16x32_bf16 v[20:23], v[172:175], v[206:209], v[20:23]
	v_mfma_f32_16x16x32_bf16 v[16:19], v[180:183], v[206:209], v[16:19]
	v_mfma_f32_16x16x32_bf16 v[4:7], v[172:175], v[214:217], v[4:7]
	v_mfma_f32_16x16x32_bf16 v[0:3], v[180:183], v[214:217], v[0:3]
	s_barrier
	s_add_i32 s21, s21, 2
	s_add_u32 s6, s6, 0x100
	s_addc_u32 s7, s7, 0
	s_cmp_lt_u32 s21, 30
	s_cbranch_scc1 .LBB0_338
	s_setprio 0
	s_andn2_b64 vcc, exec, s[38:39]
	s_cbranch_vccnz .LBB0_341
	s_barrier

.LBB0_654:
	s_add_i32 s56, s56, 1
	s_lshl_b32 s2, s56, 5
	s_add_i32 s2, s2, s34
	s_cmp_lt_i32 s2, 32
	s_mov_b32 s20, s6
	s_cselect_b64 s[26:27], -1, 0
	s_ashr_i32 s6, s2, 2
	s_ashr_i32 s7, s6, 31
	s_lshl_b64 s[2:3], s[6:7], 20
	s_mov_b64 s[0:1], s[8:9]
	s_add_u32 s8, s35, s2
	s_addc_u32 s9, s36, s3
	s_and_b64 s[2:3], s[26:27], exec
	v_mov_b32_e32 v0, 0
	s_cselect_b32 s7, s9, s1
	s_cselect_b32 s57, s8, s0
	s_mov_b32 s58, -2
	s_mov_b64 s[2:3], 0x100
	s_waitcnt lgkmcnt(0)
	v_mov_b32_e32 v1, v0
	v_mov_b32_e32 v2, v0
	v_mov_b32_e32 v3, v0
	v_mov_b32_e32 v4, v0
	v_mov_b32_e32 v5, v0
	v_mov_b32_e32 v6, v0
	v_mov_b32_e32 v7, v0
	v_mov_b32_e32 v16, v0
	v_mov_b32_e32 v17, v0
	v_mov_b32_e32 v18, v0
	v_mov_b32_e32 v19, v0
	v_mov_b32_e32 v20, v0
	v_mov_b32_e32 v21, v0
	v_mov_b32_e32 v22, v0
	v_mov_b32_e32 v23, v0
	v_mov_b32_e32 v32, v0
	v_mov_b32_e32 v33, v0
	v_mov_b32_e32 v34, v0
	v_mov_b32_e32 v35, v0
	v_mov_b32_e32 v36, v0
	v_mov_b32_e32 v37, v0
	v_mov_b32_e32 v38, v0
	v_mov_b32_e32 v39, v0
	v_mov_b32_e32 v48, v0
	v_mov_b32_e32 v49, v0
	v_mov_b32_e32 v50, v0
	v_mov_b32_e32 v51, v0
	v_mov_b32_e32 v52, v0
	v_mov_b32_e32 v53, v0
	v_mov_b32_e32 v54, v0
	v_mov_b32_e32 v55, v0
	v_mov_b32_e32 v8, v0
	v_mov_b32_e32 v9, v0
	v_mov_b32_e32 v10, v0
	v_mov_b32_e32 v11, v0
	v_mov_b32_e32 v12, v0
	v_mov_b32_e32 v13, v0
	v_mov_b32_e32 v14, v0
	v_mov_b32_e32 v15, v0
	v_mov_b32_e32 v24, v0
	v_mov_b32_e32 v25, v0
	v_mov_b32_e32 v26, v0
	v_mov_b32_e32 v27, v0
	v_mov_b32_e32 v28, v0
	v_mov_b32_e32 v29, v0
	v_mov_b32_e32 v30, v0
	v_mov_b32_e32 v31, v0
	v_mov_b32_e32 v40, v0
	v_mov_b32_e32 v41, v0
	v_mov_b32_e32 v42, v0
	v_mov_b32_e32 v43, v0
	v_mov_b32_e32 v44, v0
	v_mov_b32_e32 v45, v0
	v_mov_b32_e32 v46, v0
	v_mov_b32_e32 v47, v0
	v_mov_b32_e32 v56, v0
	v_mov_b32_e32 v57, v0
	v_mov_b32_e32 v58, v0
	v_mov_b32_e32 v59, v0
	v_mov_b32_e32 v60, v0
	v_mov_b32_e32 v61, v0
	v_mov_b32_e32 v62, v0
	v_mov_b32_e32 v63, v0
	v_mov_b32_e32 v64, v0
	v_mov_b32_e32 v65, v0
	v_mov_b32_e32 v66, v0
	v_mov_b32_e32 v67, v0
	v_mov_b32_e32 v68, v0
	v_mov_b32_e32 v69, v0
	v_mov_b32_e32 v70, v0
	v_mov_b32_e32 v71, v0
	v_mov_b32_e32 v80, v0
	v_mov_b32_e32 v81, v0
	v_mov_b32_e32 v82, v0
	v_mov_b32_e32 v83, v0
	v_mov_b32_e32 v84, v0
	v_mov_b32_e32 v85, v0
	v_mov_b32_e32 v86, v0
	v_mov_b32_e32 v87, v0
	v_mov_b32_e32 v96, v0
	v_mov_b32_e32 v97, v0
	v_mov_b32_e32 v98, v0
	v_mov_b32_e32 v99, v0
	v_mov_b32_e32 v100, v0
	v_mov_b32_e32 v101, v0
	v_mov_b32_e32 v102, v0
	v_mov_b32_e32 v103, v0
	v_mov_b32_e32 v112, v0
	v_mov_b32_e32 v113, v0
	v_mov_b32_e32 v114, v0
	v_mov_b32_e32 v115, v0
	v_mov_b32_e32 v116, v0
	v_mov_b32_e32 v117, v0
	v_mov_b32_e32 v118, v0
	v_mov_b32_e32 v119, v0
	v_mov_b32_e32 v72, v0
	v_mov_b32_e32 v73, v0
	v_mov_b32_e32 v74, v0
	v_mov_b32_e32 v75, v0
	v_mov_b32_e32 v76, v0
	v_mov_b32_e32 v77, v0
	v_mov_b32_e32 v78, v0
	v_mov_b32_e32 v79, v0
	v_mov_b32_e32 v88, v0
	v_mov_b32_e32 v89, v0
	v_mov_b32_e32 v90, v0
	v_mov_b32_e32 v91, v0
	v_mov_b32_e32 v92, v0
	v_mov_b32_e32 v93, v0
	v_mov_b32_e32 v94, v0
	v_mov_b32_e32 v95, v0
	v_mov_b32_e32 v104, v0
	v_mov_b32_e32 v105, v0
	v_mov_b32_e32 v106, v0
	v_mov_b32_e32 v107, v0
	v_mov_b32_e32 v108, v0
	v_mov_b32_e32 v109, v0
	v_mov_b32_e32 v110, v0
	v_mov_b32_e32 v111, v0
	v_mov_b32_e32 v124, v0
	v_mov_b32_e32 v125, v0
	v_mov_b32_e32 v126, v0
	v_mov_b32_e32 v127, v0
	v_mov_b32_e32 v128, v0
	v_mov_b32_e32 v129, v0
	v_mov_b32_e32 v130, v0
	v_mov_b32_e32 v131, v0
	s_lshr_b32 s101, s88, 2
	s_cmp_lg_u32 s101, 1
	s_cbranch_scc1 .Lprio_skip4
	s_setprio 1
.Lprio_skip4:
.LBB0_655:
	ds_read_b128 v[120:123], v230
	ds_read_b128 v[132:135], v230 offset:1024
	ds_read_b128 v[136:139], v230 offset:2048
	ds_read_b128 v[140:143], v230 offset:3072
	ds_read_b128 v[144:147], v231
	ds_read_b128 v[148:151], v231 offset:1024
	ds_read_b128 v[152:155], v231 offset:2048
	ds_read_b128 v[156:159], v231 offset:3072
	s_add_u32 s28, s0, s2
	s_addc_u32 s29, s1, s3
	s_cmpk_eq_i32 s2, 0x1000
	s_cselect_b32 s30, 0, s2
	s_cselect_b32 s31, 0, s3
	s_cselect_b32 s28, s57, s28
	s_cselect_b32 s29, s7, s29
	s_add_u32 s30, s10, s30
	s_addc_u32 s31, s11, s31
	s_add_u32 s98, s2, s86
	s_addc_u32 s99, s3, s87
	s_add_i32 m0, s85, 0x8000
	v_lshl_add_u64 v[204:205], v[192:193], 0, s[98:99]
	ds_read_b128 v[160:163], v232
	ds_read_b128 v[164:167], v232 offset:1024
	ds_read_b128 v[168:171], v232 offset:2048
	ds_read_b128 v[172:175], v232 offset:3072
	ds_read_b128 v[176:179], v232 offset:4096
	ds_read_b128 v[180:183], v232 offset:5120
	ds_read_b128 v[196:199], v232 offset:6144
	ds_read_b128 v[200:203], v232 offset:7168
	global_load_lds_dwordx4 v[204:205], off
	s_add_u32 s98, s98, 0x20000
	s_addc_u32 s99, s99, 0
	s_add_i32 m0, s85, 0x9000
	v_lshl_add_u64 v[204:205], v[192:193], 0, s[98:99]
	global_load_lds_dwordx4 v[204:205], off
	s_add_u32 s98, s98, 0x20000
	s_addc_u32 s99, s99, 0
	s_add_i32 m0, s85, 0xa000
	v_lshl_add_u64 v[204:205], v[192:193], 0, s[98:99]
	global_load_lds_dwordx4 v[204:205], off
	s_add_u32 s98, s98, 0x20000
	s_addc_u32 s99, s99, 0
	s_add_i32 m0, s85, 0xb000
	v_lshl_add_u64 v[204:205], v[192:193], 0, s[98:99]
	global_load_lds_dwordx4 v[204:205], off
	s_waitcnt vmcnt(8)
	s_waitcnt lgkmcnt(0)
	s_barrier
	s_waitcnt lgkmcnt(0)
	v_mfma_f32_16x16x32_bf16 v[128:131], v[120:123], v[160:163], v[128:131]
	v_mfma_f32_16x16x32_bf16 v[124:127], v[136:139], v[160:163], v[124:127]
	v_mfma_f32_16x16x32_bf16 v[108:111], v[120:123], v[168:171], v[108:111]
	v_mfma_f32_16x16x32_bf16 v[104:107], v[136:139], v[168:171], v[104:107]
	v_mfma_f32_16x16x32_bf16 v[92:95], v[120:123], v[176:179], v[92:95]
	v_mfma_f32_16x16x32_bf16 v[88:91], v[136:139], v[176:179], v[88:91]
	v_mfma_f32_16x16x32_bf16 v[76:79], v[120:123], v[196:199], v[76:79]
	v_mfma_f32_16x16x32_bf16 v[72:75], v[136:139], v[196:199], v[72:75]
	v_mfma_f32_16x16x32_bf16 v[128:131], v[132:135], v[164:167], v[128:131]
	v_mfma_f32_16x16x32_bf16 v[124:127], v[140:143], v[164:167], v[124:127]
	v_mfma_f32_16x16x32_bf16 v[108:111], v[132:135], v[172:175], v[108:111]
	v_mfma_f32_16x16x32_bf16 v[104:107], v[140:143], v[172:175], v[104:107]
	v_mfma_f32_16x16x32_bf16 v[92:95], v[132:135], v[180:183], v[92:95]
	v_mfma_f32_16x16x32_bf16 v[88:91], v[140:143], v[180:183], v[88:91]
	v_mfma_f32_16x16x32_bf16 v[76:79], v[132:135], v[200:203], v[76:79]
	v_mfma_f32_16x16x32_bf16 v[72:75], v[140:143], v[200:203], v[72:75]
	v_mfma_f32_16x16x32_bf16 v[116:119], v[144:147], v[160:163], v[116:119]
	v_mfma_f32_16x16x32_bf16 v[112:115], v[152:155], v[160:163], v[112:115]
	v_mfma_f32_16x16x32_bf16 v[100:103], v[144:147], v[168:171], v[100:103]
	v_mfma_f32_16x16x32_bf16 v[96:99], v[152:155], v[168:171], v[96:99]
	v_mfma_f32_16x16x32_bf16 v[84:87], v[144:147], v[176:179], v[84:87]
	v_mfma_f32_16x16x32_bf16 v[80:83], v[152:155], v[176:179], v[80:83]
	v_mfma_f32_16x16x32_bf16 v[68:71], v[144:147], v[196:199], v[68:71]
	v_mfma_f32_16x16x32_bf16 v[64:67], v[152:155], v[196:199], v[64:67]
	v_mfma_f32_16x16x32_bf16 v[116:119], v[148:151], v[164:167], v[116:119]
	v_mfma_f32_16x16x32_bf16 v[112:115], v[156:159], v[164:167], v[112:115]
	v_mfma_f32_16x16x32_bf16 v[100:103], v[148:151], v[172:175], v[100:103]
	v_mfma_f32_16x16x32_bf16 v[96:99], v[156:159], v[172:175], v[96:99]
	v_mfma_f32_16x16x32_bf16 v[84:87], v[148:151], v[180:183], v[84:87]
	v_mfma_f32_16x16x32_bf16 v[80:83], v[156:159], v[180:183], v[80:83]
	v_mfma_f32_16x16x32_bf16 v[68:71], v[148:151], v[200:203], v[68:71]
	v_mfma_f32_16x16x32_bf16 v[64:67], v[156:159], v[200:203], v[64:67]
	s_barrier
	s_mov_b32 m0, s50
	v_lshl_add_u64 v[204:205], s[28:29], 0, v[188:189]
	s_add_u32 s60, s28, 0x80000
	ds_read_b128 v[160:163], v232 offset:16384
	ds_read_b128 v[164:167], v232 offset:17408
	ds_read_b128 v[168:171], v232 offset:18432
	ds_read_b128 v[172:175], v232 offset:19456
	ds_read_b128 v[176:179], v232 offset:20480
	ds_read_b128 v[180:183], v232 offset:21504
	ds_read_b128 v[196:199], v232 offset:22528
	ds_read_b128 v[200:203], v232 offset:23552
	global_load_lds_dwordx4 v[204:205], off
	v_lshl_add_u64 v[206:207], s[28:29], 0, v[184:185]
	s_mov_b32 m0, s51
	s_addc_u32 s61, s29, 0
	global_load_lds_dwordx4 v[206:207], off
	v_lshl_add_u64 v[208:209], s[60:61], 0, v[188:189]
	s_mov_b32 m0, s52
	global_load_lds_dwordx4 v[208:209], off
	v_lshl_add_u64 v[208:209], s[60:61], 0, v[184:185]
	s_mov_b32 m0, s53
	s_nop 0
	global_load_lds_dwordx4 v[208:209], off
	s_waitcnt vmcnt(8)
	s_waitcnt lgkmcnt(0)
	s_barrier
	s_waitcnt lgkmcnt(0)
	v_mfma_f32_16x16x32_bf16 v[60:63], v[120:123], v[160:163], v[60:63]
	v_mfma_f32_16x16x32_bf16 v[56:59], v[136:139], v[160:163], v[56:59]
	v_mfma_f32_16x16x32_bf16 v[44:47], v[120:123], v[168:171], v[44:47]
	v_mfma_f32_16x16x32_bf16 v[40:43], v[136:139], v[168:171], v[40:43]
	v_mfma_f32_16x16x32_bf16 v[28:31], v[120:123], v[176:179], v[28:31]
	v_mfma_f32_16x16x32_bf16 v[24:27], v[136:139], v[176:179], v[24:27]
	v_mfma_f32_16x16x32_bf16 v[12:15], v[120:123], v[196:199], v[12:15]
	v_mfma_f32_16x16x32_bf16 v[8:11], v[136:139], v[196:199], v[8:11]
	v_mfma_f32_16x16x32_bf16 v[60:63], v[132:135], v[164:167], v[60:63]
	v_mfma_f32_16x16x32_bf16 v[56:59], v[140:143], v[164:167], v[56:59]
	v_mfma_f32_16x16x32_bf16 v[44:47], v[132:135], v[172:175], v[44:47]
	v_mfma_f32_16x16x32_bf16 v[40:43], v[140:143], v[172:175], v[40:43]
	v_mfma_f32_16x16x32_bf16 v[28:31], v[132:135], v[180:183], v[28:31]
	v_mfma_f32_16x16x32_bf16 v[24:27], v[140:143], v[180:183], v[24:27]
	v_mfma_f32_16x16x32_bf16 v[12:15], v[132:135], v[200:203], v[12:15]
	v_mfma_f32_16x16x32_bf16 v[8:11], v[140:143], v[200:203], v[8:11]
	v_mfma_f32_16x16x32_bf16 v[52:55], v[144:147], v[160:163], v[52:55]
	v_mfma_f32_16x16x32_bf16 v[48:51], v[152:155], v[160:163], v[48:51]
	v_mfma_f32_16x16x32_bf16 v[36:39], v[144:147], v[168:171], v[36:39]
	v_mfma_f32_16x16x32_bf16 v[32:35], v[152:155], v[168:171], v[32:35]
	v_mfma_f32_16x16x32_bf16 v[20:23], v[144:147], v[176:179], v[20:23]
	v_mfma_f32_16x16x32_bf16 v[16:19], v[152:155], v[176:179], v[16:19]
	v_mfma_f32_16x16x32_bf16 v[4:7], v[144:147], v[196:199], v[4:7]
	v_mfma_f32_16x16x32_bf16 v[0:3], v[152:155], v[196:199], v[0:3]
	v_mfma_f32_16x16x32_bf16 v[52:55], v[148:151], v[164:167], v[52:55]
	v_mfma_f32_16x16x32_bf16 v[48:51], v[156:159], v[164:167], v[48:51]
	v_mfma_f32_16x16x32_bf16 v[36:39], v[148:151], v[172:175], v[36:39]
	v_mfma_f32_16x16x32_bf16 v[32:35], v[156:159], v[172:175], v[32:35]
	v_mfma_f32_16x16x32_bf16 v[20:23], v[148:151], v[180:183], v[20:23]
	v_mfma_f32_16x16x32_bf16 v[16:19], v[156:159], v[180:183], v[16:19]
	v_mfma_f32_16x16x32_bf16 v[4:7], v[148:151], v[200:203], v[4:7]
	v_mfma_f32_16x16x32_bf16 v[0:3], v[156:159], v[200:203], v[0:3]
	s_waitcnt vmcnt(4)
	s_barrier
	ds_read_b128 v[120:123], v234
	ds_read_b128 v[132:135], v234 offset:1024
	ds_read_b128 v[136:139], v234 offset:2048
	ds_read_b128 v[140:143], v234 offset:3072
	ds_read_b128 v[144:147], v235
	ds_read_b128 v[148:151], v235 offset:1024
	ds_read_b128 v[152:155], v235 offset:2048
	ds_read_b128 v[156:159], v235 offset:3072
	s_add_u32 s98, s30, s96
	s_addc_u32 s99, s31, s97
	s_add_i32 m0, s85, 0
	v_lshl_add_u64 v[212:213], s[98:99], 0, v[190:191]
	ds_read_b128 v[160:163], v232 offset:32768
	ds_read_b128 v[164:167], v232 offset:33792
	ds_read_b128 v[168:171], v232 offset:34816
	ds_read_b128 v[172:175], v232 offset:35840
	ds_read_b128 v[176:179], v232 offset:36864
	ds_read_b128 v[180:183], v232 offset:37888
	ds_read_b128 v[196:199], v232 offset:38912
	ds_read_b128 v[200:203], v232 offset:39936
	global_load_lds_dwordx4 v[212:213], off
	s_add_u32 s98, s98, 0x20000
	s_addc_u32 s99, s99, 0
	s_add_i32 m0, s85, 0x1000
	v_lshl_add_u64 v[212:213], s[98:99], 0, v[190:191]
	global_load_lds_dwordx4 v[212:213], off
	s_add_u32 s98, s98, 0x20000
	s_addc_u32 s99, s99, 0
	s_add_i32 m0, s85, 0x2000
	v_lshl_add_u64 v[212:213], s[98:99], 0, v[190:191]
	global_load_lds_dwordx4 v[212:213], off
	s_add_u32 s98, s98, 0x20000
	s_addc_u32 s99, s99, 0
	s_add_i32 m0, s85, 0x3000
	v_lshl_add_u64 v[212:213], s[98:99], 0, v[190:191]
	global_load_lds_dwordx4 v[212:213], off
	s_waitcnt vmcnt(8)
	s_waitcnt lgkmcnt(0)
	s_barrier
	s_waitcnt lgkmcnt(0)
	v_mfma_f32_16x16x32_bf16 v[128:131], v[120:123], v[160:163], v[128:131]
	v_mfma_f32_16x16x32_bf16 v[124:127], v[136:139], v[160:163], v[124:127]
	v_mfma_f32_16x16x32_bf16 v[108:111], v[120:123], v[168:171], v[108:111]
	v_mfma_f32_16x16x32_bf16 v[104:107], v[136:139], v[168:171], v[104:107]
	v_mfma_f32_16x16x32_bf16 v[92:95], v[120:123], v[176:179], v[92:95]
	v_mfma_f32_16x16x32_bf16 v[88:91], v[136:139], v[176:179], v[88:91]
	v_mfma_f32_16x16x32_bf16 v[76:79], v[120:123], v[196:199], v[76:79]
	v_mfma_f32_16x16x32_bf16 v[72:75], v[136:139], v[196:199], v[72:75]
	v_mfma_f32_16x16x32_bf16 v[128:131], v[132:135], v[164:167], v[128:131]
	v_mfma_f32_16x16x32_bf16 v[124:127], v[140:143], v[164:167], v[124:127]
	v_mfma_f32_16x16x32_bf16 v[108:111], v[132:135], v[172:175], v[108:111]
	v_mfma_f32_16x16x32_bf16 v[104:107], v[140:143], v[172:175], v[104:107]
	v_mfma_f32_16x16x32_bf16 v[92:95], v[132:135], v[180:183], v[92:95]
	v_mfma_f32_16x16x32_bf16 v[88:91], v[140:143], v[180:183], v[88:91]
	v_mfma_f32_16x16x32_bf16 v[76:79], v[132:135], v[200:203], v[76:79]
	v_mfma_f32_16x16x32_bf16 v[72:75], v[140:143], v[200:203], v[72:75]
	v_mfma_f32_16x16x32_bf16 v[116:119], v[144:147], v[160:163], v[116:119]
	v_mfma_f32_16x16x32_bf16 v[112:115], v[152:155], v[160:163], v[112:115]
	v_mfma_f32_16x16x32_bf16 v[100:103], v[144:147], v[168:171], v[100:103]
	v_mfma_f32_16x16x32_bf16 v[96:99], v[152:155], v[168:171], v[96:99]
	v_mfma_f32_16x16x32_bf16 v[84:87], v[144:147], v[176:179], v[84:87]
	v_mfma_f32_16x16x32_bf16 v[80:83], v[152:155], v[176:179], v[80:83]
	v_mfma_f32_16x16x32_bf16 v[68:71], v[144:147], v[196:199], v[68:71]
	v_mfma_f32_16x16x32_bf16 v[64:67], v[152:155], v[196:199], v[64:67]
	v_mfma_f32_16x16x32_bf16 v[116:119], v[148:151], v[164:167], v[116:119]
	v_mfma_f32_16x16x32_bf16 v[112:115], v[156:159], v[164:167], v[112:115]
	v_mfma_f32_16x16x32_bf16 v[100:103], v[148:151], v[172:175], v[100:103]
	v_mfma_f32_16x16x32_bf16 v[96:99], v[156:159], v[172:175], v[96:99]
	v_mfma_f32_16x16x32_bf16 v[84:87], v[148:151], v[180:183], v[84:87]
	v_mfma_f32_16x16x32_bf16 v[80:83], v[156:159], v[180:183], v[80:83]
	v_mfma_f32_16x16x32_bf16 v[68:71], v[148:151], v[200:203], v[68:71]
	v_mfma_f32_16x16x32_bf16 v[64:67], v[156:159], v[200:203], v[64:67]
	s_barrier
	s_mov_b32 m0, s55
	v_lshl_add_u64 v[204:205], v[204:205], 0, s[18:19]
	ds_read_b128 v[160:163], v232 offset:49152
	ds_read_b128 v[164:167], v232 offset:50176
	ds_read_b128 v[168:171], v232 offset:51200
	ds_read_b128 v[172:175], v232 offset:52224
	ds_read_b128 v[176:179], v232 offset:53248
	ds_read_b128 v[180:183], v232 offset:54272
	ds_read_b128 v[196:199], v232 offset:55296
	ds_read_b128 v[200:203], v232 offset:56320
	global_load_lds_dwordx4 v[204:205], off
	s_add_i32 m0, s55, 0x2000
	s_add_u32 s28, s28, 0x80080
	v_lshl_add_u64 v[204:205], v[206:207], 0, s[18:19]
	s_addc_u32 s29, s29, 0
	s_add_i32 s30, s54, s37
	global_load_lds_dwordx4 v[204:205], off
	v_lshl_add_u64 v[204:205], s[28:29], 0, v[188:189]
	s_mov_b32 m0, s30
	s_nop 0
	global_load_lds_dwordx4 v[204:205], off
	v_lshl_add_u64 v[204:205], s[28:29], 0, v[184:185]
	s_add_i32 m0, s30, 0x2000
	s_nop 0
	global_load_lds_dwordx4 v[204:205], off
	s_waitcnt vmcnt(8)
	s_waitcnt lgkmcnt(0)
	s_barrier
	s_waitcnt lgkmcnt(0)
	v_mfma_f32_16x16x32_bf16 v[60:63], v[120:123], v[160:163], v[60:63]
	v_mfma_f32_16x16x32_bf16 v[56:59], v[136:139], v[160:163], v[56:59]
	v_mfma_f32_16x16x32_bf16 v[44:47], v[120:123], v[168:171], v[44:47]
	v_mfma_f32_16x16x32_bf16 v[40:43], v[136:139], v[168:171], v[40:43]
	v_mfma_f32_16x16x32_bf16 v[28:31], v[120:123], v[176:179], v[28:31]
	v_mfma_f32_16x16x32_bf16 v[24:27], v[136:139], v[176:179], v[24:27]
	v_mfma_f32_16x16x32_bf16 v[12:15], v[120:123], v[196:199], v[12:15]
	v_mfma_f32_16x16x32_bf16 v[8:11], v[136:139], v[196:199], v[8:11]
	v_mfma_f32_16x16x32_bf16 v[60:63], v[132:135], v[164:167], v[60:63]
	v_mfma_f32_16x16x32_bf16 v[56:59], v[140:143], v[164:167], v[56:59]
	v_mfma_f32_16x16x32_bf16 v[44:47], v[132:135], v[172:175], v[44:47]
	v_mfma_f32_16x16x32_bf16 v[40:43], v[140:143], v[172:175], v[40:43]
	v_mfma_f32_16x16x32_bf16 v[28:31], v[132:135], v[180:183], v[28:31]
	v_mfma_f32_16x16x32_bf16 v[24:27], v[140:143], v[180:183], v[24:27]
	v_mfma_f32_16x16x32_bf16 v[12:15], v[132:135], v[200:203], v[12:15]
	v_mfma_f32_16x16x32_bf16 v[8:11], v[140:143], v[200:203], v[8:11]
	v_mfma_f32_16x16x32_bf16 v[52:55], v[144:147], v[160:163], v[52:55]
	v_mfma_f32_16x16x32_bf16 v[48:51], v[152:155], v[160:163], v[48:51]
	v_mfma_f32_16x16x32_bf16 v[36:39], v[144:147], v[168:171], v[36:39]
	v_mfma_f32_16x16x32_bf16 v[32:35], v[152:155], v[168:171], v[32:35]
	v_mfma_f32_16x16x32_bf16 v[20:23], v[144:147], v[176:179], v[20:23]
	v_mfma_f32_16x16x32_bf16 v[16:19], v[152:155], v[176:179], v[16:19]
	v_mfma_f32_16x16x32_bf16 v[4:7], v[144:147], v[196:199], v[4:7]
	v_mfma_f32_16x16x32_bf16 v[0:3], v[152:155], v[196:199], v[0:3]
	v_mfma_f32_16x16x32_bf16 v[52:55], v[148:151], v[164:167], v[52:55]
	v_mfma_f32_16x16x32_bf16 v[48:51], v[156:159], v[164:167], v[48:51]
	v_mfma_f32_16x16x32_bf16 v[36:39], v[148:151], v[172:175], v[36:39]
	v_mfma_f32_16x16x32_bf16 v[32:35], v[156:159], v[172:175], v[32:35]
	v_mfma_f32_16x16x32_bf16 v[20:23], v[148:151], v[180:183], v[20:23]
	v_mfma_f32_16x16x32_bf16 v[16:19], v[156:159], v[180:183], v[16:19]
	v_mfma_f32_16x16x32_bf16 v[4:7], v[148:151], v[200:203], v[4:7]
	v_mfma_f32_16x16x32_bf16 v[0:3], v[156:159], v[200:203], v[0:3]
	s_waitcnt vmcnt(4)
	s_barrier
	s_add_i32 s58, s58, 2
	s_add_u32 s2, s2, 0x100
	s_addc_u32 s3, s3, 0
	s_cmp_gt_u32 s58, 29
	s_cbranch_scc0 .LBB0_655
	s_setprio 0
	s_and_b64 vcc, exec, s[22:23]
	s_cbranch_vccz .LBB0_658
	s_barrier

.LBB0_784:
	s_add_i32 s53, s53, 1
	s_mov_b64 s[38:39], s[10:11]
	s_mov_b32 s68, s4
	s_mov_b32 s10, s4
	s_lshl_b32 s4, s53, 5
	s_add_i32 s4, s4, s19
	s_cmp_lt_i32 s4, 32
	s_cselect_b64 s[34:35], -1, 0
	s_ashr_i32 s4, s4, 2
	s_mov_b64 s[36:37], s[8:9]
	s_and_b64 s[8:9], s[34:35], exec
	s_cselect_b32 s8, s42, s42
	s_cselect_b32 s10, s4, s10
	s_ashr_i32 s9, s8, 31
	s_lshl_b64 s[8:9], s[8:9], 20
	s_add_u32 s8, s43, s8
	s_addc_u32 s9, s44, s9
	s_and_b64 s[40:41], s[34:35], exec
	s_cselect_b32 s69, s9, s37
	s_cselect_b32 s70, s8, s36
	s_ashr_i32 s11, s10, 31
	s_lshl_b64 s[10:11], s[10:11], 20
	s_add_u32 s10, s45, s10
	s_addc_u32 s11, s46, s11
	s_and_b64 s[40:41], s[34:35], exec
	s_cselect_b32 s71, s11, s39
	s_cselect_b32 s72, s10, s38
	s_add_u32 s36, s36, 0x80080
	s_addc_u32 s37, s37, 0
	s_add_u32 s73, s38, 0x100
	s_addc_u32 s74, s39, 0
	s_mov_b32 s75, -2
	v_mov_b32_e32 v0, 0
	v_mov_b32_e32 v1, v137
	v_mov_b32_e32 v2, v137
	v_mov_b32_e32 v3, v137
	v_mov_b32_e32 v4, 0
	v_mov_b32_e32 v5, v137
	v_mov_b32_e32 v6, v137
	v_mov_b32_e32 v7, v137
	v_mov_b32_e32 v12, 0
	v_mov_b32_e32 v13, v137
	v_mov_b32_e32 v14, v137
	v_mov_b32_e32 v15, v137
	v_mov_b32_e32 v20, 0
	v_mov_b32_e32 v21, v137
	v_mov_b32_e32 v22, v137
	v_mov_b32_e32 v23, v137
	v_mov_b32_e32 v28, 0
	v_mov_b32_e32 v29, v137
	v_mov_b32_e32 v30, v137
	v_mov_b32_e32 v31, v137
	v_mov_b32_e32 v36, 0
	v_mov_b32_e32 v37, v137
	v_mov_b32_e32 v38, v137
	v_mov_b32_e32 v39, v137
	v_mov_b32_e32 v44, 0
	v_mov_b32_e32 v45, v137
	v_mov_b32_e32 v46, v137
	v_mov_b32_e32 v47, v137
	v_mov_b32_e32 v52, 0
	v_mov_b32_e32 v53, v137
	v_mov_b32_e32 v54, v137
	v_mov_b32_e32 v55, v137
	v_mov_b32_e32 v8, 0
	v_mov_b32_e32 v9, v137
	v_mov_b32_e32 v10, v137
	v_mov_b32_e32 v11, v137
	v_mov_b32_e32 v16, 0
	v_mov_b32_e32 v17, v137
	v_mov_b32_e32 v18, v137
	v_mov_b32_e32 v19, v137
	v_mov_b32_e32 v24, 0
	v_mov_b32_e32 v25, v137
	v_mov_b32_e32 v26, v137
	v_mov_b32_e32 v27, v137
	v_mov_b32_e32 v32, 0
	v_mov_b32_e32 v33, v137
	v_mov_b32_e32 v34, v137
	v_mov_b32_e32 v35, v137
	v_mov_b32_e32 v40, 0
	v_mov_b32_e32 v41, v137
	v_mov_b32_e32 v42, v137
	v_mov_b32_e32 v43, v137
	v_mov_b32_e32 v48, 0
	v_mov_b32_e32 v49, v137
	v_mov_b32_e32 v50, v137
	v_mov_b32_e32 v51, v137
	v_mov_b32_e32 v56, 0
	v_mov_b32_e32 v57, v137
	v_mov_b32_e32 v58, v137
	v_mov_b32_e32 v59, v137
	v_mov_b32_e32 v60, 0
	v_mov_b32_e32 v61, v137
	v_mov_b32_e32 v62, v137
	v_mov_b32_e32 v63, v137
	v_mov_b32_e32 v64, 0
	v_mov_b32_e32 v65, v137
	v_mov_b32_e32 v66, v137
	v_mov_b32_e32 v67, v137
	v_mov_b32_e32 v68, 0
	v_mov_b32_e32 v69, v137
	v_mov_b32_e32 v70, v137
	v_mov_b32_e32 v71, v137
	v_mov_b32_e32 v76, 0
	v_mov_b32_e32 v77, v137
	v_mov_b32_e32 v78, v137
	v_mov_b32_e32 v79, v137
	v_mov_b32_e32 v84, 0
	v_mov_b32_e32 v85, v137
	v_mov_b32_e32 v86, v137
	v_mov_b32_e32 v87, v137
	v_mov_b32_e32 v92, 0
	v_mov_b32_e32 v93, v137
	v_mov_b32_e32 v94, v137
	v_mov_b32_e32 v95, v137
	v_mov_b32_e32 v100, 0
	v_mov_b32_e32 v101, v137
	v_mov_b32_e32 v102, v137
	v_mov_b32_e32 v103, v137
	v_mov_b32_e32 v108, 0
	v_mov_b32_e32 v109, v137
	v_mov_b32_e32 v110, v137
	v_mov_b32_e32 v111, v137
	v_mov_b32_e32 v116, 0
	v_mov_b32_e32 v117, v137
	v_mov_b32_e32 v118, v137
	v_mov_b32_e32 v119, v137
	v_mov_b32_e32 v72, 0
	v_mov_b32_e32 v73, v137
	v_mov_b32_e32 v74, v137
	v_mov_b32_e32 v75, v137
	v_mov_b32_e32 v80, 0
	v_mov_b32_e32 v81, v137
	v_mov_b32_e32 v82, v137
	v_mov_b32_e32 v83, v137
	v_mov_b32_e32 v88, 0
	v_mov_b32_e32 v89, v137
	v_mov_b32_e32 v90, v137
	v_mov_b32_e32 v91, v137
	v_mov_b32_e32 v96, 0
	v_mov_b32_e32 v97, v137
	v_mov_b32_e32 v98, v137
	v_mov_b32_e32 v99, v137
	v_mov_b32_e32 v104, 0
	v_mov_b32_e32 v105, v137
	v_mov_b32_e32 v106, v137
	v_mov_b32_e32 v107, v137
	v_mov_b32_e32 v112, 0
	v_mov_b32_e32 v113, v137
	v_mov_b32_e32 v114, v137
	v_mov_b32_e32 v115, v137
	v_mov_b32_e32 v120, 0
	v_mov_b32_e32 v121, v137
	v_mov_b32_e32 v122, v137
	v_mov_b32_e32 v123, v137
	v_mov_b32_e32 v124, 0
	v_mov_b32_e32 v125, v137
	v_mov_b32_e32 v126, v137
	v_mov_b32_e32 v127, v137
	s_lshr_b32 s101, s88, 2
	s_cmp_lg_u32 s101, 1
	s_cbranch_scc1 .Lprio_skip5
	s_setprio 1
.Lprio_skip5:
.LBB0_785:
	ds_read_b128 v[140:143], v148
	ds_read_b128 v[154:157], v148 offset:1024
	ds_read_b128 v[158:161], v148 offset:2048
	ds_read_b128 v[162:165], v148 offset:3072
	ds_read_b128 v[166:169], v149
	ds_read_b128 v[170:173], v149 offset:1024
	ds_read_b128 v[174:177], v149 offset:2048
	ds_read_b128 v[178:181], v149 offset:3072
	s_add_u32 s38, s36, 0xfff80080
	s_addc_u32 s39, s37, -1
	s_cmp_eq_u32 s75, 28
	s_cselect_b32 s41, s69, s39
	s_cselect_b32 s40, s70, s38
	s_cselect_b32 s39, s71, s74
	s_cselect_b32 s38, s72, s73
	s_sub_u32 s98, s36, 0x80000
	s_subb_u32 s99, s37, 0
	s_add_i32 m0, s85, 0x8000
	ds_read_b128 v[182:185], v150
	ds_read_b128 v[186:189], v150 offset:1024
	ds_read_b128 v[190:193], v150 offset:2048
	ds_read_b128 v[194:197], v150 offset:3072
	ds_read_b128 v[198:201], v150 offset:4096
	ds_read_b128 v[202:205], v150 offset:5120
	ds_read_b128 v[206:209], v150 offset:6144
	ds_read_b128 v[210:213], v150 offset:7168
	global_load_lds_dwordx4 v222, s[98:99]
	s_add_u32 s98, s98, 0x20000
	s_addc_u32 s99, s99, 0
	s_add_i32 m0, s85, 0x9000
	s_nop 0
	global_load_lds_dwordx4 v222, s[98:99]
	s_add_u32 s98, s98, 0x20000
	s_addc_u32 s99, s99, 0
	s_add_i32 m0, s85, 0xa000
	s_nop 0
	global_load_lds_dwordx4 v222, s[98:99]
	s_add_u32 s98, s98, 0x20000
	s_addc_u32 s99, s99, 0
	s_add_i32 m0, s85, 0xb000
	s_nop 0
	global_load_lds_dwordx4 v222, s[98:99]
	s_waitcnt vmcnt(8)
	s_waitcnt lgkmcnt(0)
	s_barrier
	s_waitcnt lgkmcnt(0)
	v_mfma_f32_16x16x32_bf16 v[124:127], v[140:143], v[182:185], v[124:127]
	v_mfma_f32_16x16x32_bf16 v[120:123], v[158:161], v[182:185], v[120:123]
	v_mfma_f32_16x16x32_bf16 v[112:115], v[140:143], v[190:193], v[112:115]
	v_mfma_f32_16x16x32_bf16 v[104:107], v[158:161], v[190:193], v[104:107]
	v_mfma_f32_16x16x32_bf16 v[96:99], v[140:143], v[198:201], v[96:99]
	v_mfma_f32_16x16x32_bf16 v[88:91], v[158:161], v[198:201], v[88:91]
	v_mfma_f32_16x16x32_bf16 v[80:83], v[140:143], v[206:209], v[80:83]
	v_mfma_f32_16x16x32_bf16 v[72:75], v[158:161], v[206:209], v[72:75]
	v_mfma_f32_16x16x32_bf16 v[124:127], v[154:157], v[186:189], v[124:127]
	v_mfma_f32_16x16x32_bf16 v[120:123], v[162:165], v[186:189], v[120:123]
	v_mfma_f32_16x16x32_bf16 v[112:115], v[154:157], v[194:197], v[112:115]
	v_mfma_f32_16x16x32_bf16 v[104:107], v[162:165], v[194:197], v[104:107]
	v_mfma_f32_16x16x32_bf16 v[96:99], v[154:157], v[202:205], v[96:99]
	v_mfma_f32_16x16x32_bf16 v[88:91], v[162:165], v[202:205], v[88:91]
	v_mfma_f32_16x16x32_bf16 v[80:83], v[154:157], v[210:213], v[80:83]
	v_mfma_f32_16x16x32_bf16 v[72:75], v[162:165], v[210:213], v[72:75]
	v_mfma_f32_16x16x32_bf16 v[116:119], v[166:169], v[182:185], v[116:119]
	v_mfma_f32_16x16x32_bf16 v[108:111], v[174:177], v[182:185], v[108:111]
	v_mfma_f32_16x16x32_bf16 v[100:103], v[166:169], v[190:193], v[100:103]
	v_mfma_f32_16x16x32_bf16 v[92:95], v[174:177], v[190:193], v[92:95]
	v_mfma_f32_16x16x32_bf16 v[84:87], v[166:169], v[198:201], v[84:87]
	v_mfma_f32_16x16x32_bf16 v[76:79], v[174:177], v[198:201], v[76:79]
	v_mfma_f32_16x16x32_bf16 v[68:71], v[166:169], v[206:209], v[68:71]
	v_mfma_f32_16x16x32_bf16 v[64:67], v[174:177], v[206:209], v[64:67]
	v_mfma_f32_16x16x32_bf16 v[116:119], v[170:173], v[186:189], v[116:119]
	v_mfma_f32_16x16x32_bf16 v[108:111], v[178:181], v[186:189], v[108:111]
	v_mfma_f32_16x16x32_bf16 v[100:103], v[170:173], v[194:197], v[100:103]
	v_mfma_f32_16x16x32_bf16 v[92:95], v[178:181], v[194:197], v[92:95]
	v_mfma_f32_16x16x32_bf16 v[84:87], v[170:173], v[202:205], v[84:87]
	v_mfma_f32_16x16x32_bf16 v[76:79], v[178:181], v[202:205], v[76:79]
	v_mfma_f32_16x16x32_bf16 v[68:71], v[170:173], v[210:213], v[68:71]
	v_mfma_f32_16x16x32_bf16 v[64:67], v[178:181], v[210:213], v[64:67]
	s_barrier
	s_add_i32 s76, s59, s5
	v_lshl_add_u64 v[144:145], s[38:39], 0, v[130:131]
	s_mov_b32 m0, s76
	ds_read_b128 v[182:185], v150 offset:16384
	ds_read_b128 v[186:189], v150 offset:17408
	ds_read_b128 v[190:193], v150 offset:18432
	ds_read_b128 v[194:197], v150 offset:19456
	ds_read_b128 v[198:201], v150 offset:20480
	ds_read_b128 v[202:205], v150 offset:21504
	ds_read_b128 v[206:209], v150 offset:22528
	ds_read_b128 v[210:213], v150 offset:23552
	global_load_lds_dwordx4 v[144:145], off
	s_add_i32 m0, s76, 0x2000
	s_add_u32 s76, s38, 0x80000
	v_lshl_add_u64 v[214:215], s[38:39], 0, v[134:135]
	s_addc_u32 s77, s39, 0
	s_add_i32 s78, s60, s5
	global_load_lds_dwordx4 v[214:215], off
	v_lshl_add_u64 v[216:217], s[76:77], 0, v[130:131]
	s_mov_b32 m0, s78
	global_load_lds_dwordx4 v[216:217], off
	v_lshl_add_u64 v[216:217], s[76:77], 0, v[134:135]
	s_add_i32 m0, s78, 0x2000
	s_nop 0
	global_load_lds_dwordx4 v[216:217], off
	s_waitcnt vmcnt(8)
	s_waitcnt lgkmcnt(0)
	s_barrier
	s_waitcnt lgkmcnt(0)
	v_mfma_f32_16x16x32_bf16 v[60:63], v[140:143], v[182:185], v[60:63]
	v_mfma_f32_16x16x32_bf16 v[56:59], v[158:161], v[182:185], v[56:59]
	v_mfma_f32_16x16x32_bf16 v[48:51], v[140:143], v[190:193], v[48:51]
	v_mfma_f32_16x16x32_bf16 v[40:43], v[158:161], v[190:193], v[40:43]
	v_mfma_f32_16x16x32_bf16 v[32:35], v[140:143], v[198:201], v[32:35]
	v_mfma_f32_16x16x32_bf16 v[24:27], v[158:161], v[198:201], v[24:27]
	v_mfma_f32_16x16x32_bf16 v[16:19], v[140:143], v[206:209], v[16:19]
	v_mfma_f32_16x16x32_bf16 v[8:11], v[158:161], v[206:209], v[8:11]
	v_mfma_f32_16x16x32_bf16 v[60:63], v[154:157], v[186:189], v[60:63]
	v_mfma_f32_16x16x32_bf16 v[56:59], v[162:165], v[186:189], v[56:59]
	v_mfma_f32_16x16x32_bf16 v[48:51], v[154:157], v[194:197], v[48:51]
	v_mfma_f32_16x16x32_bf16 v[40:43], v[162:165], v[194:197], v[40:43]
	v_mfma_f32_16x16x32_bf16 v[32:35], v[154:157], v[202:205], v[32:35]
	v_mfma_f32_16x16x32_bf16 v[24:27], v[162:165], v[202:205], v[24:27]
	v_mfma_f32_16x16x32_bf16 v[16:19], v[154:157], v[210:213], v[16:19]
	v_mfma_f32_16x16x32_bf16 v[8:11], v[162:165], v[210:213], v[8:11]
	v_mfma_f32_16x16x32_bf16 v[52:55], v[166:169], v[182:185], v[52:55]
	v_mfma_f32_16x16x32_bf16 v[44:47], v[174:177], v[182:185], v[44:47]
	v_mfma_f32_16x16x32_bf16 v[36:39], v[166:169], v[190:193], v[36:39]
	v_mfma_f32_16x16x32_bf16 v[28:31], v[174:177], v[190:193], v[28:31]
	v_mfma_f32_16x16x32_bf16 v[20:23], v[166:169], v[198:201], v[20:23]
	v_mfma_f32_16x16x32_bf16 v[12:15], v[174:177], v[198:201], v[12:15]
	v_mfma_f32_16x16x32_bf16 v[4:7], v[166:169], v[206:209], v[4:7]
	v_mfma_f32_16x16x32_bf16 v[0:3], v[174:177], v[206:209], v[0:3]
	v_mfma_f32_16x16x32_bf16 v[52:55], v[170:173], v[186:189], v[52:55]
	v_mfma_f32_16x16x32_bf16 v[44:47], v[178:181], v[186:189], v[44:47]
	v_mfma_f32_16x16x32_bf16 v[36:39], v[170:173], v[194:197], v[36:39]
	v_mfma_f32_16x16x32_bf16 v[28:31], v[178:181], v[194:197], v[28:31]
	v_mfma_f32_16x16x32_bf16 v[20:23], v[170:173], v[202:205], v[20:23]
	v_mfma_f32_16x16x32_bf16 v[12:15], v[178:181], v[202:205], v[12:15]
	v_mfma_f32_16x16x32_bf16 v[4:7], v[170:173], v[210:213], v[4:7]
	v_mfma_f32_16x16x32_bf16 v[0:3], v[178:181], v[210:213], v[0:3]
	s_waitcnt vmcnt(4)
	s_barrier
	ds_read_b128 v[140:143], v151
	ds_read_b128 v[154:157], v151 offset:1024
	ds_read_b128 v[158:161], v151 offset:2048
	ds_read_b128 v[162:165], v151 offset:3072
	ds_read_b128 v[166:169], v152
	ds_read_b128 v[170:173], v152 offset:1024
	ds_read_b128 v[174:177], v152 offset:2048
	ds_read_b128 v[178:181], v152 offset:3072
	s_mov_b32 s98, s40
	s_mov_b32 s99, s41
	s_add_i32 m0, s85, 0
	ds_read_b128 v[182:185], v150 offset:32768
	ds_read_b128 v[186:189], v150 offset:33792
	ds_read_b128 v[190:193], v150 offset:34816
	ds_read_b128 v[194:197], v150 offset:35840
	ds_read_b128 v[198:201], v150 offset:36864
	ds_read_b128 v[202:205], v150 offset:37888
	ds_read_b128 v[206:209], v150 offset:38912
	ds_read_b128 v[210:213], v150 offset:39936
	global_load_lds_dwordx4 v222, s[98:99]
	s_add_u32 s98, s98, 0x20000
	s_addc_u32 s99, s99, 0
	s_add_i32 m0, s85, 0x1000
	s_nop 0
	global_load_lds_dwordx4 v222, s[98:99]
	s_add_u32 s98, s98, 0x20000
	s_addc_u32 s99, s99, 0
	s_add_i32 m0, s85, 0x2000
	s_nop 0
	global_load_lds_dwordx4 v222, s[98:99]
	s_add_u32 s98, s98, 0x20000
	s_addc_u32 s99, s99, 0
	s_add_i32 m0, s85, 0x3000
	s_nop 0
	global_load_lds_dwordx4 v222, s[98:99]
	s_waitcnt vmcnt(8)
	s_waitcnt lgkmcnt(0)
	s_barrier
	s_waitcnt lgkmcnt(0)
	v_mfma_f32_16x16x32_bf16 v[124:127], v[140:143], v[182:185], v[124:127]
	v_mfma_f32_16x16x32_bf16 v[120:123], v[158:161], v[182:185], v[120:123]
	v_mfma_f32_16x16x32_bf16 v[112:115], v[140:143], v[190:193], v[112:115]
	v_mfma_f32_16x16x32_bf16 v[104:107], v[158:161], v[190:193], v[104:107]
	v_mfma_f32_16x16x32_bf16 v[96:99], v[140:143], v[198:201], v[96:99]
	v_mfma_f32_16x16x32_bf16 v[88:91], v[158:161], v[198:201], v[88:91]
	v_mfma_f32_16x16x32_bf16 v[80:83], v[140:143], v[206:209], v[80:83]
	v_mfma_f32_16x16x32_bf16 v[72:75], v[158:161], v[206:209], v[72:75]
	v_mfma_f32_16x16x32_bf16 v[124:127], v[154:157], v[186:189], v[124:127]
	v_mfma_f32_16x16x32_bf16 v[120:123], v[162:165], v[186:189], v[120:123]
	v_mfma_f32_16x16x32_bf16 v[112:115], v[154:157], v[194:197], v[112:115]
	v_mfma_f32_16x16x32_bf16 v[104:107], v[162:165], v[194:197], v[104:107]
	v_mfma_f32_16x16x32_bf16 v[96:99], v[154:157], v[202:205], v[96:99]
	v_mfma_f32_16x16x32_bf16 v[88:91], v[162:165], v[202:205], v[88:91]
	v_mfma_f32_16x16x32_bf16 v[80:83], v[154:157], v[210:213], v[80:83]
	v_mfma_f32_16x16x32_bf16 v[72:75], v[162:165], v[210:213], v[72:75]
	v_mfma_f32_16x16x32_bf16 v[116:119], v[166:169], v[182:185], v[116:119]
	v_mfma_f32_16x16x32_bf16 v[108:111], v[174:177], v[182:185], v[108:111]
	v_mfma_f32_16x16x32_bf16 v[100:103], v[166:169], v[190:193], v[100:103]
	v_mfma_f32_16x16x32_bf16 v[92:95], v[174:177], v[190:193], v[92:95]
	v_mfma_f32_16x16x32_bf16 v[84:87], v[166:169], v[198:201], v[84:87]
	v_mfma_f32_16x16x32_bf16 v[76:79], v[174:177], v[198:201], v[76:79]
	v_mfma_f32_16x16x32_bf16 v[68:71], v[166:169], v[206:209], v[68:71]
	v_mfma_f32_16x16x32_bf16 v[64:67], v[174:177], v[206:209], v[64:67]
	v_mfma_f32_16x16x32_bf16 v[116:119], v[170:173], v[186:189], v[116:119]
	v_mfma_f32_16x16x32_bf16 v[108:111], v[178:181], v[186:189], v[108:111]
	v_mfma_f32_16x16x32_bf16 v[100:103], v[170:173], v[194:197], v[100:103]
	v_mfma_f32_16x16x32_bf16 v[92:95], v[178:181], v[194:197], v[92:95]
	v_mfma_f32_16x16x32_bf16 v[84:87], v[170:173], v[202:205], v[84:87]
	v_mfma_f32_16x16x32_bf16 v[76:79], v[178:181], v[202:205], v[76:79]
	v_mfma_f32_16x16x32_bf16 v[68:71], v[170:173], v[210:213], v[68:71]
	v_mfma_f32_16x16x32_bf16 v[64:67], v[178:181], v[210:213], v[64:67]
	s_barrier
	s_add_i32 s40, s61, s5
	v_lshl_add_u64 v[144:145], v[144:145], 0, s[12:13]
	s_mov_b32 m0, s40
	ds_read_b128 v[182:185], v150 offset:49152
	ds_read_b128 v[186:189], v150 offset:50176
	ds_read_b128 v[190:193], v150 offset:51200
	ds_read_b128 v[194:197], v150 offset:52224
	ds_read_b128 v[198:201], v150 offset:53248
	ds_read_b128 v[202:205], v150 offset:54272
	ds_read_b128 v[206:209], v150 offset:55296
	ds_read_b128 v[210:213], v150 offset:56320
	global_load_lds_dwordx4 v[144:145], off
	s_add_i32 m0, s40, 0x2000
	s_add_u32 s38, s38, 0x80080
	v_lshl_add_u64 v[144:145], v[214:215], 0, s[12:13]
	s_addc_u32 s39, s39, 0
	s_add_i32 s40, s62, s5
	global_load_lds_dwordx4 v[144:145], off
	v_lshl_add_u64 v[144:145], s[38:39], 0, v[130:131]
	s_mov_b32 m0, s40
	s_nop 0
	global_load_lds_dwordx4 v[144:145], off
	v_lshl_add_u64 v[144:145], s[38:39], 0, v[134:135]
	s_add_i32 m0, s40, 0x2000
	s_nop 0
	global_load_lds_dwordx4 v[144:145], off
	s_waitcnt vmcnt(8)
	s_waitcnt lgkmcnt(0)
	s_barrier
	s_waitcnt lgkmcnt(0)
	v_mfma_f32_16x16x32_bf16 v[60:63], v[140:143], v[182:185], v[60:63]
	v_mfma_f32_16x16x32_bf16 v[56:59], v[158:161], v[182:185], v[56:59]
	v_mfma_f32_16x16x32_bf16 v[48:51], v[140:143], v[190:193], v[48:51]
	v_mfma_f32_16x16x32_bf16 v[40:43], v[158:161], v[190:193], v[40:43]
	v_mfma_f32_16x16x32_bf16 v[32:35], v[140:143], v[198:201], v[32:35]
	v_mfma_f32_16x16x32_bf16 v[24:27], v[158:161], v[198:201], v[24:27]
	v_mfma_f32_16x16x32_bf16 v[16:19], v[140:143], v[206:209], v[16:19]
	v_mfma_f32_16x16x32_bf16 v[8:11], v[158:161], v[206:209], v[8:11]
	v_mfma_f32_16x16x32_bf16 v[60:63], v[154:157], v[186:189], v[60:63]
	v_mfma_f32_16x16x32_bf16 v[56:59], v[162:165], v[186:189], v[56:59]
	v_mfma_f32_16x16x32_bf16 v[48:51], v[154:157], v[194:197], v[48:51]
	v_mfma_f32_16x16x32_bf16 v[40:43], v[162:165], v[194:197], v[40:43]
	v_mfma_f32_16x16x32_bf16 v[32:35], v[154:157], v[202:205], v[32:35]
	v_mfma_f32_16x16x32_bf16 v[24:27], v[162:165], v[202:205], v[24:27]
	v_mfma_f32_16x16x32_bf16 v[16:19], v[154:157], v[210:213], v[16:19]
	v_mfma_f32_16x16x32_bf16 v[8:11], v[162:165], v[210:213], v[8:11]
	v_mfma_f32_16x16x32_bf16 v[52:55], v[166:169], v[182:185], v[52:55]
	v_mfma_f32_16x16x32_bf16 v[44:47], v[174:177], v[182:185], v[44:47]
	v_mfma_f32_16x16x32_bf16 v[36:39], v[166:169], v[190:193], v[36:39]
	v_mfma_f32_16x16x32_bf16 v[28:31], v[174:177], v[190:193], v[28:31]
	v_mfma_f32_16x16x32_bf16 v[20:23], v[166:169], v[198:201], v[20:23]
	v_mfma_f32_16x16x32_bf16 v[12:15], v[174:177], v[198:201], v[12:15]
	v_mfma_f32_16x16x32_bf16 v[4:7], v[166:169], v[206:209], v[4:7]
	v_mfma_f32_16x16x32_bf16 v[0:3], v[174:177], v[206:209], v[0:3]
	v_mfma_f32_16x16x32_bf16 v[52:55], v[170:173], v[186:189], v[52:55]
	v_mfma_f32_16x16x32_bf16 v[44:47], v[178:181], v[186:189], v[44:47]
	v_mfma_f32_16x16x32_bf16 v[36:39], v[170:173], v[194:197], v[36:39]
	v_mfma_f32_16x16x32_bf16 v[28:31], v[178:181], v[194:197], v[28:31]
	v_mfma_f32_16x16x32_bf16 v[20:23], v[170:173], v[202:205], v[20:23]
	v_mfma_f32_16x16x32_bf16 v[12:15], v[178:181], v[202:205], v[12:15]
	v_mfma_f32_16x16x32_bf16 v[4:7], v[170:173], v[210:213], v[4:7]
	v_mfma_f32_16x16x32_bf16 v[0:3], v[178:181], v[210:213], v[0:3]
	s_waitcnt vmcnt(4)
	s_barrier
	s_add_i32 s75, s75, 2
	s_add_u32 s36, s36, 0x100
	s_addc_u32 s37, s37, 0
	s_add_u32 s73, s73, 0x100
	s_addc_u32 s74, s74, 0
	s_cmp_gt_u32 s75, 29
	s_cbranch_scc0 .LBB0_785
	s_setprio 0
	s_and_b64 vcc, exec, s[14:15]
	s_cbranch_vccz .LBB0_788
	s_barrier

.LBB0_1083:
	s_add_i32 s52, s52, 1
	s_mov_b64 s[36:37], s[10:11]
	s_mov_b32 s67, s4
	s_mov_b32 s10, s4
	s_lshl_b32 s4, s52, 5
	s_add_i32 s4, s4, s40
	s_cmpk_lt_i32 s4, 0x80
	s_cselect_b64 s[34:35], -1, 0
	s_ashr_i32 s4, s4, 2
	s_mov_b64 s[0:1], s[8:9]
	s_and_b64 s[8:9], s[34:35], exec
	s_cselect_b32 s8, s41, s41
	s_cselect_b32 s10, s4, s10
	s_ashr_i32 s9, s8, 31
	s_lshl_b64 s[8:9], s[8:9], 20
	s_add_u32 s8, s42, s8
	s_addc_u32 s9, s43, s9
	s_and_b64 s[38:39], s[34:35], exec
	s_cselect_b32 s68, s9, s1
	s_cselect_b32 s69, s8, s0
	s_ashr_i32 s11, s10, 31
	s_lshl_b64 s[10:11], s[10:11], 20
	s_add_u32 s10, s44, s10
	s_addc_u32 s11, s45, s11
	s_and_b64 s[38:39], s[34:35], exec
	s_cselect_b32 s70, s11, s37
	s_cselect_b32 s71, s10, s36
	s_add_u32 s0, s0, 0x80080
	s_addc_u32 s1, s1, 0
	s_add_u32 s72, s36, 0x100
	s_addc_u32 s73, s37, 0
	s_mov_b32 s74, -2
	v_mov_b32_e32 v0, 0
	v_mov_b32_e32 v1, v137
	v_mov_b32_e32 v2, v137
	v_mov_b32_e32 v3, v137
	v_mov_b32_e32 v4, 0
	v_mov_b32_e32 v5, v137
	v_mov_b32_e32 v6, v137
	v_mov_b32_e32 v7, v137
	v_mov_b32_e32 v16, 0
	v_mov_b32_e32 v17, v137
	v_mov_b32_e32 v18, v137
	v_mov_b32_e32 v19, v137
	v_mov_b32_e32 v20, 0
	v_mov_b32_e32 v21, v137
	v_mov_b32_e32 v22, v137
	v_mov_b32_e32 v23, v137
	v_mov_b32_e32 v32, 0
	v_mov_b32_e32 v33, v137
	v_mov_b32_e32 v34, v137
	v_mov_b32_e32 v35, v137
	v_mov_b32_e32 v36, 0
	v_mov_b32_e32 v37, v137
	v_mov_b32_e32 v38, v137
	v_mov_b32_e32 v39, v137
	v_mov_b32_e32 v48, 0
	v_mov_b32_e32 v49, v137
	v_mov_b32_e32 v50, v137
	v_mov_b32_e32 v51, v137
	v_mov_b32_e32 v52, 0
	v_mov_b32_e32 v53, v137
	v_mov_b32_e32 v54, v137
	v_mov_b32_e32 v55, v137
	v_mov_b32_e32 v8, 0
	v_mov_b32_e32 v9, v137
	v_mov_b32_e32 v10, v137
	v_mov_b32_e32 v11, v137
	v_mov_b32_e32 v12, 0
	v_mov_b32_e32 v13, v137
	v_mov_b32_e32 v14, v137
	v_mov_b32_e32 v15, v137
	v_mov_b32_e32 v24, 0
	v_mov_b32_e32 v25, v137
	v_mov_b32_e32 v26, v137
	v_mov_b32_e32 v27, v137
	v_mov_b32_e32 v28, 0
	v_mov_b32_e32 v29, v137
	v_mov_b32_e32 v30, v137
	v_mov_b32_e32 v31, v137
	v_mov_b32_e32 v40, 0
	v_mov_b32_e32 v41, v137
	v_mov_b32_e32 v42, v137
	v_mov_b32_e32 v43, v137
	v_mov_b32_e32 v44, 0
	v_mov_b32_e32 v45, v137
	v_mov_b32_e32 v46, v137
	v_mov_b32_e32 v47, v137
	v_mov_b32_e32 v56, 0
	v_mov_b32_e32 v57, v137
	v_mov_b32_e32 v58, v137
	v_mov_b32_e32 v59, v137
	v_mov_b32_e32 v60, 0
	v_mov_b32_e32 v61, v137
	v_mov_b32_e32 v62, v137
	v_mov_b32_e32 v63, v137
	v_mov_b32_e32 v64, 0
	v_mov_b32_e32 v65, v137
	v_mov_b32_e32 v66, v137
	v_mov_b32_e32 v67, v137
	v_mov_b32_e32 v68, 0
	v_mov_b32_e32 v69, v137
	v_mov_b32_e32 v70, v137
	v_mov_b32_e32 v71, v137
	v_mov_b32_e32 v80, 0
	v_mov_b32_e32 v81, v137
	v_mov_b32_e32 v82, v137
	v_mov_b32_e32 v83, v137
	v_mov_b32_e32 v84, 0
	v_mov_b32_e32 v85, v137
	v_mov_b32_e32 v86, v137
	v_mov_b32_e32 v87, v137
	v_mov_b32_e32 v96, 0
	v_mov_b32_e32 v97, v137
	v_mov_b32_e32 v98, v137
	v_mov_b32_e32 v99, v137
	v_mov_b32_e32 v100, 0
	v_mov_b32_e32 v101, v137
	v_mov_b32_e32 v102, v137
	v_mov_b32_e32 v103, v137
	v_mov_b32_e32 v112, 0
	v_mov_b32_e32 v113, v137
	v_mov_b32_e32 v114, v137
	v_mov_b32_e32 v115, v137
	v_mov_b32_e32 v116, 0
	v_mov_b32_e32 v117, v137
	v_mov_b32_e32 v118, v137
	v_mov_b32_e32 v119, v137
	v_mov_b32_e32 v72, 0
	v_mov_b32_e32 v73, v137
	v_mov_b32_e32 v74, v137
	v_mov_b32_e32 v75, v137
	v_mov_b32_e32 v76, 0
	v_mov_b32_e32 v77, v137
	v_mov_b32_e32 v78, v137
	v_mov_b32_e32 v79, v137
	v_mov_b32_e32 v88, 0
	v_mov_b32_e32 v89, v137
	v_mov_b32_e32 v90, v137
	v_mov_b32_e32 v91, v137
	v_mov_b32_e32 v92, 0
	v_mov_b32_e32 v93, v137
	v_mov_b32_e32 v94, v137
	v_mov_b32_e32 v95, v137
	v_mov_b32_e32 v104, 0
	v_mov_b32_e32 v105, v137
	v_mov_b32_e32 v106, v137
	v_mov_b32_e32 v107, v137
	v_mov_b32_e32 v108, 0
	v_mov_b32_e32 v109, v137
	v_mov_b32_e32 v110, v137
	v_mov_b32_e32 v111, v137
	v_mov_b32_e32 v120, 0
	v_mov_b32_e32 v121, v137
	v_mov_b32_e32 v122, v137
	v_mov_b32_e32 v123, v137
	v_mov_b32_e32 v124, 0
	v_mov_b32_e32 v125, v137
	v_mov_b32_e32 v126, v137
	v_mov_b32_e32 v127, v137
	s_lshr_b32 s101, s88, 2
	s_cmp_lg_u32 s101, 1
	s_cbranch_scc1 .Lprio_skip7
	s_setprio 1
.Lprio_skip7:
.LBB0_1084:
	ds_read_b128 v[140:143], v150
	ds_read_b128 v[144:147], v150 offset:1024
	ds_read_b128 v[156:159], v150 offset:2048
	ds_read_b128 v[160:163], v150 offset:3072
	ds_read_b128 v[164:167], v151
	ds_read_b128 v[168:171], v151 offset:1024
	ds_read_b128 v[172:175], v151 offset:2048
	ds_read_b128 v[176:179], v151 offset:3072
	s_add_u32 s36, s0, 0xfff80080
	s_addc_u32 s37, s1, -1
	s_cmp_eq_u32 s74, 28
	s_cselect_b32 s39, s68, s37
	s_cselect_b32 s38, s69, s36
	s_cselect_b32 s37, s70, s73
	s_cselect_b32 s36, s71, s72
	s_sub_u32 s98, s0, 0x80000
	s_subb_u32 s99, s1, 0
	s_add_i32 m0, s85, 0x8000
	ds_read_b128 v[180:183], v152
	ds_read_b128 v[184:187], v152 offset:1024
	ds_read_b128 v[188:191], v152 offset:2048
	ds_read_b128 v[192:195], v152 offset:3072
	ds_read_b128 v[196:199], v152 offset:4096
	ds_read_b128 v[200:203], v152 offset:5120
	ds_read_b128 v[204:207], v152 offset:6144
	ds_read_b128 v[208:211], v152 offset:7168
	global_load_lds_dwordx4 v222, s[98:99]
	s_add_u32 s98, s98, 0x20000
	s_addc_u32 s99, s99, 0
	s_add_i32 m0, s85, 0x9000
	s_nop 0
	global_load_lds_dwordx4 v222, s[98:99]
	s_add_u32 s98, s98, 0x20000
	s_addc_u32 s99, s99, 0
	s_add_i32 m0, s85, 0xa000
	s_nop 0
	global_load_lds_dwordx4 v222, s[98:99]
	s_add_u32 s98, s98, 0x20000
	s_addc_u32 s99, s99, 0
	s_add_i32 m0, s85, 0xb000
	s_nop 0
	global_load_lds_dwordx4 v222, s[98:99]
	s_waitcnt vmcnt(8)
	s_waitcnt lgkmcnt(0)
	s_barrier
	s_waitcnt lgkmcnt(0)
	v_mfma_f32_16x16x32_bf16 v[124:127], v[140:143], v[180:183], v[124:127]
	v_mfma_f32_16x16x32_bf16 v[120:123], v[156:159], v[180:183], v[120:123]
	v_mfma_f32_16x16x32_bf16 v[108:111], v[140:143], v[188:191], v[108:111]
	v_mfma_f32_16x16x32_bf16 v[104:107], v[156:159], v[188:191], v[104:107]
	v_mfma_f32_16x16x32_bf16 v[92:95], v[140:143], v[196:199], v[92:95]
	v_mfma_f32_16x16x32_bf16 v[88:91], v[156:159], v[196:199], v[88:91]
	v_mfma_f32_16x16x32_bf16 v[76:79], v[140:143], v[204:207], v[76:79]
	v_mfma_f32_16x16x32_bf16 v[72:75], v[156:159], v[204:207], v[72:75]
	v_mfma_f32_16x16x32_bf16 v[124:127], v[144:147], v[184:187], v[124:127]
	v_mfma_f32_16x16x32_bf16 v[120:123], v[160:163], v[184:187], v[120:123]
	v_mfma_f32_16x16x32_bf16 v[108:111], v[144:147], v[192:195], v[108:111]
	v_mfma_f32_16x16x32_bf16 v[104:107], v[160:163], v[192:195], v[104:107]
	v_mfma_f32_16x16x32_bf16 v[92:95], v[144:147], v[200:203], v[92:95]
	v_mfma_f32_16x16x32_bf16 v[88:91], v[160:163], v[200:203], v[88:91]
	v_mfma_f32_16x16x32_bf16 v[76:79], v[144:147], v[208:211], v[76:79]
	v_mfma_f32_16x16x32_bf16 v[72:75], v[160:163], v[208:211], v[72:75]
	v_mfma_f32_16x16x32_bf16 v[116:119], v[164:167], v[180:183], v[116:119]
	v_mfma_f32_16x16x32_bf16 v[112:115], v[172:175], v[180:183], v[112:115]
	v_mfma_f32_16x16x32_bf16 v[100:103], v[164:167], v[188:191], v[100:103]
	v_mfma_f32_16x16x32_bf16 v[96:99], v[172:175], v[188:191], v[96:99]
	v_mfma_f32_16x16x32_bf16 v[84:87], v[164:167], v[196:199], v[84:87]
	v_mfma_f32_16x16x32_bf16 v[80:83], v[172:175], v[196:199], v[80:83]
	v_mfma_f32_16x16x32_bf16 v[68:71], v[164:167], v[204:207], v[68:71]
	v_mfma_f32_16x16x32_bf16 v[64:67], v[172:175], v[204:207], v[64:67]
	v_mfma_f32_16x16x32_bf16 v[116:119], v[168:171], v[184:187], v[116:119]
	v_mfma_f32_16x16x32_bf16 v[112:115], v[176:179], v[184:187], v[112:115]
	v_mfma_f32_16x16x32_bf16 v[100:103], v[168:171], v[192:195], v[100:103]
	v_mfma_f32_16x16x32_bf16 v[96:99], v[176:179], v[192:195], v[96:99]
	v_mfma_f32_16x16x32_bf16 v[84:87], v[168:171], v[200:203], v[84:87]
	v_mfma_f32_16x16x32_bf16 v[80:83], v[176:179], v[200:203], v[80:83]
	v_mfma_f32_16x16x32_bf16 v[68:71], v[168:171], v[208:211], v[68:71]
	v_mfma_f32_16x16x32_bf16 v[64:67], v[176:179], v[208:211], v[64:67]
	s_barrier
	s_add_i32 s75, s56, s5
	v_lshl_add_u64 v[212:213], s[36:37], 0, v[130:131]
	s_mov_b32 m0, s75
	ds_read_b128 v[180:183], v152 offset:16384
	ds_read_b128 v[184:187], v152 offset:17408
	ds_read_b128 v[188:191], v152 offset:18432
	ds_read_b128 v[192:195], v152 offset:19456
	ds_read_b128 v[196:199], v152 offset:20480
	ds_read_b128 v[200:203], v152 offset:21504
	ds_read_b128 v[204:207], v152 offset:22528
	ds_read_b128 v[208:211], v152 offset:23552
	global_load_lds_dwordx4 v[212:213], off
	s_add_i32 m0, s75, 0x2000
	s_add_u32 s76, s36, 0x80000
	v_lshl_add_u64 v[214:215], s[36:37], 0, v[134:135]
	s_addc_u32 s77, s37, 0
	s_add_i32 s75, s57, s5
	global_load_lds_dwordx4 v[214:215], off
	v_lshl_add_u64 v[216:217], s[76:77], 0, v[130:131]
	s_mov_b32 m0, s75
	global_load_lds_dwordx4 v[216:217], off
	v_lshl_add_u64 v[216:217], s[76:77], 0, v[134:135]
	s_add_i32 m0, s75, 0x2000
	s_nop 0
	global_load_lds_dwordx4 v[216:217], off
	s_waitcnt vmcnt(8)
	s_waitcnt lgkmcnt(0)
	s_barrier
	s_waitcnt lgkmcnt(0)
	v_mfma_f32_16x16x32_bf16 v[60:63], v[140:143], v[180:183], v[60:63]
	v_mfma_f32_16x16x32_bf16 v[56:59], v[156:159], v[180:183], v[56:59]
	v_mfma_f32_16x16x32_bf16 v[44:47], v[140:143], v[188:191], v[44:47]
	v_mfma_f32_16x16x32_bf16 v[40:43], v[156:159], v[188:191], v[40:43]
	v_mfma_f32_16x16x32_bf16 v[28:31], v[140:143], v[196:199], v[28:31]
	v_mfma_f32_16x16x32_bf16 v[24:27], v[156:159], v[196:199], v[24:27]
	v_mfma_f32_16x16x32_bf16 v[12:15], v[140:143], v[204:207], v[12:15]
	v_mfma_f32_16x16x32_bf16 v[8:11], v[156:159], v[204:207], v[8:11]
	v_mfma_f32_16x16x32_bf16 v[60:63], v[144:147], v[184:187], v[60:63]
	v_mfma_f32_16x16x32_bf16 v[56:59], v[160:163], v[184:187], v[56:59]
	v_mfma_f32_16x16x32_bf16 v[44:47], v[144:147], v[192:195], v[44:47]
	v_mfma_f32_16x16x32_bf16 v[40:43], v[160:163], v[192:195], v[40:43]
	v_mfma_f32_16x16x32_bf16 v[28:31], v[144:147], v[200:203], v[28:31]
	v_mfma_f32_16x16x32_bf16 v[24:27], v[160:163], v[200:203], v[24:27]
	v_mfma_f32_16x16x32_bf16 v[12:15], v[144:147], v[208:211], v[12:15]
	v_mfma_f32_16x16x32_bf16 v[8:11], v[160:163], v[208:211], v[8:11]
	v_mfma_f32_16x16x32_bf16 v[52:55], v[164:167], v[180:183], v[52:55]
	v_mfma_f32_16x16x32_bf16 v[48:51], v[172:175], v[180:183], v[48:51]
	v_mfma_f32_16x16x32_bf16 v[36:39], v[164:167], v[188:191], v[36:39]
	v_mfma_f32_16x16x32_bf16 v[32:35], v[172:175], v[188:191], v[32:35]
	v_mfma_f32_16x16x32_bf16 v[20:23], v[164:167], v[196:199], v[20:23]
	v_mfma_f32_16x16x32_bf16 v[16:19], v[172:175], v[196:199], v[16:19]
	v_mfma_f32_16x16x32_bf16 v[4:7], v[164:167], v[204:207], v[4:7]
	v_mfma_f32_16x16x32_bf16 v[0:3], v[172:175], v[204:207], v[0:3]
	v_mfma_f32_16x16x32_bf16 v[52:55], v[168:171], v[184:187], v[52:55]
	v_mfma_f32_16x16x32_bf16 v[48:51], v[176:179], v[184:187], v[48:51]
	v_mfma_f32_16x16x32_bf16 v[36:39], v[168:171], v[192:195], v[36:39]
	v_mfma_f32_16x16x32_bf16 v[32:35], v[176:179], v[192:195], v[32:35]
	v_mfma_f32_16x16x32_bf16 v[20:23], v[168:171], v[200:203], v[20:23]
	v_mfma_f32_16x16x32_bf16 v[16:19], v[176:179], v[200:203], v[16:19]
	v_mfma_f32_16x16x32_bf16 v[4:7], v[168:171], v[208:211], v[4:7]
	v_mfma_f32_16x16x32_bf16 v[0:3], v[176:179], v[208:211], v[0:3]
	s_waitcnt vmcnt(4)
	s_barrier
	ds_read_b128 v[140:143], v153
	ds_read_b128 v[144:147], v153 offset:1024
	ds_read_b128 v[156:159], v153 offset:2048
	ds_read_b128 v[160:163], v153 offset:3072
	ds_read_b128 v[164:167], v154
	ds_read_b128 v[168:171], v154 offset:1024
	ds_read_b128 v[172:175], v154 offset:2048
	ds_read_b128 v[176:179], v154 offset:3072
	s_mov_b32 s98, s38
	s_mov_b32 s99, s39
	s_add_i32 m0, s85, 0
	ds_read_b128 v[180:183], v152 offset:32768
	ds_read_b128 v[184:187], v152 offset:33792
	ds_read_b128 v[188:191], v152 offset:34816
	ds_read_b128 v[192:195], v152 offset:35840
	ds_read_b128 v[196:199], v152 offset:36864
	ds_read_b128 v[200:203], v152 offset:37888
	ds_read_b128 v[204:207], v152 offset:38912
	ds_read_b128 v[208:211], v152 offset:39936
	global_load_lds_dwordx4 v222, s[98:99]
	s_add_u32 s98, s98, 0x20000
	s_addc_u32 s99, s99, 0
	s_add_i32 m0, s85, 0x1000
	s_nop 0
	global_load_lds_dwordx4 v222, s[98:99]
	s_add_u32 s98, s98, 0x20000
	s_addc_u32 s99, s99, 0
	s_add_i32 m0, s85, 0x2000
	s_nop 0
	global_load_lds_dwordx4 v222, s[98:99]
	s_add_u32 s98, s98, 0x20000
	s_addc_u32 s99, s99, 0
	s_add_i32 m0, s85, 0x3000
	s_nop 0
	global_load_lds_dwordx4 v222, s[98:99]
	s_waitcnt vmcnt(8)
	s_waitcnt lgkmcnt(0)
	s_barrier
	s_waitcnt lgkmcnt(0)
	v_mfma_f32_16x16x32_bf16 v[124:127], v[140:143], v[180:183], v[124:127]
	v_mfma_f32_16x16x32_bf16 v[120:123], v[156:159], v[180:183], v[120:123]
	v_mfma_f32_16x16x32_bf16 v[108:111], v[140:143], v[188:191], v[108:111]
	v_mfma_f32_16x16x32_bf16 v[104:107], v[156:159], v[188:191], v[104:107]
	v_mfma_f32_16x16x32_bf16 v[92:95], v[140:143], v[196:199], v[92:95]
	v_mfma_f32_16x16x32_bf16 v[88:91], v[156:159], v[196:199], v[88:91]
	v_mfma_f32_16x16x32_bf16 v[76:79], v[140:143], v[204:207], v[76:79]
	v_mfma_f32_16x16x32_bf16 v[72:75], v[156:159], v[204:207], v[72:75]
	v_mfma_f32_16x16x32_bf16 v[124:127], v[144:147], v[184:187], v[124:127]
	v_mfma_f32_16x16x32_bf16 v[120:123], v[160:163], v[184:187], v[120:123]
	v_mfma_f32_16x16x32_bf16 v[108:111], v[144:147], v[192:195], v[108:111]
	v_mfma_f32_16x16x32_bf16 v[104:107], v[160:163], v[192:195], v[104:107]
	v_mfma_f32_16x16x32_bf16 v[92:95], v[144:147], v[200:203], v[92:95]
	v_mfma_f32_16x16x32_bf16 v[88:91], v[160:163], v[200:203], v[88:91]
	v_mfma_f32_16x16x32_bf16 v[76:79], v[144:147], v[208:211], v[76:79]
	v_mfma_f32_16x16x32_bf16 v[72:75], v[160:163], v[208:211], v[72:75]
	v_mfma_f32_16x16x32_bf16 v[116:119], v[164:167], v[180:183], v[116:119]
	v_mfma_f32_16x16x32_bf16 v[112:115], v[172:175], v[180:183], v[112:115]
	v_mfma_f32_16x16x32_bf16 v[100:103], v[164:167], v[188:191], v[100:103]
	v_mfma_f32_16x16x32_bf16 v[96:99], v[172:175], v[188:191], v[96:99]
	v_mfma_f32_16x16x32_bf16 v[84:87], v[164:167], v[196:199], v[84:87]
	v_mfma_f32_16x16x32_bf16 v[80:83], v[172:175], v[196:199], v[80:83]
	v_mfma_f32_16x16x32_bf16 v[68:71], v[164:167], v[204:207], v[68:71]
	v_mfma_f32_16x16x32_bf16 v[64:67], v[172:175], v[204:207], v[64:67]
	v_mfma_f32_16x16x32_bf16 v[116:119], v[168:171], v[184:187], v[116:119]
	v_mfma_f32_16x16x32_bf16 v[112:115], v[176:179], v[184:187], v[112:115]
	v_mfma_f32_16x16x32_bf16 v[100:103], v[168:171], v[192:195], v[100:103]
	v_mfma_f32_16x16x32_bf16 v[96:99], v[176:179], v[192:195], v[96:99]
	v_mfma_f32_16x16x32_bf16 v[84:87], v[168:171], v[200:203], v[84:87]
	v_mfma_f32_16x16x32_bf16 v[80:83], v[176:179], v[200:203], v[80:83]
	v_mfma_f32_16x16x32_bf16 v[68:71], v[168:171], v[208:211], v[68:71]
	v_mfma_f32_16x16x32_bf16 v[64:67], v[176:179], v[208:211], v[64:67]
	s_barrier
	s_add_i32 s38, s58, s5
	v_lshl_add_u64 v[212:213], v[212:213], 0, s[14:15]
	s_mov_b32 m0, s38
	ds_read_b128 v[180:183], v152 offset:49152
	ds_read_b128 v[184:187], v152 offset:50176
	ds_read_b128 v[188:191], v152 offset:51200
	ds_read_b128 v[192:195], v152 offset:52224
	ds_read_b128 v[196:199], v152 offset:53248
	ds_read_b128 v[200:203], v152 offset:54272
	ds_read_b128 v[204:207], v152 offset:55296
	ds_read_b128 v[208:211], v152 offset:56320
	global_load_lds_dwordx4 v[212:213], off
	s_add_i32 m0, s38, 0x2000
	s_add_u32 s36, s36, 0x80080
	v_lshl_add_u64 v[212:213], v[214:215], 0, s[14:15]
	s_addc_u32 s37, s37, 0
	s_add_i32 s38, s59, s5
	global_load_lds_dwordx4 v[212:213], off
	v_lshl_add_u64 v[212:213], s[36:37], 0, v[130:131]
	s_mov_b32 m0, s38
	s_nop 0
	global_load_lds_dwordx4 v[212:213], off
	v_lshl_add_u64 v[212:213], s[36:37], 0, v[134:135]
	s_add_i32 m0, s38, 0x2000
	s_nop 0
	global_load_lds_dwordx4 v[212:213], off
	s_waitcnt vmcnt(8)
	s_waitcnt lgkmcnt(0)
	s_barrier
	s_waitcnt lgkmcnt(0)
	v_mfma_f32_16x16x32_bf16 v[60:63], v[140:143], v[180:183], v[60:63]
	v_mfma_f32_16x16x32_bf16 v[56:59], v[156:159], v[180:183], v[56:59]
	v_mfma_f32_16x16x32_bf16 v[44:47], v[140:143], v[188:191], v[44:47]
	v_mfma_f32_16x16x32_bf16 v[40:43], v[156:159], v[188:191], v[40:43]
	v_mfma_f32_16x16x32_bf16 v[28:31], v[140:143], v[196:199], v[28:31]
	v_mfma_f32_16x16x32_bf16 v[24:27], v[156:159], v[196:199], v[24:27]
	v_mfma_f32_16x16x32_bf16 v[12:15], v[140:143], v[204:207], v[12:15]
	v_mfma_f32_16x16x32_bf16 v[8:11], v[156:159], v[204:207], v[8:11]
	v_mfma_f32_16x16x32_bf16 v[60:63], v[144:147], v[184:187], v[60:63]
	v_mfma_f32_16x16x32_bf16 v[56:59], v[160:163], v[184:187], v[56:59]
	v_mfma_f32_16x16x32_bf16 v[44:47], v[144:147], v[192:195], v[44:47]
	v_mfma_f32_16x16x32_bf16 v[40:43], v[160:163], v[192:195], v[40:43]
	v_mfma_f32_16x16x32_bf16 v[28:31], v[144:147], v[200:203], v[28:31]
	v_mfma_f32_16x16x32_bf16 v[24:27], v[160:163], v[200:203], v[24:27]
	v_mfma_f32_16x16x32_bf16 v[12:15], v[144:147], v[208:211], v[12:15]
	v_mfma_f32_16x16x32_bf16 v[8:11], v[160:163], v[208:211], v[8:11]
	v_mfma_f32_16x16x32_bf16 v[52:55], v[164:167], v[180:183], v[52:55]
	v_mfma_f32_16x16x32_bf16 v[48:51], v[172:175], v[180:183], v[48:51]
	v_mfma_f32_16x16x32_bf16 v[36:39], v[164:167], v[188:191], v[36:39]
	v_mfma_f32_16x16x32_bf16 v[32:35], v[172:175], v[188:191], v[32:35]
	v_mfma_f32_16x16x32_bf16 v[20:23], v[164:167], v[196:199], v[20:23]
	v_mfma_f32_16x16x32_bf16 v[16:19], v[172:175], v[196:199], v[16:19]
	v_mfma_f32_16x16x32_bf16 v[4:7], v[164:167], v[204:207], v[4:7]
	v_mfma_f32_16x16x32_bf16 v[0:3], v[172:175], v[204:207], v[0:3]
	v_mfma_f32_16x16x32_bf16 v[52:55], v[168:171], v[184:187], v[52:55]
	v_mfma_f32_16x16x32_bf16 v[48:51], v[176:179], v[184:187], v[48:51]
	v_mfma_f32_16x16x32_bf16 v[36:39], v[168:171], v[192:195], v[36:39]
	v_mfma_f32_16x16x32_bf16 v[32:35], v[176:179], v[192:195], v[32:35]
	v_mfma_f32_16x16x32_bf16 v[20:23], v[168:171], v[200:203], v[20:23]
	v_mfma_f32_16x16x32_bf16 v[16:19], v[176:179], v[200:203], v[16:19]
	v_mfma_f32_16x16x32_bf16 v[4:7], v[168:171], v[208:211], v[4:7]
	v_mfma_f32_16x16x32_bf16 v[0:3], v[176:179], v[208:211], v[0:3]
	s_waitcnt vmcnt(4)
	s_barrier
	s_add_i32 s74, s74, 2
	s_add_u32 s0, s0, 0x100
	s_addc_u32 s1, s1, 0
	s_add_u32 s72, s72, 0x100
	s_addc_u32 s73, s73, 0
	s_cmp_gt_u32 s74, 29
	s_cbranch_scc0 .LBB0_1084
	s_setprio 0
	s_and_b64 vcc, exec, s[16:17]
	s_cbranch_vccz .LBB0_1087
	s_barrier

.LBB0_1193:
	s_add_i32 s56, s56, 1
	s_lshl_b32 s2, s56, 5
	s_add_i32 s2, s2, s34
	s_cmp_lt_i32 s2, 32
	s_mov_b32 s20, s6
	s_cselect_b64 s[26:27], -1, 0
	s_ashr_i32 s6, s2, 2
	s_ashr_i32 s7, s6, 31
	s_lshl_b64 s[2:3], s[6:7], 22
	s_mov_b64 s[0:1], s[8:9]
	s_add_u32 s8, s35, s2
	s_addc_u32 s9, s36, s3
	s_and_b64 s[2:3], s[26:27], exec
	v_mov_b32_e32 v0, 0
	s_cselect_b32 s7, s9, s1
	s_cselect_b32 s57, s8, s0
	s_mov_b32 s58, -2
	s_mov_b64 s[2:3], 0x100
	s_waitcnt lgkmcnt(0)
	v_mov_b32_e32 v1, v0
	v_mov_b32_e32 v2, v0
	v_mov_b32_e32 v3, v0
	v_mov_b32_e32 v4, v0
	v_mov_b32_e32 v5, v0
	v_mov_b32_e32 v6, v0
	v_mov_b32_e32 v7, v0
	v_mov_b32_e32 v16, v0
	v_mov_b32_e32 v17, v0
	v_mov_b32_e32 v18, v0
	v_mov_b32_e32 v19, v0
	v_mov_b32_e32 v20, v0
	v_mov_b32_e32 v21, v0
	v_mov_b32_e32 v22, v0
	v_mov_b32_e32 v23, v0
	v_mov_b32_e32 v32, v0
	v_mov_b32_e32 v33, v0
	v_mov_b32_e32 v34, v0
	v_mov_b32_e32 v35, v0
	v_mov_b32_e32 v36, v0
	v_mov_b32_e32 v37, v0
	v_mov_b32_e32 v38, v0
	v_mov_b32_e32 v39, v0
	v_mov_b32_e32 v48, v0
	v_mov_b32_e32 v49, v0
	v_mov_b32_e32 v50, v0
	v_mov_b32_e32 v51, v0
	v_mov_b32_e32 v52, v0
	v_mov_b32_e32 v53, v0
	v_mov_b32_e32 v54, v0
	v_mov_b32_e32 v55, v0
	v_mov_b32_e32 v8, v0
	v_mov_b32_e32 v9, v0
	v_mov_b32_e32 v10, v0
	v_mov_b32_e32 v11, v0
	v_mov_b32_e32 v12, v0
	v_mov_b32_e32 v13, v0
	v_mov_b32_e32 v14, v0
	v_mov_b32_e32 v15, v0
	v_mov_b32_e32 v24, v0
	v_mov_b32_e32 v25, v0
	v_mov_b32_e32 v26, v0
	v_mov_b32_e32 v27, v0
	v_mov_b32_e32 v28, v0
	v_mov_b32_e32 v29, v0
	v_mov_b32_e32 v30, v0
	v_mov_b32_e32 v31, v0
	v_mov_b32_e32 v40, v0
	v_mov_b32_e32 v41, v0
	v_mov_b32_e32 v42, v0
	v_mov_b32_e32 v43, v0
	v_mov_b32_e32 v44, v0
	v_mov_b32_e32 v45, v0
	v_mov_b32_e32 v46, v0
	v_mov_b32_e32 v47, v0
	v_mov_b32_e32 v56, v0
	v_mov_b32_e32 v57, v0
	v_mov_b32_e32 v58, v0
	v_mov_b32_e32 v59, v0
	v_mov_b32_e32 v60, v0
	v_mov_b32_e32 v61, v0
	v_mov_b32_e32 v62, v0
	v_mov_b32_e32 v63, v0
	v_mov_b32_e32 v64, v0
	v_mov_b32_e32 v65, v0
	v_mov_b32_e32 v66, v0
	v_mov_b32_e32 v67, v0
	v_mov_b32_e32 v68, v0
	v_mov_b32_e32 v69, v0
	v_mov_b32_e32 v70, v0
	v_mov_b32_e32 v71, v0
	v_mov_b32_e32 v80, v0
	v_mov_b32_e32 v81, v0
	v_mov_b32_e32 v82, v0
	v_mov_b32_e32 v83, v0
	v_mov_b32_e32 v84, v0
	v_mov_b32_e32 v85, v0
	v_mov_b32_e32 v86, v0
	v_mov_b32_e32 v87, v0
	v_mov_b32_e32 v96, v0
	v_mov_b32_e32 v97, v0
	v_mov_b32_e32 v98, v0
	v_mov_b32_e32 v99, v0
	v_mov_b32_e32 v100, v0
	v_mov_b32_e32 v101, v0
	v_mov_b32_e32 v102, v0
	v_mov_b32_e32 v103, v0
	v_mov_b32_e32 v112, v0
	v_mov_b32_e32 v113, v0
	v_mov_b32_e32 v114, v0
	v_mov_b32_e32 v115, v0
	v_mov_b32_e32 v116, v0
	v_mov_b32_e32 v117, v0
	v_mov_b32_e32 v118, v0
	v_mov_b32_e32 v119, v0
	v_mov_b32_e32 v72, v0
	v_mov_b32_e32 v73, v0
	v_mov_b32_e32 v74, v0
	v_mov_b32_e32 v75, v0
	v_mov_b32_e32 v76, v0
	v_mov_b32_e32 v77, v0
	v_mov_b32_e32 v78, v0
	v_mov_b32_e32 v79, v0
	v_mov_b32_e32 v88, v0
	v_mov_b32_e32 v89, v0
	v_mov_b32_e32 v90, v0
	v_mov_b32_e32 v91, v0
	v_mov_b32_e32 v92, v0
	v_mov_b32_e32 v93, v0
	v_mov_b32_e32 v94, v0
	v_mov_b32_e32 v95, v0
	v_mov_b32_e32 v104, v0
	v_mov_b32_e32 v105, v0
	v_mov_b32_e32 v106, v0
	v_mov_b32_e32 v107, v0
	v_mov_b32_e32 v108, v0
	v_mov_b32_e32 v109, v0
	v_mov_b32_e32 v110, v0
	v_mov_b32_e32 v111, v0
	v_mov_b32_e32 v124, v0
	v_mov_b32_e32 v125, v0
	v_mov_b32_e32 v126, v0
	v_mov_b32_e32 v127, v0
	v_mov_b32_e32 v128, v0
	v_mov_b32_e32 v129, v0
	v_mov_b32_e32 v130, v0
	v_mov_b32_e32 v131, v0
	s_lshr_b32 s101, s88, 2
	s_cmp_lg_u32 s101, 1
	s_cbranch_scc1 .Lprio_skip8
	s_setprio 1
.Lprio_skip8:
.LBB0_1194:
	ds_read_b128 v[120:123], v230
	ds_read_b128 v[132:135], v230 offset:1024
	ds_read_b128 v[136:139], v230 offset:2048
	ds_read_b128 v[140:143], v230 offset:3072
	ds_read_b128 v[144:147], v231
	ds_read_b128 v[148:151], v231 offset:1024
	ds_read_b128 v[152:155], v231 offset:2048
	ds_read_b128 v[156:159], v231 offset:3072
	s_add_u32 s28, s0, s2
	s_addc_u32 s29, s1, s3
	s_cmpk_eq_i32 s2, 0x4000
	s_cselect_b32 s30, 0, s2
	s_cselect_b32 s31, 0, s3
	s_cselect_b32 s28, s57, s28
	s_cselect_b32 s29, s7, s29
	s_add_u32 s30, s10, s30
	s_addc_u32 s31, s11, s31
	s_add_u32 s98, s2, s86
	s_addc_u32 s99, s3, s87
	s_add_i32 m0, s85, 0x8000
	v_lshl_add_u64 v[204:205], v[192:193], 0, s[98:99]
	ds_read_b128 v[160:163], v232
	ds_read_b128 v[164:167], v232 offset:1024
	ds_read_b128 v[168:171], v232 offset:2048
	ds_read_b128 v[172:175], v232 offset:3072
	ds_read_b128 v[176:179], v232 offset:4096
	ds_read_b128 v[180:183], v232 offset:5120
	ds_read_b128 v[196:199], v232 offset:6144
	ds_read_b128 v[200:203], v232 offset:7168
	global_load_lds_dwordx4 v[204:205], off
	s_add_u32 s98, s98, 0x80000
	s_addc_u32 s99, s99, 0
	s_add_i32 m0, s85, 0x9000
	v_lshl_add_u64 v[204:205], v[192:193], 0, s[98:99]
	global_load_lds_dwordx4 v[204:205], off
	s_add_u32 s98, s98, 0x80000
	s_addc_u32 s99, s99, 0
	s_add_i32 m0, s85, 0xa000
	v_lshl_add_u64 v[204:205], v[192:193], 0, s[98:99]
	global_load_lds_dwordx4 v[204:205], off
	s_add_u32 s98, s98, 0x80000
	s_addc_u32 s99, s99, 0
	s_add_i32 m0, s85, 0xb000
	v_lshl_add_u64 v[204:205], v[192:193], 0, s[98:99]
	global_load_lds_dwordx4 v[204:205], off
	s_waitcnt vmcnt(8)
	s_waitcnt lgkmcnt(0)
	s_barrier
	s_waitcnt lgkmcnt(0)
	v_mfma_f32_16x16x32_bf16 v[128:131], v[120:123], v[160:163], v[128:131]
	v_mfma_f32_16x16x32_bf16 v[124:127], v[136:139], v[160:163], v[124:127]
	v_mfma_f32_16x16x32_bf16 v[108:111], v[120:123], v[168:171], v[108:111]
	v_mfma_f32_16x16x32_bf16 v[104:107], v[136:139], v[168:171], v[104:107]
	v_mfma_f32_16x16x32_bf16 v[92:95], v[120:123], v[176:179], v[92:95]
	v_mfma_f32_16x16x32_bf16 v[88:91], v[136:139], v[176:179], v[88:91]
	v_mfma_f32_16x16x32_bf16 v[76:79], v[120:123], v[196:199], v[76:79]
	v_mfma_f32_16x16x32_bf16 v[72:75], v[136:139], v[196:199], v[72:75]
	v_mfma_f32_16x16x32_bf16 v[128:131], v[132:135], v[164:167], v[128:131]
	v_mfma_f32_16x16x32_bf16 v[124:127], v[140:143], v[164:167], v[124:127]
	v_mfma_f32_16x16x32_bf16 v[108:111], v[132:135], v[172:175], v[108:111]
	v_mfma_f32_16x16x32_bf16 v[104:107], v[140:143], v[172:175], v[104:107]
	v_mfma_f32_16x16x32_bf16 v[92:95], v[132:135], v[180:183], v[92:95]
	v_mfma_f32_16x16x32_bf16 v[88:91], v[140:143], v[180:183], v[88:91]
	v_mfma_f32_16x16x32_bf16 v[76:79], v[132:135], v[200:203], v[76:79]
	v_mfma_f32_16x16x32_bf16 v[72:75], v[140:143], v[200:203], v[72:75]
	v_mfma_f32_16x16x32_bf16 v[116:119], v[144:147], v[160:163], v[116:119]
	v_mfma_f32_16x16x32_bf16 v[112:115], v[152:155], v[160:163], v[112:115]
	v_mfma_f32_16x16x32_bf16 v[100:103], v[144:147], v[168:171], v[100:103]
	v_mfma_f32_16x16x32_bf16 v[96:99], v[152:155], v[168:171], v[96:99]
	v_mfma_f32_16x16x32_bf16 v[84:87], v[144:147], v[176:179], v[84:87]
	v_mfma_f32_16x16x32_bf16 v[80:83], v[152:155], v[176:179], v[80:83]
	v_mfma_f32_16x16x32_bf16 v[68:71], v[144:147], v[196:199], v[68:71]
	v_mfma_f32_16x16x32_bf16 v[64:67], v[152:155], v[196:199], v[64:67]
	v_mfma_f32_16x16x32_bf16 v[116:119], v[148:151], v[164:167], v[116:119]
	v_mfma_f32_16x16x32_bf16 v[112:115], v[156:159], v[164:167], v[112:115]
	v_mfma_f32_16x16x32_bf16 v[100:103], v[148:151], v[172:175], v[100:103]
	v_mfma_f32_16x16x32_bf16 v[96:99], v[156:159], v[172:175], v[96:99]
	v_mfma_f32_16x16x32_bf16 v[84:87], v[148:151], v[180:183], v[84:87]
	v_mfma_f32_16x16x32_bf16 v[80:83], v[156:159], v[180:183], v[80:83]
	v_mfma_f32_16x16x32_bf16 v[68:71], v[148:151], v[200:203], v[68:71]
	v_mfma_f32_16x16x32_bf16 v[64:67], v[156:159], v[200:203], v[64:67]
	s_barrier
	s_mov_b32 m0, s50
	v_lshl_add_u64 v[204:205], s[28:29], 0, v[188:189]
	s_add_u32 s60, s28, 0x200000
	ds_read_b128 v[160:163], v232 offset:16384
	ds_read_b128 v[164:167], v232 offset:17408
	ds_read_b128 v[168:171], v232 offset:18432
	ds_read_b128 v[172:175], v232 offset:19456
	ds_read_b128 v[176:179], v232 offset:20480
	ds_read_b128 v[180:183], v232 offset:21504
	ds_read_b128 v[196:199], v232 offset:22528
	ds_read_b128 v[200:203], v232 offset:23552
	global_load_lds_dwordx4 v[204:205], off
	v_lshl_add_u64 v[206:207], s[28:29], 0, v[184:185]
	s_mov_b32 m0, s51
	s_addc_u32 s61, s29, 0
	global_load_lds_dwordx4 v[206:207], off
	v_lshl_add_u64 v[208:209], s[60:61], 0, v[188:189]
	s_mov_b32 m0, s52
	global_load_lds_dwordx4 v[208:209], off
	v_lshl_add_u64 v[208:209], s[60:61], 0, v[184:185]
	s_mov_b32 m0, s53
	s_nop 0
	global_load_lds_dwordx4 v[208:209], off
	s_waitcnt vmcnt(8)
	s_waitcnt lgkmcnt(0)
	s_barrier
	s_waitcnt lgkmcnt(0)
	v_mfma_f32_16x16x32_bf16 v[60:63], v[120:123], v[160:163], v[60:63]
	v_mfma_f32_16x16x32_bf16 v[56:59], v[136:139], v[160:163], v[56:59]
	v_mfma_f32_16x16x32_bf16 v[44:47], v[120:123], v[168:171], v[44:47]
	v_mfma_f32_16x16x32_bf16 v[40:43], v[136:139], v[168:171], v[40:43]
	v_mfma_f32_16x16x32_bf16 v[28:31], v[120:123], v[176:179], v[28:31]
	v_mfma_f32_16x16x32_bf16 v[24:27], v[136:139], v[176:179], v[24:27]
	v_mfma_f32_16x16x32_bf16 v[12:15], v[120:123], v[196:199], v[12:15]
	v_mfma_f32_16x16x32_bf16 v[8:11], v[136:139], v[196:199], v[8:11]
	v_mfma_f32_16x16x32_bf16 v[60:63], v[132:135], v[164:167], v[60:63]
	v_mfma_f32_16x16x32_bf16 v[56:59], v[140:143], v[164:167], v[56:59]
	v_mfma_f32_16x16x32_bf16 v[44:47], v[132:135], v[172:175], v[44:47]
	v_mfma_f32_16x16x32_bf16 v[40:43], v[140:143], v[172:175], v[40:43]
	v_mfma_f32_16x16x32_bf16 v[28:31], v[132:135], v[180:183], v[28:31]
	v_mfma_f32_16x16x32_bf16 v[24:27], v[140:143], v[180:183], v[24:27]
	v_mfma_f32_16x16x32_bf16 v[12:15], v[132:135], v[200:203], v[12:15]
	v_mfma_f32_16x16x32_bf16 v[8:11], v[140:143], v[200:203], v[8:11]
	v_mfma_f32_16x16x32_bf16 v[52:55], v[144:147], v[160:163], v[52:55]
	v_mfma_f32_16x16x32_bf16 v[48:51], v[152:155], v[160:163], v[48:51]
	v_mfma_f32_16x16x32_bf16 v[36:39], v[144:147], v[168:171], v[36:39]
	v_mfma_f32_16x16x32_bf16 v[32:35], v[152:155], v[168:171], v[32:35]
	v_mfma_f32_16x16x32_bf16 v[20:23], v[144:147], v[176:179], v[20:23]
	v_mfma_f32_16x16x32_bf16 v[16:19], v[152:155], v[176:179], v[16:19]
	v_mfma_f32_16x16x32_bf16 v[4:7], v[144:147], v[196:199], v[4:7]
	v_mfma_f32_16x16x32_bf16 v[0:3], v[152:155], v[196:199], v[0:3]
	v_mfma_f32_16x16x32_bf16 v[52:55], v[148:151], v[164:167], v[52:55]
	v_mfma_f32_16x16x32_bf16 v[48:51], v[156:159], v[164:167], v[48:51]
	v_mfma_f32_16x16x32_bf16 v[36:39], v[148:151], v[172:175], v[36:39]
	v_mfma_f32_16x16x32_bf16 v[32:35], v[156:159], v[172:175], v[32:35]
	v_mfma_f32_16x16x32_bf16 v[20:23], v[148:151], v[180:183], v[20:23]
	v_mfma_f32_16x16x32_bf16 v[16:19], v[156:159], v[180:183], v[16:19]
	v_mfma_f32_16x16x32_bf16 v[4:7], v[148:151], v[200:203], v[4:7]
	v_mfma_f32_16x16x32_bf16 v[0:3], v[156:159], v[200:203], v[0:3]
	s_waitcnt vmcnt(4)
	s_barrier
	ds_read_b128 v[120:123], v234
	ds_read_b128 v[132:135], v234 offset:1024
	ds_read_b128 v[136:139], v234 offset:2048
	ds_read_b128 v[140:143], v234 offset:3072
	ds_read_b128 v[144:147], v235
	ds_read_b128 v[148:151], v235 offset:1024
	ds_read_b128 v[152:155], v235 offset:2048
	ds_read_b128 v[156:159], v235 offset:3072
	s_add_u32 s98, s30, s96
	s_addc_u32 s99, s31, s97
	s_add_i32 m0, s85, 0
	v_lshl_add_u64 v[212:213], s[98:99], 0, v[190:191]
	ds_read_b128 v[160:163], v232 offset:32768
	ds_read_b128 v[164:167], v232 offset:33792
	ds_read_b128 v[168:171], v232 offset:34816
	ds_read_b128 v[172:175], v232 offset:35840
	ds_read_b128 v[176:179], v232 offset:36864
	ds_read_b128 v[180:183], v232 offset:37888
	ds_read_b128 v[196:199], v232 offset:38912
	ds_read_b128 v[200:203], v232 offset:39936
	global_load_lds_dwordx4 v[212:213], off
	s_add_u32 s98, s98, 0x80000
	s_addc_u32 s99, s99, 0
	s_add_i32 m0, s85, 0x1000
	v_lshl_add_u64 v[212:213], s[98:99], 0, v[190:191]
	global_load_lds_dwordx4 v[212:213], off
	s_add_u32 s98, s98, 0x80000
	s_addc_u32 s99, s99, 0
	s_add_i32 m0, s85, 0x2000
	v_lshl_add_u64 v[212:213], s[98:99], 0, v[190:191]
	global_load_lds_dwordx4 v[212:213], off
	s_add_u32 s98, s98, 0x80000
	s_addc_u32 s99, s99, 0
	s_add_i32 m0, s85, 0x3000
	v_lshl_add_u64 v[212:213], s[98:99], 0, v[190:191]
	global_load_lds_dwordx4 v[212:213], off
	s_waitcnt vmcnt(8)
	s_waitcnt lgkmcnt(0)
	s_barrier
	s_waitcnt lgkmcnt(0)
	v_mfma_f32_16x16x32_bf16 v[128:131], v[120:123], v[160:163], v[128:131]
	v_mfma_f32_16x16x32_bf16 v[124:127], v[136:139], v[160:163], v[124:127]
	v_mfma_f32_16x16x32_bf16 v[108:111], v[120:123], v[168:171], v[108:111]
	v_mfma_f32_16x16x32_bf16 v[104:107], v[136:139], v[168:171], v[104:107]
	v_mfma_f32_16x16x32_bf16 v[92:95], v[120:123], v[176:179], v[92:95]
	v_mfma_f32_16x16x32_bf16 v[88:91], v[136:139], v[176:179], v[88:91]
	v_mfma_f32_16x16x32_bf16 v[76:79], v[120:123], v[196:199], v[76:79]
	v_mfma_f32_16x16x32_bf16 v[72:75], v[136:139], v[196:199], v[72:75]
	v_mfma_f32_16x16x32_bf16 v[128:131], v[132:135], v[164:167], v[128:131]
	v_mfma_f32_16x16x32_bf16 v[124:127], v[140:143], v[164:167], v[124:127]
	v_mfma_f32_16x16x32_bf16 v[108:111], v[132:135], v[172:175], v[108:111]
	v_mfma_f32_16x16x32_bf16 v[104:107], v[140:143], v[172:175], v[104:107]
	v_mfma_f32_16x16x32_bf16 v[92:95], v[132:135], v[180:183], v[92:95]
	v_mfma_f32_16x16x32_bf16 v[88:91], v[140:143], v[180:183], v[88:91]
	v_mfma_f32_16x16x32_bf16 v[76:79], v[132:135], v[200:203], v[76:79]
	v_mfma_f32_16x16x32_bf16 v[72:75], v[140:143], v[200:203], v[72:75]
	v_mfma_f32_16x16x32_bf16 v[116:119], v[144:147], v[160:163], v[116:119]
	v_mfma_f32_16x16x32_bf16 v[112:115], v[152:155], v[160:163], v[112:115]
	v_mfma_f32_16x16x32_bf16 v[100:103], v[144:147], v[168:171], v[100:103]
	v_mfma_f32_16x16x32_bf16 v[96:99], v[152:155], v[168:171], v[96:99]
	v_mfma_f32_16x16x32_bf16 v[84:87], v[144:147], v[176:179], v[84:87]
	v_mfma_f32_16x16x32_bf16 v[80:83], v[152:155], v[176:179], v[80:83]
	v_mfma_f32_16x16x32_bf16 v[68:71], v[144:147], v[196:199], v[68:71]
	v_mfma_f32_16x16x32_bf16 v[64:67], v[152:155], v[196:199], v[64:67]
	v_mfma_f32_16x16x32_bf16 v[116:119], v[148:151], v[164:167], v[116:119]
	v_mfma_f32_16x16x32_bf16 v[112:115], v[156:159], v[164:167], v[112:115]
	v_mfma_f32_16x16x32_bf16 v[100:103], v[148:151], v[172:175], v[100:103]
	v_mfma_f32_16x16x32_bf16 v[96:99], v[156:159], v[172:175], v[96:99]
	v_mfma_f32_16x16x32_bf16 v[84:87], v[148:151], v[180:183], v[84:87]
	v_mfma_f32_16x16x32_bf16 v[80:83], v[156:159], v[180:183], v[80:83]
	v_mfma_f32_16x16x32_bf16 v[68:71], v[148:151], v[200:203], v[68:71]
	v_mfma_f32_16x16x32_bf16 v[64:67], v[156:159], v[200:203], v[64:67]
	s_barrier
	s_add_i32 s30, s54, s37
	v_lshl_add_u64 v[204:205], v[204:205], 0, s[18:19]
	s_mov_b32 m0, s30
	ds_read_b128 v[160:163], v232 offset:49152
	ds_read_b128 v[164:167], v232 offset:50176
	ds_read_b128 v[168:171], v232 offset:51200
	ds_read_b128 v[172:175], v232 offset:52224
	ds_read_b128 v[176:179], v232 offset:53248
	ds_read_b128 v[180:183], v232 offset:54272
	ds_read_b128 v[196:199], v232 offset:55296
	ds_read_b128 v[200:203], v232 offset:56320
	global_load_lds_dwordx4 v[204:205], off
	s_add_i32 m0, s30, 0x2000
	s_add_u32 s28, s28, 0x200080
	v_lshl_add_u64 v[204:205], v[206:207], 0, s[18:19]
	s_addc_u32 s29, s29, 0
	s_add_i32 s30, s55, s37
	global_load_lds_dwordx4 v[204:205], off
	v_lshl_add_u64 v[204:205], s[28:29], 0, v[188:189]
	s_mov_b32 m0, s30
	s_nop 0
	global_load_lds_dwordx4 v[204:205], off
	v_lshl_add_u64 v[204:205], s[28:29], 0, v[184:185]
	s_add_i32 m0, s30, 0x2000
	s_nop 0
	global_load_lds_dwordx4 v[204:205], off
	s_waitcnt vmcnt(8)
	s_waitcnt lgkmcnt(0)
	s_barrier
	s_waitcnt lgkmcnt(0)
	v_mfma_f32_16x16x32_bf16 v[60:63], v[120:123], v[160:163], v[60:63]
	v_mfma_f32_16x16x32_bf16 v[56:59], v[136:139], v[160:163], v[56:59]
	v_mfma_f32_16x16x32_bf16 v[44:47], v[120:123], v[168:171], v[44:47]
	v_mfma_f32_16x16x32_bf16 v[40:43], v[136:139], v[168:171], v[40:43]
	v_mfma_f32_16x16x32_bf16 v[28:31], v[120:123], v[176:179], v[28:31]
	v_mfma_f32_16x16x32_bf16 v[24:27], v[136:139], v[176:179], v[24:27]
	v_mfma_f32_16x16x32_bf16 v[12:15], v[120:123], v[196:199], v[12:15]
	v_mfma_f32_16x16x32_bf16 v[8:11], v[136:139], v[196:199], v[8:11]
	v_mfma_f32_16x16x32_bf16 v[60:63], v[132:135], v[164:167], v[60:63]
	v_mfma_f32_16x16x32_bf16 v[56:59], v[140:143], v[164:167], v[56:59]
	v_mfma_f32_16x16x32_bf16 v[44:47], v[132:135], v[172:175], v[44:47]
	v_mfma_f32_16x16x32_bf16 v[40:43], v[140:143], v[172:175], v[40:43]
	v_mfma_f32_16x16x32_bf16 v[28:31], v[132:135], v[180:183], v[28:31]
	v_mfma_f32_16x16x32_bf16 v[24:27], v[140:143], v[180:183], v[24:27]
	v_mfma_f32_16x16x32_bf16 v[12:15], v[132:135], v[200:203], v[12:15]
	v_mfma_f32_16x16x32_bf16 v[8:11], v[140:143], v[200:203], v[8:11]
	v_mfma_f32_16x16x32_bf16 v[52:55], v[144:147], v[160:163], v[52:55]
	v_mfma_f32_16x16x32_bf16 v[48:51], v[152:155], v[160:163], v[48:51]
	v_mfma_f32_16x16x32_bf16 v[36:39], v[144:147], v[168:171], v[36:39]
	v_mfma_f32_16x16x32_bf16 v[32:35], v[152:155], v[168:171], v[32:35]
	v_mfma_f32_16x16x32_bf16 v[20:23], v[144:147], v[176:179], v[20:23]
	v_mfma_f32_16x16x32_bf16 v[16:19], v[152:155], v[176:179], v[16:19]
	v_mfma_f32_16x16x32_bf16 v[4:7], v[144:147], v[196:199], v[4:7]
	v_mfma_f32_16x16x32_bf16 v[0:3], v[152:155], v[196:199], v[0:3]
	v_mfma_f32_16x16x32_bf16 v[52:55], v[148:151], v[164:167], v[52:55]
	v_mfma_f32_16x16x32_bf16 v[48:51], v[156:159], v[164:167], v[48:51]
	v_mfma_f32_16x16x32_bf16 v[36:39], v[148:151], v[172:175], v[36:39]
	v_mfma_f32_16x16x32_bf16 v[32:35], v[156:159], v[172:175], v[32:35]
	v_mfma_f32_16x16x32_bf16 v[20:23], v[148:151], v[180:183], v[20:23]
	v_mfma_f32_16x16x32_bf16 v[16:19], v[156:159], v[180:183], v[16:19]
	v_mfma_f32_16x16x32_bf16 v[4:7], v[148:151], v[200:203], v[4:7]
	v_mfma_f32_16x16x32_bf16 v[0:3], v[156:159], v[200:203], v[0:3]
	s_waitcnt vmcnt(4)
	s_barrier
	s_add_i32 s58, s58, 2
	s_add_u32 s2, s2, 0x100
	s_addc_u32 s3, s3, 0
	s_cmpk_gt_u32 s58, 0x7d
	s_cbranch_scc0 .LBB0_1194
	s_setprio 0
	s_and_b64 vcc, exec, s[22:23]
	s_cbranch_vccz .LBB0_1197
	s_barrier

.LBB0_1323:
	s_add_i32 s50, s50, 1
	s_mov_b64 s[34:35], s[0:1]
	s_lshl_b32 s0, s50, 5
	s_add_i32 s0, s0, s38
	s_cmp_lt_i32 s0, 32
	s_mov_b64 s[30:31], s[6:7]
	s_mov_b32 s65, s4
	s_mov_b32 s6, s4
	s_cselect_b64 s[28:29], -1, 0
	s_ashr_i32 s4, s0, 2
	s_and_b64 s[0:1], s[28:29], exec
	s_cselect_b32 s0, s4, s6
	s_cselect_b32 s6, s39, s39
	s_ashr_i32 s7, s6, 31
	s_lshl_b64 s[6:7], s[6:7], 20
	s_add_u32 s6, s40, s6
	s_addc_u32 s7, s41, s7
	s_and_b64 s[36:37], s[28:29], exec
	s_cselect_b32 s66, s7, s31
	s_cselect_b32 s67, s6, s30
	s_ashr_i32 s1, s0, 31
	s_lshl_b64 s[0:1], s[0:1], 20
	s_add_u32 s0, s42, s0
	s_addc_u32 s1, s43, s1
	s_and_b64 s[36:37], s[28:29], exec
	s_cselect_b32 s68, s1, s35
	s_cselect_b32 s69, s0, s34
	s_add_u32 s30, s30, 0x80080
	s_addc_u32 s31, s31, 0
	s_add_u32 s70, s34, 0x100
	s_addc_u32 s71, s35, 0
	s_mov_b32 s72, -2
	v_mov_b32_e32 v0, 0
	v_mov_b32_e32 v1, v137
	v_mov_b32_e32 v2, v137
	v_mov_b32_e32 v3, v137
	v_mov_b32_e32 v4, 0
	v_mov_b32_e32 v5, v137
	v_mov_b32_e32 v6, v137
	v_mov_b32_e32 v7, v137
	v_mov_b32_e32 v12, 0
	v_mov_b32_e32 v13, v137
	v_mov_b32_e32 v14, v137
	v_mov_b32_e32 v15, v137
	v_mov_b32_e32 v20, 0
	v_mov_b32_e32 v21, v137
	v_mov_b32_e32 v22, v137
	v_mov_b32_e32 v23, v137
	v_mov_b32_e32 v28, 0
	v_mov_b32_e32 v29, v137
	v_mov_b32_e32 v30, v137
	v_mov_b32_e32 v31, v137
	v_mov_b32_e32 v36, 0
	v_mov_b32_e32 v37, v137
	v_mov_b32_e32 v38, v137
	v_mov_b32_e32 v39, v137
	v_mov_b32_e32 v44, 0
	v_mov_b32_e32 v45, v137
	v_mov_b32_e32 v46, v137
	v_mov_b32_e32 v47, v137
	v_mov_b32_e32 v52, 0
	v_mov_b32_e32 v53, v137
	v_mov_b32_e32 v54, v137
	v_mov_b32_e32 v55, v137
	v_mov_b32_e32 v8, 0
	v_mov_b32_e32 v9, v137
	v_mov_b32_e32 v10, v137
	v_mov_b32_e32 v11, v137
	v_mov_b32_e32 v16, 0
	v_mov_b32_e32 v17, v137
	v_mov_b32_e32 v18, v137
	v_mov_b32_e32 v19, v137
	v_mov_b32_e32 v24, 0
	v_mov_b32_e32 v25, v137
	v_mov_b32_e32 v26, v137
	v_mov_b32_e32 v27, v137
	v_mov_b32_e32 v32, 0
	v_mov_b32_e32 v33, v137
	v_mov_b32_e32 v34, v137
	v_mov_b32_e32 v35, v137
	v_mov_b32_e32 v40, 0
	v_mov_b32_e32 v41, v137
	v_mov_b32_e32 v42, v137
	v_mov_b32_e32 v43, v137
	v_mov_b32_e32 v48, 0
	v_mov_b32_e32 v49, v137
	v_mov_b32_e32 v50, v137
	v_mov_b32_e32 v51, v137
	v_mov_b32_e32 v56, 0
	v_mov_b32_e32 v57, v137
	v_mov_b32_e32 v58, v137
	v_mov_b32_e32 v59, v137
	v_mov_b32_e32 v60, 0
	v_mov_b32_e32 v61, v137
	v_mov_b32_e32 v62, v137
	v_mov_b32_e32 v63, v137
	v_mov_b32_e32 v64, 0
	v_mov_b32_e32 v65, v137
	v_mov_b32_e32 v66, v137
	v_mov_b32_e32 v67, v137
	v_mov_b32_e32 v68, 0
	v_mov_b32_e32 v69, v137
	v_mov_b32_e32 v70, v137
	v_mov_b32_e32 v71, v137
	v_mov_b32_e32 v76, 0
	v_mov_b32_e32 v77, v137
	v_mov_b32_e32 v78, v137
	v_mov_b32_e32 v79, v137
	v_mov_b32_e32 v84, 0
	v_mov_b32_e32 v85, v137
	v_mov_b32_e32 v86, v137
	v_mov_b32_e32 v87, v137
	v_mov_b32_e32 v92, 0
	v_mov_b32_e32 v93, v137
	v_mov_b32_e32 v94, v137
	v_mov_b32_e32 v95, v137
	v_mov_b32_e32 v100, 0
	v_mov_b32_e32 v101, v137
	v_mov_b32_e32 v102, v137
	v_mov_b32_e32 v103, v137
	v_mov_b32_e32 v108, 0
	v_mov_b32_e32 v109, v137
	v_mov_b32_e32 v110, v137
	v_mov_b32_e32 v111, v137
	v_mov_b32_e32 v116, 0
	v_mov_b32_e32 v117, v137
	v_mov_b32_e32 v118, v137
	v_mov_b32_e32 v119, v137
	v_mov_b32_e32 v72, 0
	v_mov_b32_e32 v73, v137
	v_mov_b32_e32 v74, v137
	v_mov_b32_e32 v75, v137
	v_mov_b32_e32 v80, 0
	v_mov_b32_e32 v81, v137
	v_mov_b32_e32 v82, v137
	v_mov_b32_e32 v83, v137
	v_mov_b32_e32 v88, 0
	v_mov_b32_e32 v89, v137
	v_mov_b32_e32 v90, v137
	v_mov_b32_e32 v91, v137
	v_mov_b32_e32 v96, 0
	v_mov_b32_e32 v97, v137
	v_mov_b32_e32 v98, v137
	v_mov_b32_e32 v99, v137
	v_mov_b32_e32 v104, 0
	v_mov_b32_e32 v105, v137
	v_mov_b32_e32 v106, v137
	v_mov_b32_e32 v107, v137
	v_mov_b32_e32 v112, 0
	v_mov_b32_e32 v113, v137
	v_mov_b32_e32 v114, v137
	v_mov_b32_e32 v115, v137
	v_mov_b32_e32 v120, 0
	v_mov_b32_e32 v121, v137
	v_mov_b32_e32 v122, v137
	v_mov_b32_e32 v123, v137
	v_mov_b32_e32 v124, 0
	v_mov_b32_e32 v125, v137
	v_mov_b32_e32 v126, v137
	v_mov_b32_e32 v127, v137
	s_lshr_b32 s101, s88, 2
	s_cmp_lg_u32 s101, 1
	s_cbranch_scc1 .Lprio_skip9
	s_setprio 1
.Lprio_skip9:
.LBB0_1324:
	ds_read_b128 v[140:143], v148
	ds_read_b128 v[154:157], v148 offset:1024
	ds_read_b128 v[158:161], v148 offset:2048
	ds_read_b128 v[162:165], v148 offset:3072
	ds_read_b128 v[166:169], v149
	ds_read_b128 v[170:173], v149 offset:1024
	ds_read_b128 v[174:177], v149 offset:2048
	ds_read_b128 v[178:181], v149 offset:3072
	s_add_u32 s34, s30, 0xfff80080
	s_addc_u32 s35, s31, -1
	s_cmp_eq_u32 s72, 28
	s_cselect_b32 s37, s66, s35
	s_cselect_b32 s36, s67, s34
	s_cselect_b32 s35, s68, s71
	s_cselect_b32 s34, s69, s70
	s_sub_u32 s98, s30, 0x80000
	s_subb_u32 s99, s31, 0
	s_add_i32 m0, s85, 0x8000
	ds_read_b128 v[182:185], v150
	ds_read_b128 v[186:189], v150 offset:1024
	ds_read_b128 v[190:193], v150 offset:2048
	ds_read_b128 v[194:197], v150 offset:3072
	ds_read_b128 v[198:201], v150 offset:4096
	ds_read_b128 v[202:205], v150 offset:5120
	ds_read_b128 v[206:209], v150 offset:6144
	ds_read_b128 v[210:213], v150 offset:7168
	global_load_lds_dwordx4 v222, s[98:99]
	s_add_u32 s98, s98, 0x20000
	s_addc_u32 s99, s99, 0
	s_add_i32 m0, s85, 0x9000
	s_nop 0
	global_load_lds_dwordx4 v222, s[98:99]
	s_add_u32 s98, s98, 0x20000
	s_addc_u32 s99, s99, 0
	s_add_i32 m0, s85, 0xa000
	s_nop 0
	global_load_lds_dwordx4 v222, s[98:99]
	s_add_u32 s98, s98, 0x20000
	s_addc_u32 s99, s99, 0
	s_add_i32 m0, s85, 0xb000
	s_nop 0
	global_load_lds_dwordx4 v222, s[98:99]
	s_waitcnt vmcnt(8)
	s_waitcnt lgkmcnt(0)
	s_barrier
	s_waitcnt lgkmcnt(0)
	v_mfma_f32_16x16x32_bf16 v[124:127], v[140:143], v[182:185], v[124:127]
	v_mfma_f32_16x16x32_bf16 v[120:123], v[158:161], v[182:185], v[120:123]
	v_mfma_f32_16x16x32_bf16 v[112:115], v[140:143], v[190:193], v[112:115]
	v_mfma_f32_16x16x32_bf16 v[104:107], v[158:161], v[190:193], v[104:107]
	v_mfma_f32_16x16x32_bf16 v[96:99], v[140:143], v[198:201], v[96:99]
	v_mfma_f32_16x16x32_bf16 v[88:91], v[158:161], v[198:201], v[88:91]
	v_mfma_f32_16x16x32_bf16 v[80:83], v[140:143], v[206:209], v[80:83]
	v_mfma_f32_16x16x32_bf16 v[72:75], v[158:161], v[206:209], v[72:75]
	v_mfma_f32_16x16x32_bf16 v[124:127], v[154:157], v[186:189], v[124:127]
	v_mfma_f32_16x16x32_bf16 v[120:123], v[162:165], v[186:189], v[120:123]
	v_mfma_f32_16x16x32_bf16 v[112:115], v[154:157], v[194:197], v[112:115]
	v_mfma_f32_16x16x32_bf16 v[104:107], v[162:165], v[194:197], v[104:107]
	v_mfma_f32_16x16x32_bf16 v[96:99], v[154:157], v[202:205], v[96:99]
	v_mfma_f32_16x16x32_bf16 v[88:91], v[162:165], v[202:205], v[88:91]
	v_mfma_f32_16x16x32_bf16 v[80:83], v[154:157], v[210:213], v[80:83]
	v_mfma_f32_16x16x32_bf16 v[72:75], v[162:165], v[210:213], v[72:75]
	v_mfma_f32_16x16x32_bf16 v[116:119], v[166:169], v[182:185], v[116:119]
	v_mfma_f32_16x16x32_bf16 v[108:111], v[174:177], v[182:185], v[108:111]
	v_mfma_f32_16x16x32_bf16 v[100:103], v[166:169], v[190:193], v[100:103]
	v_mfma_f32_16x16x32_bf16 v[92:95], v[174:177], v[190:193], v[92:95]
	v_mfma_f32_16x16x32_bf16 v[84:87], v[166:169], v[198:201], v[84:87]
	v_mfma_f32_16x16x32_bf16 v[76:79], v[174:177], v[198:201], v[76:79]
	v_mfma_f32_16x16x32_bf16 v[68:71], v[166:169], v[206:209], v[68:71]
	v_mfma_f32_16x16x32_bf16 v[64:67], v[174:177], v[206:209], v[64:67]
	v_mfma_f32_16x16x32_bf16 v[116:119], v[170:173], v[186:189], v[116:119]
	v_mfma_f32_16x16x32_bf16 v[108:111], v[178:181], v[186:189], v[108:111]
	v_mfma_f32_16x16x32_bf16 v[100:103], v[170:173], v[194:197], v[100:103]
	v_mfma_f32_16x16x32_bf16 v[92:95], v[178:181], v[194:197], v[92:95]
	v_mfma_f32_16x16x32_bf16 v[84:87], v[170:173], v[202:205], v[84:87]
	v_mfma_f32_16x16x32_bf16 v[76:79], v[178:181], v[202:205], v[76:79]
	v_mfma_f32_16x16x32_bf16 v[68:71], v[170:173], v[210:213], v[68:71]
	v_mfma_f32_16x16x32_bf16 v[64:67], v[178:181], v[210:213], v[64:67]
	s_barrier
	s_add_i32 s73, s56, s5
	v_lshl_add_u64 v[144:145], s[34:35], 0, v[130:131]
	s_mov_b32 m0, s73
	ds_read_b128 v[182:185], v150 offset:16384
	ds_read_b128 v[186:189], v150 offset:17408
	ds_read_b128 v[190:193], v150 offset:18432
	ds_read_b128 v[194:197], v150 offset:19456
	ds_read_b128 v[198:201], v150 offset:20480
	ds_read_b128 v[202:205], v150 offset:21504
	ds_read_b128 v[206:209], v150 offset:22528
	ds_read_b128 v[210:213], v150 offset:23552
	global_load_lds_dwordx4 v[144:145], off
	s_add_i32 m0, s73, 0x2000
	s_add_u32 s74, s34, 0x80000
	v_lshl_add_u64 v[214:215], s[34:35], 0, v[134:135]
	s_addc_u32 s75, s35, 0
	s_add_i32 s73, s57, s5
	global_load_lds_dwordx4 v[214:215], off
	v_lshl_add_u64 v[216:217], s[74:75], 0, v[130:131]
	s_mov_b32 m0, s73
	global_load_lds_dwordx4 v[216:217], off
	v_lshl_add_u64 v[216:217], s[74:75], 0, v[134:135]
	s_add_i32 m0, s73, 0x2000
	s_nop 0
	global_load_lds_dwordx4 v[216:217], off
	s_waitcnt vmcnt(8)
	s_waitcnt lgkmcnt(0)
	s_barrier
	s_waitcnt lgkmcnt(0)
	v_mfma_f32_16x16x32_bf16 v[60:63], v[140:143], v[182:185], v[60:63]
	v_mfma_f32_16x16x32_bf16 v[56:59], v[158:161], v[182:185], v[56:59]
	v_mfma_f32_16x16x32_bf16 v[48:51], v[140:143], v[190:193], v[48:51]
	v_mfma_f32_16x16x32_bf16 v[40:43], v[158:161], v[190:193], v[40:43]
	v_mfma_f32_16x16x32_bf16 v[32:35], v[140:143], v[198:201], v[32:35]
	v_mfma_f32_16x16x32_bf16 v[24:27], v[158:161], v[198:201], v[24:27]
	v_mfma_f32_16x16x32_bf16 v[16:19], v[140:143], v[206:209], v[16:19]
	v_mfma_f32_16x16x32_bf16 v[8:11], v[158:161], v[206:209], v[8:11]
	v_mfma_f32_16x16x32_bf16 v[60:63], v[154:157], v[186:189], v[60:63]
	v_mfma_f32_16x16x32_bf16 v[56:59], v[162:165], v[186:189], v[56:59]
	v_mfma_f32_16x16x32_bf16 v[48:51], v[154:157], v[194:197], v[48:51]
	v_mfma_f32_16x16x32_bf16 v[40:43], v[162:165], v[194:197], v[40:43]
	v_mfma_f32_16x16x32_bf16 v[32:35], v[154:157], v[202:205], v[32:35]
	v_mfma_f32_16x16x32_bf16 v[24:27], v[162:165], v[202:205], v[24:27]
	v_mfma_f32_16x16x32_bf16 v[16:19], v[154:157], v[210:213], v[16:19]
	v_mfma_f32_16x16x32_bf16 v[8:11], v[162:165], v[210:213], v[8:11]
	v_mfma_f32_16x16x32_bf16 v[52:55], v[166:169], v[182:185], v[52:55]
	v_mfma_f32_16x16x32_bf16 v[44:47], v[174:177], v[182:185], v[44:47]
	v_mfma_f32_16x16x32_bf16 v[36:39], v[166:169], v[190:193], v[36:39]
	v_mfma_f32_16x16x32_bf16 v[28:31], v[174:177], v[190:193], v[28:31]
	v_mfma_f32_16x16x32_bf16 v[20:23], v[166:169], v[198:201], v[20:23]
	v_mfma_f32_16x16x32_bf16 v[12:15], v[174:177], v[198:201], v[12:15]
	v_mfma_f32_16x16x32_bf16 v[4:7], v[166:169], v[206:209], v[4:7]
	v_mfma_f32_16x16x32_bf16 v[0:3], v[174:177], v[206:209], v[0:3]
	v_mfma_f32_16x16x32_bf16 v[52:55], v[170:173], v[186:189], v[52:55]
	v_mfma_f32_16x16x32_bf16 v[44:47], v[178:181], v[186:189], v[44:47]
	v_mfma_f32_16x16x32_bf16 v[36:39], v[170:173], v[194:197], v[36:39]
	v_mfma_f32_16x16x32_bf16 v[28:31], v[178:181], v[194:197], v[28:31]
	v_mfma_f32_16x16x32_bf16 v[20:23], v[170:173], v[202:205], v[20:23]
	v_mfma_f32_16x16x32_bf16 v[12:15], v[178:181], v[202:205], v[12:15]
	v_mfma_f32_16x16x32_bf16 v[4:7], v[170:173], v[210:213], v[4:7]
	v_mfma_f32_16x16x32_bf16 v[0:3], v[178:181], v[210:213], v[0:3]
	s_waitcnt vmcnt(4)
	s_barrier
	ds_read_b128 v[140:143], v151
	ds_read_b128 v[154:157], v151 offset:1024
	ds_read_b128 v[158:161], v151 offset:2048
	ds_read_b128 v[162:165], v151 offset:3072
	ds_read_b128 v[166:169], v152
	ds_read_b128 v[170:173], v152 offset:1024
	ds_read_b128 v[174:177], v152 offset:2048
	ds_read_b128 v[178:181], v152 offset:3072
	s_mov_b32 s98, s36
	s_mov_b32 s99, s37
	s_add_i32 m0, s85, 0
	ds_read_b128 v[182:185], v150 offset:32768
	ds_read_b128 v[186:189], v150 offset:33792
	ds_read_b128 v[190:193], v150 offset:34816
	ds_read_b128 v[194:197], v150 offset:35840
	ds_read_b128 v[198:201], v150 offset:36864
	ds_read_b128 v[202:205], v150 offset:37888
	ds_read_b128 v[206:209], v150 offset:38912
	ds_read_b128 v[210:213], v150 offset:39936
	global_load_lds_dwordx4 v222, s[98:99]
	s_add_u32 s98, s98, 0x20000
	s_addc_u32 s99, s99, 0
	s_add_i32 m0, s85, 0x1000
	s_nop 0
	global_load_lds_dwordx4 v222, s[98:99]
	s_add_u32 s98, s98, 0x20000
	s_addc_u32 s99, s99, 0
	s_add_i32 m0, s85, 0x2000
	s_nop 0
	global_load_lds_dwordx4 v222, s[98:99]
	s_add_u32 s98, s98, 0x20000
	s_addc_u32 s99, s99, 0
	s_add_i32 m0, s85, 0x3000
	s_nop 0
	global_load_lds_dwordx4 v222, s[98:99]
	s_waitcnt vmcnt(8)
	s_waitcnt lgkmcnt(0)
	s_barrier
	s_waitcnt lgkmcnt(0)
	v_mfma_f32_16x16x32_bf16 v[124:127], v[140:143], v[182:185], v[124:127]
	v_mfma_f32_16x16x32_bf16 v[120:123], v[158:161], v[182:185], v[120:123]
	v_mfma_f32_16x16x32_bf16 v[112:115], v[140:143], v[190:193], v[112:115]
	v_mfma_f32_16x16x32_bf16 v[104:107], v[158:161], v[190:193], v[104:107]
	v_mfma_f32_16x16x32_bf16 v[96:99], v[140:143], v[198:201], v[96:99]
	v_mfma_f32_16x16x32_bf16 v[88:91], v[158:161], v[198:201], v[88:91]
	v_mfma_f32_16x16x32_bf16 v[80:83], v[140:143], v[206:209], v[80:83]
	v_mfma_f32_16x16x32_bf16 v[72:75], v[158:161], v[206:209], v[72:75]
	v_mfma_f32_16x16x32_bf16 v[124:127], v[154:157], v[186:189], v[124:127]
	v_mfma_f32_16x16x32_bf16 v[120:123], v[162:165], v[186:189], v[120:123]
	v_mfma_f32_16x16x32_bf16 v[112:115], v[154:157], v[194:197], v[112:115]
	v_mfma_f32_16x16x32_bf16 v[104:107], v[162:165], v[194:197], v[104:107]
	v_mfma_f32_16x16x32_bf16 v[96:99], v[154:157], v[202:205], v[96:99]
	v_mfma_f32_16x16x32_bf16 v[88:91], v[162:165], v[202:205], v[88:91]
	v_mfma_f32_16x16x32_bf16 v[80:83], v[154:157], v[210:213], v[80:83]
	v_mfma_f32_16x16x32_bf16 v[72:75], v[162:165], v[210:213], v[72:75]
	v_mfma_f32_16x16x32_bf16 v[116:119], v[166:169], v[182:185], v[116:119]
	v_mfma_f32_16x16x32_bf16 v[108:111], v[174:177], v[182:185], v[108:111]
	v_mfma_f32_16x16x32_bf16 v[100:103], v[166:169], v[190:193], v[100:103]
	v_mfma_f32_16x16x32_bf16 v[92:95], v[174:177], v[190:193], v[92:95]
	v_mfma_f32_16x16x32_bf16 v[84:87], v[166:169], v[198:201], v[84:87]
	v_mfma_f32_16x16x32_bf16 v[76:79], v[174:177], v[198:201], v[76:79]
	v_mfma_f32_16x16x32_bf16 v[68:71], v[166:169], v[206:209], v[68:71]
	v_mfma_f32_16x16x32_bf16 v[64:67], v[174:177], v[206:209], v[64:67]
	v_mfma_f32_16x16x32_bf16 v[116:119], v[170:173], v[186:189], v[116:119]
	v_mfma_f32_16x16x32_bf16 v[108:111], v[178:181], v[186:189], v[108:111]
	v_mfma_f32_16x16x32_bf16 v[100:103], v[170:173], v[194:197], v[100:103]
	v_mfma_f32_16x16x32_bf16 v[92:95], v[178:181], v[194:197], v[92:95]
	v_mfma_f32_16x16x32_bf16 v[84:87], v[170:173], v[202:205], v[84:87]
	v_mfma_f32_16x16x32_bf16 v[76:79], v[178:181], v[202:205], v[76:79]
	v_mfma_f32_16x16x32_bf16 v[68:71], v[170:173], v[210:213], v[68:71]
	v_mfma_f32_16x16x32_bf16 v[64:67], v[178:181], v[210:213], v[64:67]
	s_barrier
	s_add_i32 s36, s58, s5
	v_lshl_add_u64 v[144:145], v[144:145], 0, s[10:11]
	s_mov_b32 m0, s36
	ds_read_b128 v[182:185], v150 offset:49152
	ds_read_b128 v[186:189], v150 offset:50176
	ds_read_b128 v[190:193], v150 offset:51200
	ds_read_b128 v[194:197], v150 offset:52224
	ds_read_b128 v[198:201], v150 offset:53248
	ds_read_b128 v[202:205], v150 offset:54272
	ds_read_b128 v[206:209], v150 offset:55296
	ds_read_b128 v[210:213], v150 offset:56320
	global_load_lds_dwordx4 v[144:145], off
	s_add_i32 m0, s36, 0x2000
	s_add_u32 s34, s34, 0x80080
	v_lshl_add_u64 v[144:145], v[214:215], 0, s[10:11]
	s_addc_u32 s35, s35, 0
	s_add_i32 s36, s59, s5
	global_load_lds_dwordx4 v[144:145], off
	v_lshl_add_u64 v[144:145], s[34:35], 0, v[130:131]
	s_mov_b32 m0, s36
	s_nop 0
	global_load_lds_dwordx4 v[144:145], off
	v_lshl_add_u64 v[144:145], s[34:35], 0, v[134:135]
	s_add_i32 m0, s36, 0x2000
	s_nop 0
	global_load_lds_dwordx4 v[144:145], off
	s_waitcnt vmcnt(8)
	s_waitcnt lgkmcnt(0)
	s_barrier
	s_waitcnt lgkmcnt(0)
	v_mfma_f32_16x16x32_bf16 v[60:63], v[140:143], v[182:185], v[60:63]
	v_mfma_f32_16x16x32_bf16 v[56:59], v[158:161], v[182:185], v[56:59]
	v_mfma_f32_16x16x32_bf16 v[48:51], v[140:143], v[190:193], v[48:51]
	v_mfma_f32_16x16x32_bf16 v[40:43], v[158:161], v[190:193], v[40:43]
	v_mfma_f32_16x16x32_bf16 v[32:35], v[140:143], v[198:201], v[32:35]
	v_mfma_f32_16x16x32_bf16 v[24:27], v[158:161], v[198:201], v[24:27]
	v_mfma_f32_16x16x32_bf16 v[16:19], v[140:143], v[206:209], v[16:19]
	v_mfma_f32_16x16x32_bf16 v[8:11], v[158:161], v[206:209], v[8:11]
	v_mfma_f32_16x16x32_bf16 v[60:63], v[154:157], v[186:189], v[60:63]
	v_mfma_f32_16x16x32_bf16 v[56:59], v[162:165], v[186:189], v[56:59]
	v_mfma_f32_16x16x32_bf16 v[48:51], v[154:157], v[194:197], v[48:51]
	v_mfma_f32_16x16x32_bf16 v[40:43], v[162:165], v[194:197], v[40:43]
	v_mfma_f32_16x16x32_bf16 v[32:35], v[154:157], v[202:205], v[32:35]
	v_mfma_f32_16x16x32_bf16 v[24:27], v[162:165], v[202:205], v[24:27]
	v_mfma_f32_16x16x32_bf16 v[16:19], v[154:157], v[210:213], v[16:19]
	v_mfma_f32_16x16x32_bf16 v[8:11], v[162:165], v[210:213], v[8:11]
	v_mfma_f32_16x16x32_bf16 v[52:55], v[166:169], v[182:185], v[52:55]
	v_mfma_f32_16x16x32_bf16 v[44:47], v[174:177], v[182:185], v[44:47]
	v_mfma_f32_16x16x32_bf16 v[36:39], v[166:169], v[190:193], v[36:39]
	v_mfma_f32_16x16x32_bf16 v[28:31], v[174:177], v[190:193], v[28:31]
	v_mfma_f32_16x16x32_bf16 v[20:23], v[166:169], v[198:201], v[20:23]
	v_mfma_f32_16x16x32_bf16 v[12:15], v[174:177], v[198:201], v[12:15]
	v_mfma_f32_16x16x32_bf16 v[4:7], v[166:169], v[206:209], v[4:7]
	v_mfma_f32_16x16x32_bf16 v[0:3], v[174:177], v[206:209], v[0:3]
	v_mfma_f32_16x16x32_bf16 v[52:55], v[170:173], v[186:189], v[52:55]
	v_mfma_f32_16x16x32_bf16 v[44:47], v[178:181], v[186:189], v[44:47]
	v_mfma_f32_16x16x32_bf16 v[36:39], v[170:173], v[194:197], v[36:39]
	v_mfma_f32_16x16x32_bf16 v[28:31], v[178:181], v[194:197], v[28:31]
	v_mfma_f32_16x16x32_bf16 v[20:23], v[170:173], v[202:205], v[20:23]
	v_mfma_f32_16x16x32_bf16 v[12:15], v[178:181], v[202:205], v[12:15]
	v_mfma_f32_16x16x32_bf16 v[4:7], v[170:173], v[210:213], v[4:7]
	v_mfma_f32_16x16x32_bf16 v[0:3], v[178:181], v[210:213], v[0:3]
	s_waitcnt vmcnt(4)
	s_barrier
	s_add_i32 s72, s72, 2
	s_add_u32 s30, s30, 0x100
	s_addc_u32 s31, s31, 0
	s_add_u32 s70, s70, 0x100
	s_addc_u32 s71, s71, 0
	s_cmp_gt_u32 s72, 29
	s_cbranch_scc0 .LBB0_1324
	s_setprio 0
	s_and_b64 vcc, exec, s[12:13]
	s_cbranch_vccz .LBB0_1327
	s_barrier

.LBB0_1525:
	s_add_i32 s51, s51, 1
	s_mov_b64 s[0:1], s[10:11]
	s_mov_b32 s22, s6
	s_mov_b32 s10, s6
	s_lshl_b32 s6, s51, 5
	s_add_i32 s6, s6, s34
	s_cmp_lt_i32 s6, 64
	s_cselect_b64 s[28:29], -1, 0
	s_ashr_i32 s6, s6, 2
	s_mov_b64 s[2:3], s[8:9]
	s_and_b64 s[8:9], s[28:29], exec
	s_cselect_b32 s8, s6, s10
	s_cselect_b32 s10, s40, s40
	s_ashr_i32 s11, s10, 31
	s_lshl_b64 s[10:11], s[10:11], 20
	s_add_u32 s10, s35, s10
	s_addc_u32 s11, s36, s11
	s_and_b64 s[30:31], s[28:29], exec
	s_cselect_b32 s52, s11, s1
	s_cselect_b32 s53, s10, s0
	s_ashr_i32 s9, s8, 31
	s_lshl_b64 s[8:9], s[8:9], 20
	s_add_u32 s8, s37, s8
	s_addc_u32 s9, s38, s9
	s_and_b64 s[30:31], s[28:29], exec
	s_cselect_b32 s54, s9, s3
	s_cselect_b32 s55, s8, s2
	s_add_u32 s0, s0, 0x80080
	s_addc_u32 s1, s1, 0
	s_add_u32 s56, s2, 0x100
	v_mov_b32_e32 v4, 0
	s_addc_u32 s57, s3, 0
	s_mov_b32 s58, -2
	v_mov_b32_e32 v5, v4
	v_mov_b32_e32 v6, v4
	v_mov_b32_e32 v7, v4
	v_mov_b32_e32 v0, v4
	s_waitcnt lgkmcnt(0)
	v_mov_b32_e32 v1, v4
	v_mov_b32_e32 v2, v4
	v_mov_b32_e32 v3, v4
	v_mov_b32_e32 v20, v4
	v_mov_b32_e32 v21, v4
	v_mov_b32_e32 v22, v4
	v_mov_b32_e32 v23, v4
	v_mov_b32_e32 v16, v4
	v_mov_b32_e32 v17, v4
	v_mov_b32_e32 v18, v4
	v_mov_b32_e32 v19, v4
	v_mov_b32_e32 v36, v4
	v_mov_b32_e32 v37, v4
	v_mov_b32_e32 v38, v4
	v_mov_b32_e32 v39, v4
	v_mov_b32_e32 v32, v4
	v_mov_b32_e32 v33, v4
	v_mov_b32_e32 v34, v4
	v_mov_b32_e32 v35, v4
	v_mov_b32_e32 v52, v4
	v_mov_b32_e32 v53, v4
	v_mov_b32_e32 v54, v4
	v_mov_b32_e32 v55, v4
	v_mov_b32_e32 v48, v4
	v_mov_b32_e32 v49, v4
	v_mov_b32_e32 v50, v4
	v_mov_b32_e32 v51, v4
	v_mov_b32_e32 v12, v4
	v_mov_b32_e32 v13, v4
	v_mov_b32_e32 v14, v4
	v_mov_b32_e32 v15, v4
	v_mov_b32_e32 v8, v4
	v_mov_b32_e32 v9, v4
	v_mov_b32_e32 v10, v4
	v_mov_b32_e32 v11, v4
	v_mov_b32_e32 v28, v4
	v_mov_b32_e32 v29, v4
	v_mov_b32_e32 v30, v4
	v_mov_b32_e32 v31, v4
	v_mov_b32_e32 v24, v4
	v_mov_b32_e32 v25, v4
	v_mov_b32_e32 v26, v4
	v_mov_b32_e32 v27, v4
	v_mov_b32_e32 v44, v4
	v_mov_b32_e32 v45, v4
	v_mov_b32_e32 v46, v4
	v_mov_b32_e32 v47, v4
	v_mov_b32_e32 v40, v4
	v_mov_b32_e32 v41, v4
	v_mov_b32_e32 v42, v4
	v_mov_b32_e32 v43, v4
	v_mov_b32_e32 v60, v4
	v_mov_b32_e32 v61, v4
	v_mov_b32_e32 v62, v4
	v_mov_b32_e32 v63, v4
	v_mov_b32_e32 v56, v4
	v_mov_b32_e32 v57, v4
	v_mov_b32_e32 v58, v4
	v_mov_b32_e32 v59, v4
	v_mov_b32_e32 v68, v4
	v_mov_b32_e32 v69, v4
	v_mov_b32_e32 v70, v4
	v_mov_b32_e32 v71, v4
	v_mov_b32_e32 v64, v4
	v_mov_b32_e32 v65, v4
	v_mov_b32_e32 v66, v4
	v_mov_b32_e32 v67, v4
	v_mov_b32_e32 v96, v4
	v_mov_b32_e32 v97, v4
	v_mov_b32_e32 v98, v4
	v_mov_b32_e32 v99, v4
	v_mov_b32_e32 v88, v4
	v_mov_b32_e32 v89, v4
	v_mov_b32_e32 v90, v4
	v_mov_b32_e32 v91, v4
	v_mov_b32_e32 v116, v4
	v_mov_b32_e32 v117, v4
	v_mov_b32_e32 v118, v4
	v_mov_b32_e32 v119, v4
	v_mov_b32_e32 v112, v4
	v_mov_b32_e32 v113, v4
	v_mov_b32_e32 v114, v4
	v_mov_b32_e32 v115, v4
	v_mov_b32_e32 v132, v4
	v_mov_b32_e32 v133, v4
	v_mov_b32_e32 v134, v4
	v_mov_b32_e32 v135, v4
	v_mov_b32_e32 v128, v4
	v_mov_b32_e32 v129, v4
	v_mov_b32_e32 v130, v4
	v_mov_b32_e32 v131, v4
	v_mov_b32_e32 v76, v4
	v_mov_b32_e32 v77, v4
	v_mov_b32_e32 v78, v4
	v_mov_b32_e32 v79, v4
	v_mov_b32_e32 v72, v4
	v_mov_b32_e32 v73, v4
	v_mov_b32_e32 v74, v4
	v_mov_b32_e32 v75, v4
	v_mov_b32_e32 v108, v4
	v_mov_b32_e32 v109, v4
	v_mov_b32_e32 v110, v4
	v_mov_b32_e32 v111, v4
	v_mov_b32_e32 v104, v4
	v_mov_b32_e32 v105, v4
	v_mov_b32_e32 v106, v4
	v_mov_b32_e32 v107, v4
	v_mov_b32_e32 v124, v4
	v_mov_b32_e32 v125, v4
	v_mov_b32_e32 v126, v4
	v_mov_b32_e32 v127, v4
	v_mov_b32_e32 v120, v4
	v_mov_b32_e32 v121, v4
	v_mov_b32_e32 v122, v4
	v_mov_b32_e32 v123, v4
	v_mov_b32_e32 v140, v4
	v_mov_b32_e32 v141, v4
	v_mov_b32_e32 v142, v4
	v_mov_b32_e32 v143, v4
	v_mov_b32_e32 v136, v4
	v_mov_b32_e32 v137, v4
	v_mov_b32_e32 v138, v4
	v_mov_b32_e32 v139, v4
	s_lshr_b32 s101, s88, 2
	s_cmp_lg_u32 s101, 1
	s_cbranch_scc1 .Lprio_skip10
	s_setprio 1
.Lprio_skip10:
.LBB0_1526:
	ds_read_b128 v[80:83], v185
	ds_read_b128 v[84:87], v185 offset:1024
	ds_read_b128 v[92:95], v185 offset:2048
	ds_read_b128 v[100:103], v185 offset:3072
	ds_read_b128 v[152:155], v186
	ds_read_b128 v[156:159], v186 offset:1024
	ds_read_b128 v[160:163], v186 offset:2048
	ds_read_b128 v[164:167], v186 offset:3072
	s_add_u32 s2, s0, 0xfff80080
	s_addc_u32 s3, s1, -1
	s_cmp_eq_u32 s58, 28
	s_cselect_b32 s31, s52, s3
	s_cselect_b32 s30, s53, s2
	s_cselect_b32 s3, s54, s57
	s_cselect_b32 s2, s55, s56
	s_sub_u32 s98, s0, 0x80000
	s_subb_u32 s99, s1, 0
	s_add_i32 m0, s85, 0x8000
	ds_read_b128 v[168:171], v187
	ds_read_b128 v[172:175], v187 offset:1024
	ds_read_b128 v[176:179], v187 offset:2048
	ds_read_b128 v[190:193], v187 offset:3072
	ds_read_b128 v[194:197], v187 offset:4096
	ds_read_b128 v[198:201], v187 offset:5120
	ds_read_b128 v[202:205], v187 offset:6144
	ds_read_b128 v[206:209], v187 offset:7168
	global_load_lds_dwordx4 v222, s[98:99]
	s_add_u32 s98, s98, 0x20000
	s_addc_u32 s99, s99, 0
	s_add_i32 m0, s85, 0x9000
	s_nop 0
	global_load_lds_dwordx4 v222, s[98:99]
	s_add_u32 s98, s98, 0x20000
	s_addc_u32 s99, s99, 0
	s_add_i32 m0, s85, 0xa000
	s_nop 0
	global_load_lds_dwordx4 v222, s[98:99]
	s_add_u32 s98, s98, 0x20000
	s_addc_u32 s99, s99, 0
	s_add_i32 m0, s85, 0xb000
	s_nop 0
	global_load_lds_dwordx4 v222, s[98:99]
	s_waitcnt vmcnt(8)
	s_waitcnt lgkmcnt(0)
	s_barrier
	s_waitcnt lgkmcnt(0)
	v_mfma_f32_16x16x32_bf16 v[136:139], v[80:83], v[168:171], v[136:139]
	v_mfma_f32_16x16x32_bf16 v[140:143], v[92:95], v[168:171], v[140:143]
	v_mfma_f32_16x16x32_bf16 v[120:123], v[80:83], v[176:179], v[120:123]
	v_mfma_f32_16x16x32_bf16 v[124:127], v[92:95], v[176:179], v[124:127]
	v_mfma_f32_16x16x32_bf16 v[104:107], v[80:83], v[194:197], v[104:107]
	v_mfma_f32_16x16x32_bf16 v[108:111], v[92:95], v[194:197], v[108:111]
	v_mfma_f32_16x16x32_bf16 v[72:75], v[80:83], v[202:205], v[72:75]
	v_mfma_f32_16x16x32_bf16 v[76:79], v[92:95], v[202:205], v[76:79]
	v_mfma_f32_16x16x32_bf16 v[136:139], v[84:87], v[172:175], v[136:139]
	v_mfma_f32_16x16x32_bf16 v[140:143], v[100:103], v[172:175], v[140:143]
	v_mfma_f32_16x16x32_bf16 v[120:123], v[84:87], v[190:193], v[120:123]
	v_mfma_f32_16x16x32_bf16 v[124:127], v[100:103], v[190:193], v[124:127]
	v_mfma_f32_16x16x32_bf16 v[104:107], v[84:87], v[198:201], v[104:107]
	v_mfma_f32_16x16x32_bf16 v[108:111], v[100:103], v[198:201], v[108:111]
	v_mfma_f32_16x16x32_bf16 v[72:75], v[84:87], v[206:209], v[72:75]
	v_mfma_f32_16x16x32_bf16 v[76:79], v[100:103], v[206:209], v[76:79]
	v_mfma_f32_16x16x32_bf16 v[128:131], v[152:155], v[168:171], v[128:131]
	v_mfma_f32_16x16x32_bf16 v[132:135], v[160:163], v[168:171], v[132:135]
	v_mfma_f32_16x16x32_bf16 v[112:115], v[152:155], v[176:179], v[112:115]
	v_mfma_f32_16x16x32_bf16 v[116:119], v[160:163], v[176:179], v[116:119]
	v_mfma_f32_16x16x32_bf16 v[88:91], v[152:155], v[194:197], v[88:91]
	v_mfma_f32_16x16x32_bf16 v[96:99], v[160:163], v[194:197], v[96:99]
	v_mfma_f32_16x16x32_bf16 v[64:67], v[152:155], v[202:205], v[64:67]
	v_mfma_f32_16x16x32_bf16 v[68:71], v[160:163], v[202:205], v[68:71]
	v_mfma_f32_16x16x32_bf16 v[128:131], v[156:159], v[172:175], v[128:131]
	v_mfma_f32_16x16x32_bf16 v[132:135], v[164:167], v[172:175], v[132:135]
	v_mfma_f32_16x16x32_bf16 v[112:115], v[156:159], v[190:193], v[112:115]
	v_mfma_f32_16x16x32_bf16 v[116:119], v[164:167], v[190:193], v[116:119]
	v_mfma_f32_16x16x32_bf16 v[88:91], v[156:159], v[198:201], v[88:91]
	v_mfma_f32_16x16x32_bf16 v[96:99], v[164:167], v[198:201], v[96:99]
	v_mfma_f32_16x16x32_bf16 v[64:67], v[156:159], v[206:209], v[64:67]
	v_mfma_f32_16x16x32_bf16 v[68:71], v[164:167], v[206:209], v[68:71]
	s_barrier
	s_add_i32 s59, s49, s39
	v_lshl_add_u64 v[180:181], s[2:3], 0, v[146:147]
	s_mov_b32 m0, s59
	ds_read_b128 v[168:171], v187 offset:16384
	ds_read_b128 v[172:175], v187 offset:17408
	ds_read_b128 v[176:179], v187 offset:18432
	ds_read_b128 v[190:193], v187 offset:19456
	ds_read_b128 v[194:197], v187 offset:20480
	ds_read_b128 v[198:201], v187 offset:21504
	ds_read_b128 v[202:205], v187 offset:22528
	ds_read_b128 v[206:209], v187 offset:23552
	global_load_lds_dwordx4 v[180:181], off
	s_add_i32 m0, s59, 0x2000
	s_add_u32 s60, s2, 0x80000
	v_lshl_add_u64 v[210:211], s[2:3], 0, v[144:145]
	s_addc_u32 s61, s3, 0
	s_add_i32 s59, s50, s39
	global_load_lds_dwordx4 v[210:211], off
	v_lshl_add_u64 v[212:213], s[60:61], 0, v[146:147]
	s_mov_b32 m0, s59
	global_load_lds_dwordx4 v[212:213], off
	v_lshl_add_u64 v[212:213], s[60:61], 0, v[144:145]
	s_add_i32 m0, s59, 0x2000
	s_nop 0
	global_load_lds_dwordx4 v[212:213], off
	s_waitcnt vmcnt(8)
	s_waitcnt lgkmcnt(0)
	s_barrier
	s_waitcnt lgkmcnt(0)
	v_mfma_f32_16x16x32_bf16 v[56:59], v[80:83], v[168:171], v[56:59]
	v_mfma_f32_16x16x32_bf16 v[60:63], v[92:95], v[168:171], v[60:63]
	v_mfma_f32_16x16x32_bf16 v[40:43], v[80:83], v[176:179], v[40:43]
	v_mfma_f32_16x16x32_bf16 v[44:47], v[92:95], v[176:179], v[44:47]
	v_mfma_f32_16x16x32_bf16 v[24:27], v[80:83], v[194:197], v[24:27]
	v_mfma_f32_16x16x32_bf16 v[28:31], v[92:95], v[194:197], v[28:31]
	v_mfma_f32_16x16x32_bf16 v[8:11], v[80:83], v[202:205], v[8:11]
	v_mfma_f32_16x16x32_bf16 v[12:15], v[92:95], v[202:205], v[12:15]
	v_mfma_f32_16x16x32_bf16 v[56:59], v[84:87], v[172:175], v[56:59]
	v_mfma_f32_16x16x32_bf16 v[60:63], v[100:103], v[172:175], v[60:63]
	v_mfma_f32_16x16x32_bf16 v[40:43], v[84:87], v[190:193], v[40:43]
	v_mfma_f32_16x16x32_bf16 v[44:47], v[100:103], v[190:193], v[44:47]
	v_mfma_f32_16x16x32_bf16 v[24:27], v[84:87], v[198:201], v[24:27]
	v_mfma_f32_16x16x32_bf16 v[28:31], v[100:103], v[198:201], v[28:31]
	v_mfma_f32_16x16x32_bf16 v[8:11], v[84:87], v[206:209], v[8:11]
	v_mfma_f32_16x16x32_bf16 v[12:15], v[100:103], v[206:209], v[12:15]
	v_mfma_f32_16x16x32_bf16 v[48:51], v[152:155], v[168:171], v[48:51]
	v_mfma_f32_16x16x32_bf16 v[52:55], v[160:163], v[168:171], v[52:55]
	v_mfma_f32_16x16x32_bf16 v[32:35], v[152:155], v[176:179], v[32:35]
	v_mfma_f32_16x16x32_bf16 v[36:39], v[160:163], v[176:179], v[36:39]
	v_mfma_f32_16x16x32_bf16 v[16:19], v[152:155], v[194:197], v[16:19]
	v_mfma_f32_16x16x32_bf16 v[20:23], v[160:163], v[194:197], v[20:23]
	v_mfma_f32_16x16x32_bf16 v[0:3], v[152:155], v[202:205], v[0:3]
	v_mfma_f32_16x16x32_bf16 v[4:7], v[160:163], v[202:205], v[4:7]
	v_mfma_f32_16x16x32_bf16 v[48:51], v[156:159], v[172:175], v[48:51]
	v_mfma_f32_16x16x32_bf16 v[52:55], v[164:167], v[172:175], v[52:55]
	v_mfma_f32_16x16x32_bf16 v[32:35], v[156:159], v[190:193], v[32:35]
	v_mfma_f32_16x16x32_bf16 v[36:39], v[164:167], v[190:193], v[36:39]
	v_mfma_f32_16x16x32_bf16 v[16:19], v[156:159], v[198:201], v[16:19]
	v_mfma_f32_16x16x32_bf16 v[20:23], v[164:167], v[198:201], v[20:23]
	v_mfma_f32_16x16x32_bf16 v[0:3], v[156:159], v[206:209], v[0:3]
	v_mfma_f32_16x16x32_bf16 v[4:7], v[164:167], v[206:209], v[4:7]
	s_waitcnt vmcnt(4)
	s_barrier
	s_add_i32 s59, 0, 0x18000
	s_add_i32 s60, 0, 0x1c000
	v_add_u32_e32 v100, s59, v184
	v_add_u32_e32 v164, s60, v184
	ds_read_b128 v[80:83], v100
	ds_read_b128 v[84:87], v100 offset:1024
	ds_read_b128 v[92:95], v100 offset:2048
	ds_read_b128 v[100:103], v100 offset:3072
	ds_read_b128 v[152:155], v164
	ds_read_b128 v[156:159], v164 offset:1024
	ds_read_b128 v[160:163], v164 offset:2048
	ds_read_b128 v[164:167], v164 offset:3072
	s_mov_b32 s98, s30
	s_mov_b32 s99, s31
	s_add_i32 m0, s85, 0
	ds_read_b128 v[168:171], v187 offset:32768
	ds_read_b128 v[172:175], v187 offset:33792
	ds_read_b128 v[176:179], v187 offset:34816
	ds_read_b128 v[190:193], v187 offset:35840
	ds_read_b128 v[194:197], v187 offset:36864
	ds_read_b128 v[198:201], v187 offset:37888
	ds_read_b128 v[202:205], v187 offset:38912
	ds_read_b128 v[206:209], v187 offset:39936
	global_load_lds_dwordx4 v222, s[98:99]
	s_add_u32 s98, s98, 0x20000
	s_addc_u32 s99, s99, 0
	s_add_i32 m0, s85, 0x1000
	s_nop 0
	global_load_lds_dwordx4 v222, s[98:99]
	s_add_u32 s98, s98, 0x20000
	s_addc_u32 s99, s99, 0
	s_add_i32 m0, s85, 0x2000
	s_nop 0
	global_load_lds_dwordx4 v222, s[98:99]
	s_add_u32 s98, s98, 0x20000
	s_addc_u32 s99, s99, 0
	s_add_i32 m0, s85, 0x3000
	s_nop 0
	global_load_lds_dwordx4 v222, s[98:99]
	s_waitcnt vmcnt(8)
	s_waitcnt lgkmcnt(0)
	s_barrier
	s_waitcnt lgkmcnt(0)
	v_mfma_f32_16x16x32_bf16 v[136:139], v[80:83], v[168:171], v[136:139]
	v_mfma_f32_16x16x32_bf16 v[140:143], v[92:95], v[168:171], v[140:143]
	v_mfma_f32_16x16x32_bf16 v[120:123], v[80:83], v[176:179], v[120:123]
	v_mfma_f32_16x16x32_bf16 v[124:127], v[92:95], v[176:179], v[124:127]
	v_mfma_f32_16x16x32_bf16 v[104:107], v[80:83], v[194:197], v[104:107]
	v_mfma_f32_16x16x32_bf16 v[108:111], v[92:95], v[194:197], v[108:111]
	v_mfma_f32_16x16x32_bf16 v[72:75], v[80:83], v[202:205], v[72:75]
	v_mfma_f32_16x16x32_bf16 v[76:79], v[92:95], v[202:205], v[76:79]
	v_mfma_f32_16x16x32_bf16 v[136:139], v[84:87], v[172:175], v[136:139]
	v_mfma_f32_16x16x32_bf16 v[140:143], v[100:103], v[172:175], v[140:143]
	v_mfma_f32_16x16x32_bf16 v[120:123], v[84:87], v[190:193], v[120:123]
	v_mfma_f32_16x16x32_bf16 v[124:127], v[100:103], v[190:193], v[124:127]
	v_mfma_f32_16x16x32_bf16 v[104:107], v[84:87], v[198:201], v[104:107]
	v_mfma_f32_16x16x32_bf16 v[108:111], v[100:103], v[198:201], v[108:111]
	v_mfma_f32_16x16x32_bf16 v[72:75], v[84:87], v[206:209], v[72:75]
	v_mfma_f32_16x16x32_bf16 v[76:79], v[100:103], v[206:209], v[76:79]
	v_mfma_f32_16x16x32_bf16 v[128:131], v[152:155], v[168:171], v[128:131]
	v_mfma_f32_16x16x32_bf16 v[132:135], v[160:163], v[168:171], v[132:135]
	v_mfma_f32_16x16x32_bf16 v[112:115], v[152:155], v[176:179], v[112:115]
	v_mfma_f32_16x16x32_bf16 v[116:119], v[160:163], v[176:179], v[116:119]
	v_mfma_f32_16x16x32_bf16 v[88:91], v[152:155], v[194:197], v[88:91]
	v_mfma_f32_16x16x32_bf16 v[96:99], v[160:163], v[194:197], v[96:99]
	v_mfma_f32_16x16x32_bf16 v[64:67], v[152:155], v[202:205], v[64:67]
	v_mfma_f32_16x16x32_bf16 v[68:71], v[160:163], v[202:205], v[68:71]
	v_mfma_f32_16x16x32_bf16 v[128:131], v[156:159], v[172:175], v[128:131]
	v_mfma_f32_16x16x32_bf16 v[132:135], v[164:167], v[172:175], v[132:135]
	v_mfma_f32_16x16x32_bf16 v[112:115], v[156:159], v[190:193], v[112:115]
	v_mfma_f32_16x16x32_bf16 v[116:119], v[164:167], v[190:193], v[116:119]
	v_mfma_f32_16x16x32_bf16 v[88:91], v[156:159], v[198:201], v[88:91]
	v_mfma_f32_16x16x32_bf16 v[96:99], v[164:167], v[198:201], v[96:99]
	v_mfma_f32_16x16x32_bf16 v[64:67], v[156:159], v[206:209], v[64:67]
	v_mfma_f32_16x16x32_bf16 v[68:71], v[164:167], v[206:209], v[68:71]
	s_barrier
	s_add_i32 s30, s59, s39
	v_lshl_add_u64 v[180:181], v[180:181], 0, s[20:21]
	s_mov_b32 m0, s30
	ds_read_b128 v[168:171], v187 offset:49152
	ds_read_b128 v[172:175], v187 offset:50176
	ds_read_b128 v[176:179], v187 offset:51200
	ds_read_b128 v[190:193], v187 offset:52224
	ds_read_b128 v[194:197], v187 offset:53248
	ds_read_b128 v[198:201], v187 offset:54272
	ds_read_b128 v[202:205], v187 offset:55296
	ds_read_b128 v[206:209], v187 offset:56320
	global_load_lds_dwordx4 v[180:181], off
	s_add_i32 m0, s30, 0x2000
	s_add_u32 s2, s2, 0x80080
	v_lshl_add_u64 v[180:181], v[210:211], 0, s[20:21]
	s_addc_u32 s3, s3, 0
	s_add_i32 s30, s60, s39
	global_load_lds_dwordx4 v[180:181], off
	v_lshl_add_u64 v[180:181], s[2:3], 0, v[146:147]
	s_mov_b32 m0, s30
	s_nop 0
	global_load_lds_dwordx4 v[180:181], off
	v_lshl_add_u64 v[180:181], s[2:3], 0, v[144:145]
	s_add_i32 m0, s30, 0x2000
	s_nop 0
	global_load_lds_dwordx4 v[180:181], off
	s_waitcnt vmcnt(8)
	s_waitcnt lgkmcnt(0)
	s_barrier
	s_waitcnt lgkmcnt(0)
	v_mfma_f32_16x16x32_bf16 v[56:59], v[80:83], v[168:171], v[56:59]
	v_mfma_f32_16x16x32_bf16 v[60:63], v[92:95], v[168:171], v[60:63]
	v_mfma_f32_16x16x32_bf16 v[40:43], v[80:83], v[176:179], v[40:43]
	v_mfma_f32_16x16x32_bf16 v[44:47], v[92:95], v[176:179], v[44:47]
	v_mfma_f32_16x16x32_bf16 v[24:27], v[80:83], v[194:197], v[24:27]
	v_mfma_f32_16x16x32_bf16 v[28:31], v[92:95], v[194:197], v[28:31]
	v_mfma_f32_16x16x32_bf16 v[8:11], v[80:83], v[202:205], v[8:11]
	v_mfma_f32_16x16x32_bf16 v[12:15], v[92:95], v[202:205], v[12:15]
	v_mfma_f32_16x16x32_bf16 v[56:59], v[84:87], v[172:175], v[56:59]
	v_mfma_f32_16x16x32_bf16 v[60:63], v[100:103], v[172:175], v[60:63]
	v_mfma_f32_16x16x32_bf16 v[40:43], v[84:87], v[190:193], v[40:43]
	v_mfma_f32_16x16x32_bf16 v[44:47], v[100:103], v[190:193], v[44:47]
	v_mfma_f32_16x16x32_bf16 v[24:27], v[84:87], v[198:201], v[24:27]
	v_mfma_f32_16x16x32_bf16 v[28:31], v[100:103], v[198:201], v[28:31]
	v_mfma_f32_16x16x32_bf16 v[8:11], v[84:87], v[206:209], v[8:11]
	v_mfma_f32_16x16x32_bf16 v[12:15], v[100:103], v[206:209], v[12:15]
	v_mfma_f32_16x16x32_bf16 v[48:51], v[152:155], v[168:171], v[48:51]
	v_mfma_f32_16x16x32_bf16 v[52:55], v[160:163], v[168:171], v[52:55]
	v_mfma_f32_16x16x32_bf16 v[32:35], v[152:155], v[176:179], v[32:35]
	v_mfma_f32_16x16x32_bf16 v[36:39], v[160:163], v[176:179], v[36:39]
	v_mfma_f32_16x16x32_bf16 v[16:19], v[152:155], v[194:197], v[16:19]
	v_mfma_f32_16x16x32_bf16 v[20:23], v[160:163], v[194:197], v[20:23]
	v_mfma_f32_16x16x32_bf16 v[0:3], v[152:155], v[202:205], v[0:3]
	v_mfma_f32_16x16x32_bf16 v[4:7], v[160:163], v[202:205], v[4:7]
	v_mfma_f32_16x16x32_bf16 v[48:51], v[156:159], v[172:175], v[48:51]
	v_mfma_f32_16x16x32_bf16 v[52:55], v[164:167], v[172:175], v[52:55]
	v_mfma_f32_16x16x32_bf16 v[32:35], v[156:159], v[190:193], v[32:35]
	v_mfma_f32_16x16x32_bf16 v[36:39], v[164:167], v[190:193], v[36:39]
	v_mfma_f32_16x16x32_bf16 v[16:19], v[156:159], v[198:201], v[16:19]
	v_mfma_f32_16x16x32_bf16 v[20:23], v[164:167], v[198:201], v[20:23]
	v_mfma_f32_16x16x32_bf16 v[0:3], v[156:159], v[206:209], v[0:3]
	v_mfma_f32_16x16x32_bf16 v[4:7], v[164:167], v[206:209], v[4:7]
	s_waitcnt vmcnt(4)
	s_barrier
	s_add_i32 s58, s58, 2
	s_add_u32 s0, s0, 0x100
	s_addc_u32 s1, s1, 0
	s_add_u32 s56, s56, 0x100
	s_addc_u32 s57, s57, 0
	s_cmp_gt_u32 s58, 29
	s_cbranch_scc0 .LBB0_1526
	s_setprio 0
	s_and_b64 vcc, exec, s[24:25]
	s_cbranch_vccz .LBB0_1529
	s_barrier

.LBB0_1824:
	s_add_i32 s56, s56, 1
	s_lshl_b32 s2, s56, 5
	s_add_i32 s2, s2, s34
	s_cmp_lt_i32 s2, 32
	s_mov_b32 s20, s4
	s_cselect_b64 s[26:27], -1, 0
	s_ashr_i32 s4, s2, 2
	s_ashr_i32 s5, s4, 31
	s_lshl_b64 s[2:3], s[4:5], 20
	s_mov_b64 s[0:1], s[8:9]
	s_add_u32 s8, s35, s2
	s_addc_u32 s9, s36, s3
	s_and_b64 s[2:3], s[26:27], exec
	v_mov_b32_e32 v0, 0
	s_cselect_b32 s5, s9, s1
	s_cselect_b32 s57, s8, s0
	s_mov_b32 s58, -2
	s_mov_b64 s[2:3], 0x100
	s_waitcnt lgkmcnt(0)
	v_mov_b32_e32 v1, v0
	v_mov_b32_e32 v2, v0
	v_mov_b32_e32 v3, v0
	v_mov_b32_e32 v4, v0
	v_mov_b32_e32 v5, v0
	v_mov_b32_e32 v6, v0
	v_mov_b32_e32 v7, v0
	v_mov_b32_e32 v16, v0
	v_mov_b32_e32 v17, v0
	v_mov_b32_e32 v18, v0
	v_mov_b32_e32 v19, v0
	v_mov_b32_e32 v20, v0
	v_mov_b32_e32 v21, v0
	v_mov_b32_e32 v22, v0
	v_mov_b32_e32 v23, v0
	v_mov_b32_e32 v32, v0
	v_mov_b32_e32 v33, v0
	v_mov_b32_e32 v34, v0
	v_mov_b32_e32 v35, v0
	v_mov_b32_e32 v36, v0
	v_mov_b32_e32 v37, v0
	v_mov_b32_e32 v38, v0
	v_mov_b32_e32 v39, v0
	v_mov_b32_e32 v48, v0
	v_mov_b32_e32 v49, v0
	v_mov_b32_e32 v50, v0
	v_mov_b32_e32 v51, v0
	v_mov_b32_e32 v52, v0
	v_mov_b32_e32 v53, v0
	v_mov_b32_e32 v54, v0
	v_mov_b32_e32 v55, v0
	v_mov_b32_e32 v8, v0
	v_mov_b32_e32 v9, v0
	v_mov_b32_e32 v10, v0
	v_mov_b32_e32 v11, v0
	v_mov_b32_e32 v12, v0
	v_mov_b32_e32 v13, v0
	v_mov_b32_e32 v14, v0
	v_mov_b32_e32 v15, v0
	v_mov_b32_e32 v24, v0
	v_mov_b32_e32 v25, v0
	v_mov_b32_e32 v26, v0
	v_mov_b32_e32 v27, v0
	v_mov_b32_e32 v28, v0
	v_mov_b32_e32 v29, v0
	v_mov_b32_e32 v30, v0
	v_mov_b32_e32 v31, v0
	v_mov_b32_e32 v40, v0
	v_mov_b32_e32 v41, v0
	v_mov_b32_e32 v42, v0
	v_mov_b32_e32 v43, v0
	v_mov_b32_e32 v44, v0
	v_mov_b32_e32 v45, v0
	v_mov_b32_e32 v46, v0
	v_mov_b32_e32 v47, v0
	v_mov_b32_e32 v56, v0
	v_mov_b32_e32 v57, v0
	v_mov_b32_e32 v58, v0
	v_mov_b32_e32 v59, v0
	v_mov_b32_e32 v60, v0
	v_mov_b32_e32 v61, v0
	v_mov_b32_e32 v62, v0
	v_mov_b32_e32 v63, v0
	v_mov_b32_e32 v64, v0
	v_mov_b32_e32 v65, v0
	v_mov_b32_e32 v66, v0
	v_mov_b32_e32 v67, v0
	v_mov_b32_e32 v68, v0
	v_mov_b32_e32 v69, v0
	v_mov_b32_e32 v70, v0
	v_mov_b32_e32 v71, v0
	v_mov_b32_e32 v80, v0
	v_mov_b32_e32 v81, v0
	v_mov_b32_e32 v82, v0
	v_mov_b32_e32 v83, v0
	v_mov_b32_e32 v84, v0
	v_mov_b32_e32 v85, v0
	v_mov_b32_e32 v86, v0
	v_mov_b32_e32 v87, v0
	v_mov_b32_e32 v96, v0
	v_mov_b32_e32 v97, v0
	v_mov_b32_e32 v98, v0
	v_mov_b32_e32 v99, v0
	v_mov_b32_e32 v100, v0
	v_mov_b32_e32 v101, v0
	v_mov_b32_e32 v102, v0
	v_mov_b32_e32 v103, v0
	v_mov_b32_e32 v112, v0
	v_mov_b32_e32 v113, v0
	v_mov_b32_e32 v114, v0
	v_mov_b32_e32 v115, v0
	v_mov_b32_e32 v116, v0
	v_mov_b32_e32 v117, v0
	v_mov_b32_e32 v118, v0
	v_mov_b32_e32 v119, v0
	v_mov_b32_e32 v72, v0
	v_mov_b32_e32 v73, v0
	v_mov_b32_e32 v74, v0
	v_mov_b32_e32 v75, v0
	v_mov_b32_e32 v76, v0
	v_mov_b32_e32 v77, v0
	v_mov_b32_e32 v78, v0
	v_mov_b32_e32 v79, v0
	v_mov_b32_e32 v88, v0
	v_mov_b32_e32 v89, v0
	v_mov_b32_e32 v90, v0
	v_mov_b32_e32 v91, v0
	v_mov_b32_e32 v92, v0
	v_mov_b32_e32 v93, v0
	v_mov_b32_e32 v94, v0
	v_mov_b32_e32 v95, v0
	v_mov_b32_e32 v104, v0
	v_mov_b32_e32 v105, v0
	v_mov_b32_e32 v106, v0
	v_mov_b32_e32 v107, v0
	v_mov_b32_e32 v108, v0
	v_mov_b32_e32 v109, v0
	v_mov_b32_e32 v110, v0
	v_mov_b32_e32 v111, v0
	v_mov_b32_e32 v124, v0
	v_mov_b32_e32 v125, v0
	v_mov_b32_e32 v126, v0
	v_mov_b32_e32 v127, v0
	v_mov_b32_e32 v128, v0
	v_mov_b32_e32 v129, v0
	v_mov_b32_e32 v130, v0
	v_mov_b32_e32 v131, v0
	s_lshr_b32 s101, s88, 2
	s_cmp_lg_u32 s101, 1
	s_cbranch_scc1 .Lprio_skip12
	s_setprio 1
.Lprio_skip12:
.LBB0_1825:
	ds_read_b128 v[120:123], v230
	ds_read_b128 v[132:135], v230 offset:1024
	ds_read_b128 v[136:139], v230 offset:2048
	ds_read_b128 v[140:143], v230 offset:3072
	ds_read_b128 v[144:147], v231
	ds_read_b128 v[148:151], v231 offset:1024
	ds_read_b128 v[152:155], v231 offset:2048
	ds_read_b128 v[156:159], v231 offset:3072
	s_add_u32 s28, s0, s2
	s_addc_u32 s29, s1, s3
	s_cmpk_eq_i32 s2, 0x1000
	s_cselect_b32 s30, 0, s2
	s_cselect_b32 s31, 0, s3
	s_cselect_b32 s28, s57, s28
	s_cselect_b32 s29, s5, s29
	s_add_u32 s30, s10, s30
	s_addc_u32 s31, s11, s31
	s_add_u32 s98, s2, s86
	s_addc_u32 s99, s3, s87
	s_add_i32 m0, s85, 0x8000
	v_lshl_add_u64 v[204:205], v[192:193], 0, s[98:99]
	ds_read_b128 v[160:163], v232
	ds_read_b128 v[164:167], v232 offset:1024
	ds_read_b128 v[168:171], v232 offset:2048
	ds_read_b128 v[172:175], v232 offset:3072
	ds_read_b128 v[176:179], v232 offset:4096
	ds_read_b128 v[180:183], v232 offset:5120
	ds_read_b128 v[196:199], v232 offset:6144
	ds_read_b128 v[200:203], v232 offset:7168
	global_load_lds_dwordx4 v[204:205], off
	s_add_u32 s98, s98, 0x20000
	s_addc_u32 s99, s99, 0
	s_add_i32 m0, s85, 0x9000
	v_lshl_add_u64 v[204:205], v[192:193], 0, s[98:99]
	global_load_lds_dwordx4 v[204:205], off
	s_add_u32 s98, s98, 0x20000
	s_addc_u32 s99, s99, 0
	s_add_i32 m0, s85, 0xa000
	v_lshl_add_u64 v[204:205], v[192:193], 0, s[98:99]
	global_load_lds_dwordx4 v[204:205], off
	s_add_u32 s98, s98, 0x20000
	s_addc_u32 s99, s99, 0
	s_add_i32 m0, s85, 0xb000
	v_lshl_add_u64 v[204:205], v[192:193], 0, s[98:99]
	global_load_lds_dwordx4 v[204:205], off
	s_waitcnt vmcnt(8)
	s_waitcnt lgkmcnt(0)
	s_barrier
	s_waitcnt lgkmcnt(0)
	v_mfma_f32_16x16x32_bf16 v[128:131], v[120:123], v[160:163], v[128:131]
	v_mfma_f32_16x16x32_bf16 v[124:127], v[136:139], v[160:163], v[124:127]
	v_mfma_f32_16x16x32_bf16 v[108:111], v[120:123], v[168:171], v[108:111]
	v_mfma_f32_16x16x32_bf16 v[104:107], v[136:139], v[168:171], v[104:107]
	v_mfma_f32_16x16x32_bf16 v[92:95], v[120:123], v[176:179], v[92:95]
	v_mfma_f32_16x16x32_bf16 v[88:91], v[136:139], v[176:179], v[88:91]
	v_mfma_f32_16x16x32_bf16 v[76:79], v[120:123], v[196:199], v[76:79]
	v_mfma_f32_16x16x32_bf16 v[72:75], v[136:139], v[196:199], v[72:75]
	v_mfma_f32_16x16x32_bf16 v[128:131], v[132:135], v[164:167], v[128:131]
	v_mfma_f32_16x16x32_bf16 v[124:127], v[140:143], v[164:167], v[124:127]
	v_mfma_f32_16x16x32_bf16 v[108:111], v[132:135], v[172:175], v[108:111]
	v_mfma_f32_16x16x32_bf16 v[104:107], v[140:143], v[172:175], v[104:107]
	v_mfma_f32_16x16x32_bf16 v[92:95], v[132:135], v[180:183], v[92:95]
	v_mfma_f32_16x16x32_bf16 v[88:91], v[140:143], v[180:183], v[88:91]
	v_mfma_f32_16x16x32_bf16 v[76:79], v[132:135], v[200:203], v[76:79]
	v_mfma_f32_16x16x32_bf16 v[72:75], v[140:143], v[200:203], v[72:75]
	v_mfma_f32_16x16x32_bf16 v[116:119], v[144:147], v[160:163], v[116:119]
	v_mfma_f32_16x16x32_bf16 v[112:115], v[152:155], v[160:163], v[112:115]
	v_mfma_f32_16x16x32_bf16 v[100:103], v[144:147], v[168:171], v[100:103]
	v_mfma_f32_16x16x32_bf16 v[96:99], v[152:155], v[168:171], v[96:99]
	v_mfma_f32_16x16x32_bf16 v[84:87], v[144:147], v[176:179], v[84:87]
	v_mfma_f32_16x16x32_bf16 v[80:83], v[152:155], v[176:179], v[80:83]
	v_mfma_f32_16x16x32_bf16 v[68:71], v[144:147], v[196:199], v[68:71]
	v_mfma_f32_16x16x32_bf16 v[64:67], v[152:155], v[196:199], v[64:67]
	v_mfma_f32_16x16x32_bf16 v[116:119], v[148:151], v[164:167], v[116:119]
	v_mfma_f32_16x16x32_bf16 v[112:115], v[156:159], v[164:167], v[112:115]
	v_mfma_f32_16x16x32_bf16 v[100:103], v[148:151], v[172:175], v[100:103]
	v_mfma_f32_16x16x32_bf16 v[96:99], v[156:159], v[172:175], v[96:99]
	v_mfma_f32_16x16x32_bf16 v[84:87], v[148:151], v[180:183], v[84:87]
	v_mfma_f32_16x16x32_bf16 v[80:83], v[156:159], v[180:183], v[80:83]
	v_mfma_f32_16x16x32_bf16 v[68:71], v[148:151], v[200:203], v[68:71]
	v_mfma_f32_16x16x32_bf16 v[64:67], v[156:159], v[200:203], v[64:67]
	s_barrier
	s_mov_b32 m0, s50
	v_lshl_add_u64 v[204:205], s[28:29], 0, v[188:189]
	s_add_u32 s60, s28, 0x80000
	ds_read_b128 v[160:163], v232 offset:16384
	ds_read_b128 v[164:167], v232 offset:17408
	ds_read_b128 v[168:171], v232 offset:18432
	ds_read_b128 v[172:175], v232 offset:19456
	ds_read_b128 v[176:179], v232 offset:20480
	ds_read_b128 v[180:183], v232 offset:21504
	ds_read_b128 v[196:199], v232 offset:22528
	ds_read_b128 v[200:203], v232 offset:23552
	global_load_lds_dwordx4 v[204:205], off
	v_lshl_add_u64 v[206:207], s[28:29], 0, v[184:185]
	s_mov_b32 m0, s51
	s_addc_u32 s61, s29, 0
	global_load_lds_dwordx4 v[206:207], off
	v_lshl_add_u64 v[208:209], s[60:61], 0, v[188:189]
	s_mov_b32 m0, s52
	global_load_lds_dwordx4 v[208:209], off
	v_lshl_add_u64 v[208:209], s[60:61], 0, v[184:185]
	s_mov_b32 m0, s53
	s_nop 0
	global_load_lds_dwordx4 v[208:209], off
	s_waitcnt vmcnt(8)
	s_waitcnt lgkmcnt(0)
	s_barrier
	s_waitcnt lgkmcnt(0)
	v_mfma_f32_16x16x32_bf16 v[60:63], v[120:123], v[160:163], v[60:63]
	v_mfma_f32_16x16x32_bf16 v[56:59], v[136:139], v[160:163], v[56:59]
	v_mfma_f32_16x16x32_bf16 v[44:47], v[120:123], v[168:171], v[44:47]
	v_mfma_f32_16x16x32_bf16 v[40:43], v[136:139], v[168:171], v[40:43]
	v_mfma_f32_16x16x32_bf16 v[28:31], v[120:123], v[176:179], v[28:31]
	v_mfma_f32_16x16x32_bf16 v[24:27], v[136:139], v[176:179], v[24:27]
	v_mfma_f32_16x16x32_bf16 v[12:15], v[120:123], v[196:199], v[12:15]
	v_mfma_f32_16x16x32_bf16 v[8:11], v[136:139], v[196:199], v[8:11]
	v_mfma_f32_16x16x32_bf16 v[60:63], v[132:135], v[164:167], v[60:63]
	v_mfma_f32_16x16x32_bf16 v[56:59], v[140:143], v[164:167], v[56:59]
	v_mfma_f32_16x16x32_bf16 v[44:47], v[132:135], v[172:175], v[44:47]
	v_mfma_f32_16x16x32_bf16 v[40:43], v[140:143], v[172:175], v[40:43]
	v_mfma_f32_16x16x32_bf16 v[28:31], v[132:135], v[180:183], v[28:31]
	v_mfma_f32_16x16x32_bf16 v[24:27], v[140:143], v[180:183], v[24:27]
	v_mfma_f32_16x16x32_bf16 v[12:15], v[132:135], v[200:203], v[12:15]
	v_mfma_f32_16x16x32_bf16 v[8:11], v[140:143], v[200:203], v[8:11]
	v_mfma_f32_16x16x32_bf16 v[52:55], v[144:147], v[160:163], v[52:55]
	v_mfma_f32_16x16x32_bf16 v[48:51], v[152:155], v[160:163], v[48:51]
	v_mfma_f32_16x16x32_bf16 v[36:39], v[144:147], v[168:171], v[36:39]
	v_mfma_f32_16x16x32_bf16 v[32:35], v[152:155], v[168:171], v[32:35]
	v_mfma_f32_16x16x32_bf16 v[20:23], v[144:147], v[176:179], v[20:23]
	v_mfma_f32_16x16x32_bf16 v[16:19], v[152:155], v[176:179], v[16:19]
	v_mfma_f32_16x16x32_bf16 v[4:7], v[144:147], v[196:199], v[4:7]
	v_mfma_f32_16x16x32_bf16 v[0:3], v[152:155], v[196:199], v[0:3]
	v_mfma_f32_16x16x32_bf16 v[52:55], v[148:151], v[164:167], v[52:55]
	v_mfma_f32_16x16x32_bf16 v[48:51], v[156:159], v[164:167], v[48:51]
	v_mfma_f32_16x16x32_bf16 v[36:39], v[148:151], v[172:175], v[36:39]
	v_mfma_f32_16x16x32_bf16 v[32:35], v[156:159], v[172:175], v[32:35]
	v_mfma_f32_16x16x32_bf16 v[20:23], v[148:151], v[180:183], v[20:23]
	v_mfma_f32_16x16x32_bf16 v[16:19], v[156:159], v[180:183], v[16:19]
	v_mfma_f32_16x16x32_bf16 v[4:7], v[148:151], v[200:203], v[4:7]
	v_mfma_f32_16x16x32_bf16 v[0:3], v[156:159], v[200:203], v[0:3]
	s_waitcnt vmcnt(4)
	s_barrier
	ds_read_b128 v[120:123], v234
	ds_read_b128 v[132:135], v234 offset:1024
	ds_read_b128 v[136:139], v234 offset:2048
	ds_read_b128 v[140:143], v234 offset:3072
	ds_read_b128 v[144:147], v235
	ds_read_b128 v[148:151], v235 offset:1024
	ds_read_b128 v[152:155], v235 offset:2048
	ds_read_b128 v[156:159], v235 offset:3072
	s_add_u32 s98, s30, s96
	s_addc_u32 s99, s31, s97
	s_add_i32 m0, s85, 0
	v_lshl_add_u64 v[212:213], s[98:99], 0, v[190:191]
	ds_read_b128 v[160:163], v232 offset:32768
	ds_read_b128 v[164:167], v232 offset:33792
	ds_read_b128 v[168:171], v232 offset:34816
	ds_read_b128 v[172:175], v232 offset:35840
	ds_read_b128 v[176:179], v232 offset:36864
	ds_read_b128 v[180:183], v232 offset:37888
	ds_read_b128 v[196:199], v232 offset:38912
	ds_read_b128 v[200:203], v232 offset:39936
	global_load_lds_dwordx4 v[212:213], off
	s_add_u32 s98, s98, 0x20000
	s_addc_u32 s99, s99, 0
	s_add_i32 m0, s85, 0x1000
	v_lshl_add_u64 v[212:213], s[98:99], 0, v[190:191]
	global_load_lds_dwordx4 v[212:213], off
	s_add_u32 s98, s98, 0x20000
	s_addc_u32 s99, s99, 0
	s_add_i32 m0, s85, 0x2000
	v_lshl_add_u64 v[212:213], s[98:99], 0, v[190:191]
	global_load_lds_dwordx4 v[212:213], off
	s_add_u32 s98, s98, 0x20000
	s_addc_u32 s99, s99, 0
	s_add_i32 m0, s85, 0x3000
	v_lshl_add_u64 v[212:213], s[98:99], 0, v[190:191]
	global_load_lds_dwordx4 v[212:213], off
	s_waitcnt vmcnt(8)
	s_waitcnt lgkmcnt(0)
	s_barrier
	s_waitcnt lgkmcnt(0)
	v_mfma_f32_16x16x32_bf16 v[128:131], v[120:123], v[160:163], v[128:131]
	v_mfma_f32_16x16x32_bf16 v[124:127], v[136:139], v[160:163], v[124:127]
	v_mfma_f32_16x16x32_bf16 v[108:111], v[120:123], v[168:171], v[108:111]
	v_mfma_f32_16x16x32_bf16 v[104:107], v[136:139], v[168:171], v[104:107]
	v_mfma_f32_16x16x32_bf16 v[92:95], v[120:123], v[176:179], v[92:95]
	v_mfma_f32_16x16x32_bf16 v[88:91], v[136:139], v[176:179], v[88:91]
	v_mfma_f32_16x16x32_bf16 v[76:79], v[120:123], v[196:199], v[76:79]
	v_mfma_f32_16x16x32_bf16 v[72:75], v[136:139], v[196:199], v[72:75]
	v_mfma_f32_16x16x32_bf16 v[128:131], v[132:135], v[164:167], v[128:131]
	v_mfma_f32_16x16x32_bf16 v[124:127], v[140:143], v[164:167], v[124:127]
	v_mfma_f32_16x16x32_bf16 v[108:111], v[132:135], v[172:175], v[108:111]
	v_mfma_f32_16x16x32_bf16 v[104:107], v[140:143], v[172:175], v[104:107]
	v_mfma_f32_16x16x32_bf16 v[92:95], v[132:135], v[180:183], v[92:95]
	v_mfma_f32_16x16x32_bf16 v[88:91], v[140:143], v[180:183], v[88:91]
	v_mfma_f32_16x16x32_bf16 v[76:79], v[132:135], v[200:203], v[76:79]
	v_mfma_f32_16x16x32_bf16 v[72:75], v[140:143], v[200:203], v[72:75]
	v_mfma_f32_16x16x32_bf16 v[116:119], v[144:147], v[160:163], v[116:119]
	v_mfma_f32_16x16x32_bf16 v[112:115], v[152:155], v[160:163], v[112:115]
	v_mfma_f32_16x16x32_bf16 v[100:103], v[144:147], v[168:171], v[100:103]
	v_mfma_f32_16x16x32_bf16 v[96:99], v[152:155], v[168:171], v[96:99]
	v_mfma_f32_16x16x32_bf16 v[84:87], v[144:147], v[176:179], v[84:87]
	v_mfma_f32_16x16x32_bf16 v[80:83], v[152:155], v[176:179], v[80:83]
	v_mfma_f32_16x16x32_bf16 v[68:71], v[144:147], v[196:199], v[68:71]
	v_mfma_f32_16x16x32_bf16 v[64:67], v[152:155], v[196:199], v[64:67]
	v_mfma_f32_16x16x32_bf16 v[116:119], v[148:151], v[164:167], v[116:119]
	v_mfma_f32_16x16x32_bf16 v[112:115], v[156:159], v[164:167], v[112:115]
	v_mfma_f32_16x16x32_bf16 v[100:103], v[148:151], v[172:175], v[100:103]
	v_mfma_f32_16x16x32_bf16 v[96:99], v[156:159], v[172:175], v[96:99]
	v_mfma_f32_16x16x32_bf16 v[84:87], v[148:151], v[180:183], v[84:87]
	v_mfma_f32_16x16x32_bf16 v[80:83], v[156:159], v[180:183], v[80:83]
	v_mfma_f32_16x16x32_bf16 v[68:71], v[148:151], v[200:203], v[68:71]
	v_mfma_f32_16x16x32_bf16 v[64:67], v[156:159], v[200:203], v[64:67]
	s_barrier
	s_mov_b32 m0, s55
	v_lshl_add_u64 v[204:205], v[204:205], 0, s[18:19]
	ds_read_b128 v[160:163], v232 offset:49152
	ds_read_b128 v[164:167], v232 offset:50176
	ds_read_b128 v[168:171], v232 offset:51200
	ds_read_b128 v[172:175], v232 offset:52224
	ds_read_b128 v[176:179], v232 offset:53248
	ds_read_b128 v[180:183], v232 offset:54272
	ds_read_b128 v[196:199], v232 offset:55296
	ds_read_b128 v[200:203], v232 offset:56320
	global_load_lds_dwordx4 v[204:205], off
	s_add_i32 m0, s55, 0x2000
	s_add_u32 s28, s28, 0x80080
	v_lshl_add_u64 v[204:205], v[206:207], 0, s[18:19]
	s_addc_u32 s29, s29, 0
	s_add_i32 s30, s54, s37
	global_load_lds_dwordx4 v[204:205], off
	v_lshl_add_u64 v[204:205], s[28:29], 0, v[188:189]
	s_mov_b32 m0, s30
	s_nop 0
	global_load_lds_dwordx4 v[204:205], off
	v_lshl_add_u64 v[204:205], s[28:29], 0, v[184:185]
	s_add_i32 m0, s30, 0x2000
	s_nop 0
	global_load_lds_dwordx4 v[204:205], off
	s_waitcnt vmcnt(8)
	s_waitcnt lgkmcnt(0)
	s_barrier
	s_waitcnt lgkmcnt(0)
	v_mfma_f32_16x16x32_bf16 v[60:63], v[120:123], v[160:163], v[60:63]
	v_mfma_f32_16x16x32_bf16 v[56:59], v[136:139], v[160:163], v[56:59]
	v_mfma_f32_16x16x32_bf16 v[44:47], v[120:123], v[168:171], v[44:47]
	v_mfma_f32_16x16x32_bf16 v[40:43], v[136:139], v[168:171], v[40:43]
	v_mfma_f32_16x16x32_bf16 v[28:31], v[120:123], v[176:179], v[28:31]
	v_mfma_f32_16x16x32_bf16 v[24:27], v[136:139], v[176:179], v[24:27]
	v_mfma_f32_16x16x32_bf16 v[12:15], v[120:123], v[196:199], v[12:15]
	v_mfma_f32_16x16x32_bf16 v[8:11], v[136:139], v[196:199], v[8:11]
	v_mfma_f32_16x16x32_bf16 v[60:63], v[132:135], v[164:167], v[60:63]
	v_mfma_f32_16x16x32_bf16 v[56:59], v[140:143], v[164:167], v[56:59]
	v_mfma_f32_16x16x32_bf16 v[44:47], v[132:135], v[172:175], v[44:47]
	v_mfma_f32_16x16x32_bf16 v[40:43], v[140:143], v[172:175], v[40:43]
	v_mfma_f32_16x16x32_bf16 v[28:31], v[132:135], v[180:183], v[28:31]
	v_mfma_f32_16x16x32_bf16 v[24:27], v[140:143], v[180:183], v[24:27]
	v_mfma_f32_16x16x32_bf16 v[12:15], v[132:135], v[200:203], v[12:15]
	v_mfma_f32_16x16x32_bf16 v[8:11], v[140:143], v[200:203], v[8:11]
	v_mfma_f32_16x16x32_bf16 v[52:55], v[144:147], v[160:163], v[52:55]
	v_mfma_f32_16x16x32_bf16 v[48:51], v[152:155], v[160:163], v[48:51]
	v_mfma_f32_16x16x32_bf16 v[36:39], v[144:147], v[168:171], v[36:39]
	v_mfma_f32_16x16x32_bf16 v[32:35], v[152:155], v[168:171], v[32:35]
	v_mfma_f32_16x16x32_bf16 v[20:23], v[144:147], v[176:179], v[20:23]
	v_mfma_f32_16x16x32_bf16 v[16:19], v[152:155], v[176:179], v[16:19]
	v_mfma_f32_16x16x32_bf16 v[4:7], v[144:147], v[196:199], v[4:7]
	v_mfma_f32_16x16x32_bf16 v[0:3], v[152:155], v[196:199], v[0:3]
	v_mfma_f32_16x16x32_bf16 v[52:55], v[148:151], v[164:167], v[52:55]
	v_mfma_f32_16x16x32_bf16 v[48:51], v[156:159], v[164:167], v[48:51]
	v_mfma_f32_16x16x32_bf16 v[36:39], v[148:151], v[172:175], v[36:39]
	v_mfma_f32_16x16x32_bf16 v[32:35], v[156:159], v[172:175], v[32:35]
	v_mfma_f32_16x16x32_bf16 v[20:23], v[148:151], v[180:183], v[20:23]
	v_mfma_f32_16x16x32_bf16 v[16:19], v[156:159], v[180:183], v[16:19]
	v_mfma_f32_16x16x32_bf16 v[4:7], v[148:151], v[200:203], v[4:7]
	v_mfma_f32_16x16x32_bf16 v[0:3], v[156:159], v[200:203], v[0:3]
	s_waitcnt vmcnt(4)
	s_barrier
	s_add_i32 s58, s58, 2
	s_add_u32 s2, s2, 0x100
	s_addc_u32 s3, s3, 0
	s_cmp_gt_u32 s58, 29
	s_cbranch_scc0 .LBB0_1825
	s_setprio 0
	s_and_b64 vcc, exec, s[22:23]
	s_cbranch_vccz .LBB0_1828
	s_barrier

.LBB0_1954:
	s_add_i32 s52, s52, 1
	s_mov_b64 s[36:37], s[10:11]
	s_mov_b32 s67, s6
	s_mov_b32 s10, s6
	s_lshl_b32 s6, s52, 5
	s_add_i32 s6, s6, s40
	s_cmpk_lt_i32 s6, 0x80
	s_cselect_b64 s[34:35], -1, 0
	s_ashr_i32 s6, s6, 2
	s_mov_b64 s[0:1], s[8:9]
	s_and_b64 s[8:9], s[34:35], exec
	s_cselect_b32 s8, s41, s41
	s_cselect_b32 s10, s6, s10
	s_ashr_i32 s9, s8, 31
	s_lshl_b64 s[8:9], s[8:9], 20
	s_add_u32 s8, s42, s8
	s_addc_u32 s9, s43, s9
	s_and_b64 s[38:39], s[34:35], exec
	s_cselect_b32 s68, s9, s1
	s_cselect_b32 s69, s8, s0
	s_ashr_i32 s11, s10, 31
	s_lshl_b64 s[10:11], s[10:11], 20
	s_add_u32 s10, s44, s10
	s_addc_u32 s11, s45, s11
	s_and_b64 s[38:39], s[34:35], exec
	s_cselect_b32 s70, s11, s37
	s_cselect_b32 s71, s10, s36
	s_add_u32 s0, s0, 0x80080
	s_addc_u32 s1, s1, 0
	s_add_u32 s72, s36, 0x100
	s_addc_u32 s73, s37, 0
	s_mov_b32 s74, -2
	v_mov_b32_e32 v0, 0
	v_mov_b32_e32 v1, v137
	v_mov_b32_e32 v2, v137
	v_mov_b32_e32 v3, v137
	v_mov_b32_e32 v4, 0
	v_mov_b32_e32 v5, v137
	v_mov_b32_e32 v6, v137
	v_mov_b32_e32 v7, v137
	v_mov_b32_e32 v16, 0
	v_mov_b32_e32 v17, v137
	v_mov_b32_e32 v18, v137
	v_mov_b32_e32 v19, v137
	v_mov_b32_e32 v20, 0
	v_mov_b32_e32 v21, v137
	v_mov_b32_e32 v22, v137
	v_mov_b32_e32 v23, v137
	v_mov_b32_e32 v32, 0
	v_mov_b32_e32 v33, v137
	v_mov_b32_e32 v34, v137
	v_mov_b32_e32 v35, v137
	v_mov_b32_e32 v36, 0
	v_mov_b32_e32 v37, v137
	v_mov_b32_e32 v38, v137
	v_mov_b32_e32 v39, v137
	v_mov_b32_e32 v48, 0
	v_mov_b32_e32 v49, v137
	v_mov_b32_e32 v50, v137
	v_mov_b32_e32 v51, v137
	v_mov_b32_e32 v52, 0
	v_mov_b32_e32 v53, v137
	v_mov_b32_e32 v54, v137
	v_mov_b32_e32 v55, v137
	v_mov_b32_e32 v8, 0
	v_mov_b32_e32 v9, v137
	v_mov_b32_e32 v10, v137
	v_mov_b32_e32 v11, v137
	v_mov_b32_e32 v12, 0
	v_mov_b32_e32 v13, v137
	v_mov_b32_e32 v14, v137
	v_mov_b32_e32 v15, v137
	v_mov_b32_e32 v24, 0
	v_mov_b32_e32 v25, v137
	v_mov_b32_e32 v26, v137
	v_mov_b32_e32 v27, v137
	v_mov_b32_e32 v28, 0
	v_mov_b32_e32 v29, v137
	v_mov_b32_e32 v30, v137
	v_mov_b32_e32 v31, v137
	v_mov_b32_e32 v40, 0
	v_mov_b32_e32 v41, v137
	v_mov_b32_e32 v42, v137
	v_mov_b32_e32 v43, v137
	v_mov_b32_e32 v44, 0
	v_mov_b32_e32 v45, v137
	v_mov_b32_e32 v46, v137
	v_mov_b32_e32 v47, v137
	v_mov_b32_e32 v56, 0
	v_mov_b32_e32 v57, v137
	v_mov_b32_e32 v58, v137
	v_mov_b32_e32 v59, v137
	v_mov_b32_e32 v60, 0
	v_mov_b32_e32 v61, v137
	v_mov_b32_e32 v62, v137
	v_mov_b32_e32 v63, v137
	v_mov_b32_e32 v64, 0
	v_mov_b32_e32 v65, v137
	v_mov_b32_e32 v66, v137
	v_mov_b32_e32 v67, v137
	v_mov_b32_e32 v68, 0
	v_mov_b32_e32 v69, v137
	v_mov_b32_e32 v70, v137
	v_mov_b32_e32 v71, v137
	v_mov_b32_e32 v80, 0
	v_mov_b32_e32 v81, v137
	v_mov_b32_e32 v82, v137
	v_mov_b32_e32 v83, v137
	v_mov_b32_e32 v84, 0
	v_mov_b32_e32 v85, v137
	v_mov_b32_e32 v86, v137
	v_mov_b32_e32 v87, v137
	v_mov_b32_e32 v96, 0
	v_mov_b32_e32 v97, v137
	v_mov_b32_e32 v98, v137
	v_mov_b32_e32 v99, v137
	v_mov_b32_e32 v100, 0
	v_mov_b32_e32 v101, v137
	v_mov_b32_e32 v102, v137
	v_mov_b32_e32 v103, v137
	v_mov_b32_e32 v112, 0
	v_mov_b32_e32 v113, v137
	v_mov_b32_e32 v114, v137
	v_mov_b32_e32 v115, v137
	v_mov_b32_e32 v116, 0
	v_mov_b32_e32 v117, v137
	v_mov_b32_e32 v118, v137
	v_mov_b32_e32 v119, v137
	v_mov_b32_e32 v72, 0
	v_mov_b32_e32 v73, v137
	v_mov_b32_e32 v74, v137
	v_mov_b32_e32 v75, v137
	v_mov_b32_e32 v76, 0
	v_mov_b32_e32 v77, v137
	v_mov_b32_e32 v78, v137
	v_mov_b32_e32 v79, v137
	v_mov_b32_e32 v88, 0
	v_mov_b32_e32 v89, v137
	v_mov_b32_e32 v90, v137
	v_mov_b32_e32 v91, v137
	v_mov_b32_e32 v92, 0
	v_mov_b32_e32 v93, v137
	v_mov_b32_e32 v94, v137
	v_mov_b32_e32 v95, v137
	v_mov_b32_e32 v104, 0
	v_mov_b32_e32 v105, v137
	v_mov_b32_e32 v106, v137
	v_mov_b32_e32 v107, v137
	v_mov_b32_e32 v108, 0
	v_mov_b32_e32 v109, v137
	v_mov_b32_e32 v110, v137
	v_mov_b32_e32 v111, v137
	v_mov_b32_e32 v120, 0
	v_mov_b32_e32 v121, v137
	v_mov_b32_e32 v122, v137
	v_mov_b32_e32 v123, v137
	v_mov_b32_e32 v124, 0
	v_mov_b32_e32 v125, v137
	v_mov_b32_e32 v126, v137
	v_mov_b32_e32 v127, v137
	s_lshr_b32 s101, s88, 2
	s_cmp_lg_u32 s101, 1
	s_cbranch_scc1 .Lprio_skip13
	s_setprio 1
.Lprio_skip13:
.LBB0_1955:
	ds_read_b128 v[140:143], v150
	ds_read_b128 v[144:147], v150 offset:1024
	ds_read_b128 v[156:159], v150 offset:2048
	ds_read_b128 v[160:163], v150 offset:3072
	ds_read_b128 v[164:167], v151
	ds_read_b128 v[168:171], v151 offset:1024
	ds_read_b128 v[172:175], v151 offset:2048
	ds_read_b128 v[176:179], v151 offset:3072
	s_add_u32 s36, s0, 0xfff80080
	s_addc_u32 s37, s1, -1
	s_cmp_eq_u32 s74, 28
	s_cselect_b32 s39, s68, s37
	s_cselect_b32 s38, s69, s36
	s_cselect_b32 s37, s70, s73
	s_cselect_b32 s36, s71, s72
	s_sub_u32 s98, s0, 0x80000
	s_subb_u32 s99, s1, 0
	s_add_i32 m0, s85, 0x8000
	ds_read_b128 v[180:183], v152
	ds_read_b128 v[184:187], v152 offset:1024
	ds_read_b128 v[188:191], v152 offset:2048
	ds_read_b128 v[192:195], v152 offset:3072
	ds_read_b128 v[196:199], v152 offset:4096
	ds_read_b128 v[200:203], v152 offset:5120
	ds_read_b128 v[204:207], v152 offset:6144
	ds_read_b128 v[208:211], v152 offset:7168
	global_load_lds_dwordx4 v222, s[98:99]
	s_add_u32 s98, s98, 0x20000
	s_addc_u32 s99, s99, 0
	s_add_i32 m0, s85, 0x9000
	s_nop 0
	global_load_lds_dwordx4 v222, s[98:99]
	s_add_u32 s98, s98, 0x20000
	s_addc_u32 s99, s99, 0
	s_add_i32 m0, s85, 0xa000
	s_nop 0
	global_load_lds_dwordx4 v222, s[98:99]
	s_add_u32 s98, s98, 0x20000
	s_addc_u32 s99, s99, 0
	s_add_i32 m0, s85, 0xb000
	s_nop 0
	global_load_lds_dwordx4 v222, s[98:99]
	s_waitcnt vmcnt(8)
	s_waitcnt lgkmcnt(0)
	s_barrier
	s_waitcnt lgkmcnt(0)
	v_mfma_f32_16x16x32_bf16 v[124:127], v[140:143], v[180:183], v[124:127]
	v_mfma_f32_16x16x32_bf16 v[120:123], v[156:159], v[180:183], v[120:123]
	v_mfma_f32_16x16x32_bf16 v[108:111], v[140:143], v[188:191], v[108:111]
	v_mfma_f32_16x16x32_bf16 v[104:107], v[156:159], v[188:191], v[104:107]
	v_mfma_f32_16x16x32_bf16 v[92:95], v[140:143], v[196:199], v[92:95]
	v_mfma_f32_16x16x32_bf16 v[88:91], v[156:159], v[196:199], v[88:91]
	v_mfma_f32_16x16x32_bf16 v[76:79], v[140:143], v[204:207], v[76:79]
	v_mfma_f32_16x16x32_bf16 v[72:75], v[156:159], v[204:207], v[72:75]
	v_mfma_f32_16x16x32_bf16 v[124:127], v[144:147], v[184:187], v[124:127]
	v_mfma_f32_16x16x32_bf16 v[120:123], v[160:163], v[184:187], v[120:123]
	v_mfma_f32_16x16x32_bf16 v[108:111], v[144:147], v[192:195], v[108:111]
	v_mfma_f32_16x16x32_bf16 v[104:107], v[160:163], v[192:195], v[104:107]
	v_mfma_f32_16x16x32_bf16 v[92:95], v[144:147], v[200:203], v[92:95]
	v_mfma_f32_16x16x32_bf16 v[88:91], v[160:163], v[200:203], v[88:91]
	v_mfma_f32_16x16x32_bf16 v[76:79], v[144:147], v[208:211], v[76:79]
	v_mfma_f32_16x16x32_bf16 v[72:75], v[160:163], v[208:211], v[72:75]
	v_mfma_f32_16x16x32_bf16 v[116:119], v[164:167], v[180:183], v[116:119]
	v_mfma_f32_16x16x32_bf16 v[112:115], v[172:175], v[180:183], v[112:115]
	v_mfma_f32_16x16x32_bf16 v[100:103], v[164:167], v[188:191], v[100:103]
	v_mfma_f32_16x16x32_bf16 v[96:99], v[172:175], v[188:191], v[96:99]
	v_mfma_f32_16x16x32_bf16 v[84:87], v[164:167], v[196:199], v[84:87]
	v_mfma_f32_16x16x32_bf16 v[80:83], v[172:175], v[196:199], v[80:83]
	v_mfma_f32_16x16x32_bf16 v[68:71], v[164:167], v[204:207], v[68:71]
	v_mfma_f32_16x16x32_bf16 v[64:67], v[172:175], v[204:207], v[64:67]
	v_mfma_f32_16x16x32_bf16 v[116:119], v[168:171], v[184:187], v[116:119]
	v_mfma_f32_16x16x32_bf16 v[112:115], v[176:179], v[184:187], v[112:115]
	v_mfma_f32_16x16x32_bf16 v[100:103], v[168:171], v[192:195], v[100:103]
	v_mfma_f32_16x16x32_bf16 v[96:99], v[176:179], v[192:195], v[96:99]
	v_mfma_f32_16x16x32_bf16 v[84:87], v[168:171], v[200:203], v[84:87]
	v_mfma_f32_16x16x32_bf16 v[80:83], v[176:179], v[200:203], v[80:83]
	v_mfma_f32_16x16x32_bf16 v[68:71], v[168:171], v[208:211], v[68:71]
	v_mfma_f32_16x16x32_bf16 v[64:67], v[176:179], v[208:211], v[64:67]
	s_barrier
	s_add_i32 s75, s56, s7
	v_lshl_add_u64 v[212:213], s[36:37], 0, v[130:131]
	s_mov_b32 m0, s75
	ds_read_b128 v[180:183], v152 offset:16384
	ds_read_b128 v[184:187], v152 offset:17408
	ds_read_b128 v[188:191], v152 offset:18432
	ds_read_b128 v[192:195], v152 offset:19456
	ds_read_b128 v[196:199], v152 offset:20480
	ds_read_b128 v[200:203], v152 offset:21504
	ds_read_b128 v[204:207], v152 offset:22528
	ds_read_b128 v[208:211], v152 offset:23552
	global_load_lds_dwordx4 v[212:213], off
	s_add_i32 m0, s75, 0x2000
	s_add_u32 s76, s36, 0x80000
	v_lshl_add_u64 v[214:215], s[36:37], 0, v[134:135]
	s_addc_u32 s77, s37, 0
	s_add_i32 s75, s57, s7
	global_load_lds_dwordx4 v[214:215], off
	v_lshl_add_u64 v[216:217], s[76:77], 0, v[130:131]
	s_mov_b32 m0, s75
	global_load_lds_dwordx4 v[216:217], off
	v_lshl_add_u64 v[216:217], s[76:77], 0, v[134:135]
	s_add_i32 m0, s75, 0x2000
	s_nop 0
	global_load_lds_dwordx4 v[216:217], off
	s_waitcnt vmcnt(8)
	s_waitcnt lgkmcnt(0)
	s_barrier
	s_waitcnt lgkmcnt(0)
	v_mfma_f32_16x16x32_bf16 v[60:63], v[140:143], v[180:183], v[60:63]
	v_mfma_f32_16x16x32_bf16 v[56:59], v[156:159], v[180:183], v[56:59]
	v_mfma_f32_16x16x32_bf16 v[44:47], v[140:143], v[188:191], v[44:47]
	v_mfma_f32_16x16x32_bf16 v[40:43], v[156:159], v[188:191], v[40:43]
	v_mfma_f32_16x16x32_bf16 v[28:31], v[140:143], v[196:199], v[28:31]
	v_mfma_f32_16x16x32_bf16 v[24:27], v[156:159], v[196:199], v[24:27]
	v_mfma_f32_16x16x32_bf16 v[12:15], v[140:143], v[204:207], v[12:15]
	v_mfma_f32_16x16x32_bf16 v[8:11], v[156:159], v[204:207], v[8:11]
	v_mfma_f32_16x16x32_bf16 v[60:63], v[144:147], v[184:187], v[60:63]
	v_mfma_f32_16x16x32_bf16 v[56:59], v[160:163], v[184:187], v[56:59]
	v_mfma_f32_16x16x32_bf16 v[44:47], v[144:147], v[192:195], v[44:47]
	v_mfma_f32_16x16x32_bf16 v[40:43], v[160:163], v[192:195], v[40:43]
	v_mfma_f32_16x16x32_bf16 v[28:31], v[144:147], v[200:203], v[28:31]
	v_mfma_f32_16x16x32_bf16 v[24:27], v[160:163], v[200:203], v[24:27]
	v_mfma_f32_16x16x32_bf16 v[12:15], v[144:147], v[208:211], v[12:15]
	v_mfma_f32_16x16x32_bf16 v[8:11], v[160:163], v[208:211], v[8:11]
	v_mfma_f32_16x16x32_bf16 v[52:55], v[164:167], v[180:183], v[52:55]
	v_mfma_f32_16x16x32_bf16 v[48:51], v[172:175], v[180:183], v[48:51]
	v_mfma_f32_16x16x32_bf16 v[36:39], v[164:167], v[188:191], v[36:39]
	v_mfma_f32_16x16x32_bf16 v[32:35], v[172:175], v[188:191], v[32:35]
	v_mfma_f32_16x16x32_bf16 v[20:23], v[164:167], v[196:199], v[20:23]
	v_mfma_f32_16x16x32_bf16 v[16:19], v[172:175], v[196:199], v[16:19]
	v_mfma_f32_16x16x32_bf16 v[4:7], v[164:167], v[204:207], v[4:7]
	v_mfma_f32_16x16x32_bf16 v[0:3], v[172:175], v[204:207], v[0:3]
	v_mfma_f32_16x16x32_bf16 v[52:55], v[168:171], v[184:187], v[52:55]
	v_mfma_f32_16x16x32_bf16 v[48:51], v[176:179], v[184:187], v[48:51]
	v_mfma_f32_16x16x32_bf16 v[36:39], v[168:171], v[192:195], v[36:39]
	v_mfma_f32_16x16x32_bf16 v[32:35], v[176:179], v[192:195], v[32:35]
	v_mfma_f32_16x16x32_bf16 v[20:23], v[168:171], v[200:203], v[20:23]
	v_mfma_f32_16x16x32_bf16 v[16:19], v[176:179], v[200:203], v[16:19]
	v_mfma_f32_16x16x32_bf16 v[4:7], v[168:171], v[208:211], v[4:7]
	v_mfma_f32_16x16x32_bf16 v[0:3], v[176:179], v[208:211], v[0:3]
	s_waitcnt vmcnt(4)
	s_barrier
	ds_read_b128 v[140:143], v153
	ds_read_b128 v[144:147], v153 offset:1024
	ds_read_b128 v[156:159], v153 offset:2048
	ds_read_b128 v[160:163], v153 offset:3072
	ds_read_b128 v[164:167], v154
	ds_read_b128 v[168:171], v154 offset:1024
	ds_read_b128 v[172:175], v154 offset:2048
	ds_read_b128 v[176:179], v154 offset:3072
	s_mov_b32 s98, s38
	s_mov_b32 s99, s39
	s_add_i32 m0, s85, 0
	ds_read_b128 v[180:183], v152 offset:32768
	ds_read_b128 v[184:187], v152 offset:33792
	ds_read_b128 v[188:191], v152 offset:34816
	ds_read_b128 v[192:195], v152 offset:35840
	ds_read_b128 v[196:199], v152 offset:36864
	ds_read_b128 v[200:203], v152 offset:37888
	ds_read_b128 v[204:207], v152 offset:38912
	ds_read_b128 v[208:211], v152 offset:39936
	global_load_lds_dwordx4 v222, s[98:99]
	s_add_u32 s98, s98, 0x20000
	s_addc_u32 s99, s99, 0
	s_add_i32 m0, s85, 0x1000
	s_nop 0
	global_load_lds_dwordx4 v222, s[98:99]
	s_add_u32 s98, s98, 0x20000
	s_addc_u32 s99, s99, 0
	s_add_i32 m0, s85, 0x2000
	s_nop 0
	global_load_lds_dwordx4 v222, s[98:99]
	s_add_u32 s98, s98, 0x20000
	s_addc_u32 s99, s99, 0
	s_add_i32 m0, s85, 0x3000
	s_nop 0
	global_load_lds_dwordx4 v222, s[98:99]
	s_waitcnt vmcnt(8)
	s_waitcnt lgkmcnt(0)
	s_barrier
	s_waitcnt lgkmcnt(0)
	v_mfma_f32_16x16x32_bf16 v[124:127], v[140:143], v[180:183], v[124:127]
	v_mfma_f32_16x16x32_bf16 v[120:123], v[156:159], v[180:183], v[120:123]
	v_mfma_f32_16x16x32_bf16 v[108:111], v[140:143], v[188:191], v[108:111]
	v_mfma_f32_16x16x32_bf16 v[104:107], v[156:159], v[188:191], v[104:107]
	v_mfma_f32_16x16x32_bf16 v[92:95], v[140:143], v[196:199], v[92:95]
	v_mfma_f32_16x16x32_bf16 v[88:91], v[156:159], v[196:199], v[88:91]
	v_mfma_f32_16x16x32_bf16 v[76:79], v[140:143], v[204:207], v[76:79]
	v_mfma_f32_16x16x32_bf16 v[72:75], v[156:159], v[204:207], v[72:75]
	v_mfma_f32_16x16x32_bf16 v[124:127], v[144:147], v[184:187], v[124:127]
	v_mfma_f32_16x16x32_bf16 v[120:123], v[160:163], v[184:187], v[120:123]
	v_mfma_f32_16x16x32_bf16 v[108:111], v[144:147], v[192:195], v[108:111]
	v_mfma_f32_16x16x32_bf16 v[104:107], v[160:163], v[192:195], v[104:107]
	v_mfma_f32_16x16x32_bf16 v[92:95], v[144:147], v[200:203], v[92:95]
	v_mfma_f32_16x16x32_bf16 v[88:91], v[160:163], v[200:203], v[88:91]
	v_mfma_f32_16x16x32_bf16 v[76:79], v[144:147], v[208:211], v[76:79]
	v_mfma_f32_16x16x32_bf16 v[72:75], v[160:163], v[208:211], v[72:75]
	v_mfma_f32_16x16x32_bf16 v[116:119], v[164:167], v[180:183], v[116:119]
	v_mfma_f32_16x16x32_bf16 v[112:115], v[172:175], v[180:183], v[112:115]
	v_mfma_f32_16x16x32_bf16 v[100:103], v[164:167], v[188:191], v[100:103]
	v_mfma_f32_16x16x32_bf16 v[96:99], v[172:175], v[188:191], v[96:99]
	v_mfma_f32_16x16x32_bf16 v[84:87], v[164:167], v[196:199], v[84:87]
	v_mfma_f32_16x16x32_bf16 v[80:83], v[172:175], v[196:199], v[80:83]
	v_mfma_f32_16x16x32_bf16 v[68:71], v[164:167], v[204:207], v[68:71]
	v_mfma_f32_16x16x32_bf16 v[64:67], v[172:175], v[204:207], v[64:67]
	v_mfma_f32_16x16x32_bf16 v[116:119], v[168:171], v[184:187], v[116:119]
	v_mfma_f32_16x16x32_bf16 v[112:115], v[176:179], v[184:187], v[112:115]
	v_mfma_f32_16x16x32_bf16 v[100:103], v[168:171], v[192:195], v[100:103]
	v_mfma_f32_16x16x32_bf16 v[96:99], v[176:179], v[192:195], v[96:99]
	v_mfma_f32_16x16x32_bf16 v[84:87], v[168:171], v[200:203], v[84:87]
	v_mfma_f32_16x16x32_bf16 v[80:83], v[176:179], v[200:203], v[80:83]
	v_mfma_f32_16x16x32_bf16 v[68:71], v[168:171], v[208:211], v[68:71]
	v_mfma_f32_16x16x32_bf16 v[64:67], v[176:179], v[208:211], v[64:67]
	s_barrier
	s_add_i32 s38, s58, s7
	v_lshl_add_u64 v[212:213], v[212:213], 0, s[14:15]
	s_mov_b32 m0, s38
	ds_read_b128 v[180:183], v152 offset:49152
	ds_read_b128 v[184:187], v152 offset:50176
	ds_read_b128 v[188:191], v152 offset:51200
	ds_read_b128 v[192:195], v152 offset:52224
	ds_read_b128 v[196:199], v152 offset:53248
	ds_read_b128 v[200:203], v152 offset:54272
	ds_read_b128 v[204:207], v152 offset:55296
	ds_read_b128 v[208:211], v152 offset:56320
	global_load_lds_dwordx4 v[212:213], off
	s_add_i32 m0, s38, 0x2000
	s_add_u32 s36, s36, 0x80080
	v_lshl_add_u64 v[212:213], v[214:215], 0, s[14:15]
	s_addc_u32 s37, s37, 0
	s_add_i32 s38, s59, s7
	global_load_lds_dwordx4 v[212:213], off
	v_lshl_add_u64 v[212:213], s[36:37], 0, v[130:131]
	s_mov_b32 m0, s38
	s_nop 0
	global_load_lds_dwordx4 v[212:213], off
	v_lshl_add_u64 v[212:213], s[36:37], 0, v[134:135]
	s_add_i32 m0, s38, 0x2000
	s_nop 0
	global_load_lds_dwordx4 v[212:213], off
	s_waitcnt vmcnt(8)
	s_waitcnt lgkmcnt(0)
	s_barrier
	s_waitcnt lgkmcnt(0)
	v_mfma_f32_16x16x32_bf16 v[60:63], v[140:143], v[180:183], v[60:63]
	v_mfma_f32_16x16x32_bf16 v[56:59], v[156:159], v[180:183], v[56:59]
	v_mfma_f32_16x16x32_bf16 v[44:47], v[140:143], v[188:191], v[44:47]
	v_mfma_f32_16x16x32_bf16 v[40:43], v[156:159], v[188:191], v[40:43]
	v_mfma_f32_16x16x32_bf16 v[28:31], v[140:143], v[196:199], v[28:31]
	v_mfma_f32_16x16x32_bf16 v[24:27], v[156:159], v[196:199], v[24:27]
	v_mfma_f32_16x16x32_bf16 v[12:15], v[140:143], v[204:207], v[12:15]
	v_mfma_f32_16x16x32_bf16 v[8:11], v[156:159], v[204:207], v[8:11]
	v_mfma_f32_16x16x32_bf16 v[60:63], v[144:147], v[184:187], v[60:63]
	v_mfma_f32_16x16x32_bf16 v[56:59], v[160:163], v[184:187], v[56:59]
	v_mfma_f32_16x16x32_bf16 v[44:47], v[144:147], v[192:195], v[44:47]
	v_mfma_f32_16x16x32_bf16 v[40:43], v[160:163], v[192:195], v[40:43]
	v_mfma_f32_16x16x32_bf16 v[28:31], v[144:147], v[200:203], v[28:31]
	v_mfma_f32_16x16x32_bf16 v[24:27], v[160:163], v[200:203], v[24:27]
	v_mfma_f32_16x16x32_bf16 v[12:15], v[144:147], v[208:211], v[12:15]
	v_mfma_f32_16x16x32_bf16 v[8:11], v[160:163], v[208:211], v[8:11]
	v_mfma_f32_16x16x32_bf16 v[52:55], v[164:167], v[180:183], v[52:55]
	v_mfma_f32_16x16x32_bf16 v[48:51], v[172:175], v[180:183], v[48:51]
	v_mfma_f32_16x16x32_bf16 v[36:39], v[164:167], v[188:191], v[36:39]
	v_mfma_f32_16x16x32_bf16 v[32:35], v[172:175], v[188:191], v[32:35]
	v_mfma_f32_16x16x32_bf16 v[20:23], v[164:167], v[196:199], v[20:23]
	v_mfma_f32_16x16x32_bf16 v[16:19], v[172:175], v[196:199], v[16:19]
	v_mfma_f32_16x16x32_bf16 v[4:7], v[164:167], v[204:207], v[4:7]
	v_mfma_f32_16x16x32_bf16 v[0:3], v[172:175], v[204:207], v[0:3]
	v_mfma_f32_16x16x32_bf16 v[52:55], v[168:171], v[184:187], v[52:55]
	v_mfma_f32_16x16x32_bf16 v[48:51], v[176:179], v[184:187], v[48:51]
	v_mfma_f32_16x16x32_bf16 v[36:39], v[168:171], v[192:195], v[36:39]
	v_mfma_f32_16x16x32_bf16 v[32:35], v[176:179], v[192:195], v[32:35]
	v_mfma_f32_16x16x32_bf16 v[20:23], v[168:171], v[200:203], v[20:23]
	v_mfma_f32_16x16x32_bf16 v[16:19], v[176:179], v[200:203], v[16:19]
	v_mfma_f32_16x16x32_bf16 v[4:7], v[168:171], v[208:211], v[4:7]
	v_mfma_f32_16x16x32_bf16 v[0:3], v[176:179], v[208:211], v[0:3]
	s_waitcnt vmcnt(4)
	s_barrier
	s_add_i32 s74, s74, 2
	s_add_u32 s0, s0, 0x100
	s_addc_u32 s1, s1, 0
	s_add_u32 s72, s72, 0x100
	s_addc_u32 s73, s73, 0
	s_cmp_gt_u32 s74, 29
	s_cbranch_scc0 .LBB0_1955
	s_setprio 0
	s_and_b64 vcc, exec, s[16:17]
	s_cbranch_vccz .LBB0_1958
	s_barrier

.LBB0_2062:
	s_mov_b64 s[22:23], s[12:13]
	s_add_u32 s56, s22, 0x100
	s_addc_u32 s57, s23, 0
	s_add_i32 s54, s55, 1
	s_lshl_b32 s12, s54, 5
	s_add_i32 s12, s12, s30
	s_cmp_lt_i32 s12, 32
	s_cselect_b64 s[20:21], -1, 0
	s_cmp_gt_i32 s12, 31
	s_mov_b32 s16, s53
	s_cselect_b64 s[14:15], -1, 0
	s_ashr_i32 s53, s12, 2
	s_and_b64 s[12:13], s[20:21], exec
	s_cselect_b32 s12, s53, s16
	s_cselect_b32 s16, s34, s34
	s_ashr_i32 s17, s16, 31
	s_lshl_b64 s[16:17], s[16:17], 22
	s_add_u32 s16, s31, s16
	s_addc_u32 s17, s35, s17
	s_and_b64 s[24:25], s[20:21], exec
	s_cselect_b32 s58, s17, s19
	s_cselect_b32 s59, s16, s18
	s_ashr_i32 s13, s12, 31
	s_lshl_b64 s[12:13], s[12:13], 22
	s_add_u32 s12, s36, s12
	s_addc_u32 s13, s37, s13
	s_and_b64 s[24:25], s[20:21], exec
	s_cselect_b32 s60, s13, s23
	s_cselect_b32 s61, s12, s22
	v_lshl_add_u64 v[140:141], s[18:19], 0, v[136:137]
	v_lshl_add_u64 v[142:143], s[18:19], 0, v[138:139]
	s_lshr_b32 s84, s88, 2
	s_mul_i32 s85, s84, 0x3000
	s_add_i32 s85, s85, s1
	s_mul_i32 s96, s84, 0x180000
	s_mov_b32 s97, 0
	s_sub_u32 s86, s96, 0x200000
	s_subb_u32 s87, 0, 0
	s_mov_b32 s62, -2
	s_mov_b64 s[22:23], 0
	s_lshr_b32 s101, s88, 2
	s_cmp_lg_u32 s101, 1
	s_cbranch_scc1 .Lprio_skip14
	s_setprio 1
.Lprio_skip14:
.LBB0_2063:
	v_add_u32_e32 v147, s33, v145
	ds_read_b128 v[148:151], v147
	ds_read_b128 v[152:155], v147 offset:1024
	ds_read_b128 v[156:159], v147 offset:2048
	ds_read_b128 v[160:163], v147 offset:3072
	v_add_u32_e32 v147, s45, v145
	s_add_u32 s24, s18, s22
	ds_read_b128 v[164:167], v147
	ds_read_b128 v[168:171], v147 offset:1024
	ds_read_b128 v[172:175], v147 offset:2048
	ds_read_b128 v[176:179], v147 offset:3072
	s_addc_u32 s25, s19, s23
	s_add_u32 s24, s24, 0x100
	s_addc_u32 s25, s25, 0
	s_add_u32 s63, s56, s22
	s_addc_u32 s64, s57, s23
	s_cmpk_eq_i32 s22, 0x3f00
	s_cselect_b32 s27, s58, s25
	s_cselect_b32 s26, s59, s24
	s_cselect_b32 s25, s60, s64
	s_cselect_b32 s24, s61, s63
	s_add_u32 s98, s22, s86
	s_addc_u32 s99, s23, s87
	s_add_i32 m0, s85, 0x8000
	v_lshl_add_u64 v[214:215], v[140:141], 0, s[98:99]
	ds_read_b128 v[180:183], v146
	ds_read_b128 v[184:187], v146 offset:1024
	ds_read_b128 v[188:191], v146 offset:2048
	ds_read_b128 v[192:195], v146 offset:3072
	ds_read_b128 v[196:199], v146 offset:4096
	ds_read_b128 v[202:205], v146 offset:5120
	ds_read_b128 v[206:209], v146 offset:6144
	ds_read_b128 v[210:213], v146 offset:7168
	global_load_lds_dwordx4 v[214:215], off
	s_add_u32 s98, s98, 0x80000
	s_addc_u32 s99, s99, 0
	s_add_i32 m0, s85, 0x9000
	v_lshl_add_u64 v[214:215], v[140:141], 0, s[98:99]
	global_load_lds_dwordx4 v[214:215], off
	s_add_u32 s98, s98, 0x80000
	s_addc_u32 s99, s99, 0
	s_add_i32 m0, s85, 0xa000
	v_lshl_add_u64 v[214:215], v[140:141], 0, s[98:99]
	global_load_lds_dwordx4 v[214:215], off
	s_add_u32 s98, s98, 0x80000
	s_addc_u32 s99, s99, 0
	s_add_i32 m0, s85, 0xb000
	v_lshl_add_u64 v[214:215], v[140:141], 0, s[98:99]
	global_load_lds_dwordx4 v[214:215], off
	s_waitcnt vmcnt(8)
	s_waitcnt lgkmcnt(0)
	s_barrier
	s_waitcnt lgkmcnt(0)
	v_mfma_f32_16x16x32_bf16 v[124:127], v[148:151], v[180:183], v[124:127]
	v_mfma_f32_16x16x32_bf16 v[120:123], v[156:159], v[180:183], v[120:123]
	v_mfma_f32_16x16x32_bf16 v[108:111], v[148:151], v[188:191], v[108:111]
	v_mfma_f32_16x16x32_bf16 v[104:107], v[156:159], v[188:191], v[104:107]
	v_mfma_f32_16x16x32_bf16 v[92:95], v[148:151], v[196:199], v[92:95]
	v_mfma_f32_16x16x32_bf16 v[88:91], v[156:159], v[196:199], v[88:91]
	v_mfma_f32_16x16x32_bf16 v[76:79], v[148:151], v[206:209], v[76:79]
	v_mfma_f32_16x16x32_bf16 v[72:75], v[156:159], v[206:209], v[72:75]
	v_mfma_f32_16x16x32_bf16 v[124:127], v[152:155], v[184:187], v[124:127]
	v_mfma_f32_16x16x32_bf16 v[120:123], v[160:163], v[184:187], v[120:123]
	v_mfma_f32_16x16x32_bf16 v[108:111], v[152:155], v[192:195], v[108:111]
	v_mfma_f32_16x16x32_bf16 v[104:107], v[160:163], v[192:195], v[104:107]
	v_mfma_f32_16x16x32_bf16 v[92:95], v[152:155], v[202:205], v[92:95]
	v_mfma_f32_16x16x32_bf16 v[88:91], v[160:163], v[202:205], v[88:91]
	v_mfma_f32_16x16x32_bf16 v[76:79], v[152:155], v[210:213], v[76:79]
	v_mfma_f32_16x16x32_bf16 v[72:75], v[160:163], v[210:213], v[72:75]
	v_mfma_f32_16x16x32_bf16 v[116:119], v[164:167], v[180:183], v[116:119]
	v_mfma_f32_16x16x32_bf16 v[112:115], v[172:175], v[180:183], v[112:115]
	v_mfma_f32_16x16x32_bf16 v[100:103], v[164:167], v[188:191], v[100:103]
	v_mfma_f32_16x16x32_bf16 v[96:99], v[172:175], v[188:191], v[96:99]
	v_mfma_f32_16x16x32_bf16 v[84:87], v[164:167], v[196:199], v[84:87]
	v_mfma_f32_16x16x32_bf16 v[80:83], v[172:175], v[196:199], v[80:83]
	v_mfma_f32_16x16x32_bf16 v[68:71], v[164:167], v[206:209], v[68:71]
	v_mfma_f32_16x16x32_bf16 v[64:67], v[172:175], v[206:209], v[64:67]
	v_mfma_f32_16x16x32_bf16 v[116:119], v[168:171], v[184:187], v[116:119]
	v_mfma_f32_16x16x32_bf16 v[112:115], v[176:179], v[184:187], v[112:115]
	v_mfma_f32_16x16x32_bf16 v[100:103], v[168:171], v[192:195], v[100:103]
	v_mfma_f32_16x16x32_bf16 v[96:99], v[176:179], v[192:195], v[96:99]
	v_mfma_f32_16x16x32_bf16 v[84:87], v[168:171], v[202:205], v[84:87]
	v_mfma_f32_16x16x32_bf16 v[80:83], v[176:179], v[202:205], v[80:83]
	v_mfma_f32_16x16x32_bf16 v[68:71], v[168:171], v[210:213], v[68:71]
	v_mfma_f32_16x16x32_bf16 v[64:67], v[176:179], v[210:213], v[64:67]
	s_barrier
	s_mov_b32 m0, s48
	v_lshl_add_u64 v[214:215], s[24:25], 0, v[132:133]
	s_add_u32 s64, s24, 0x200000
	ds_read_b128 v[180:183], v146 offset:16384
	ds_read_b128 v[184:187], v146 offset:17408
	ds_read_b128 v[188:191], v146 offset:18432
	ds_read_b128 v[192:195], v146 offset:19456
	ds_read_b128 v[196:199], v146 offset:20480
	ds_read_b128 v[202:205], v146 offset:21504
	ds_read_b128 v[206:209], v146 offset:22528
	ds_read_b128 v[210:213], v146 offset:23552
	global_load_lds_dwordx4 v[214:215], off
	v_lshl_add_u64 v[216:217], s[24:25], 0, v[128:129]
	s_mov_b32 m0, s49
	s_addc_u32 s65, s25, 0
	global_load_lds_dwordx4 v[216:217], off
	v_lshl_add_u64 v[218:219], s[64:65], 0, v[132:133]
	s_mov_b32 m0, s50
	global_load_lds_dwordx4 v[218:219], off
	v_lshl_add_u64 v[218:219], s[64:65], 0, v[128:129]
	s_mov_b32 m0, s51
	s_nop 0
	global_load_lds_dwordx4 v[218:219], off
	s_waitcnt vmcnt(8)
	s_waitcnt lgkmcnt(0)
	s_barrier
	s_waitcnt lgkmcnt(0)
	v_mfma_f32_16x16x32_bf16 v[60:63], v[148:151], v[180:183], v[60:63]
	v_mfma_f32_16x16x32_bf16 v[56:59], v[156:159], v[180:183], v[56:59]
	v_mfma_f32_16x16x32_bf16 v[44:47], v[148:151], v[188:191], v[44:47]
	v_mfma_f32_16x16x32_bf16 v[40:43], v[156:159], v[188:191], v[40:43]
	v_mfma_f32_16x16x32_bf16 v[28:31], v[148:151], v[196:199], v[28:31]
	v_mfma_f32_16x16x32_bf16 v[24:27], v[156:159], v[196:199], v[24:27]
	v_mfma_f32_16x16x32_bf16 v[12:15], v[148:151], v[206:209], v[12:15]
	v_mfma_f32_16x16x32_bf16 v[8:11], v[156:159], v[206:209], v[8:11]
	v_mfma_f32_16x16x32_bf16 v[60:63], v[152:155], v[184:187], v[60:63]
	v_mfma_f32_16x16x32_bf16 v[56:59], v[160:163], v[184:187], v[56:59]
	v_mfma_f32_16x16x32_bf16 v[44:47], v[152:155], v[192:195], v[44:47]
	v_mfma_f32_16x16x32_bf16 v[40:43], v[160:163], v[192:195], v[40:43]
	v_mfma_f32_16x16x32_bf16 v[28:31], v[152:155], v[202:205], v[28:31]
	v_mfma_f32_16x16x32_bf16 v[24:27], v[160:163], v[202:205], v[24:27]
	v_mfma_f32_16x16x32_bf16 v[12:15], v[152:155], v[210:213], v[12:15]
	v_mfma_f32_16x16x32_bf16 v[8:11], v[160:163], v[210:213], v[8:11]
	v_mfma_f32_16x16x32_bf16 v[52:55], v[164:167], v[180:183], v[52:55]
	v_mfma_f32_16x16x32_bf16 v[48:51], v[172:175], v[180:183], v[48:51]
	v_mfma_f32_16x16x32_bf16 v[36:39], v[164:167], v[188:191], v[36:39]
	v_mfma_f32_16x16x32_bf16 v[32:35], v[172:175], v[188:191], v[32:35]
	v_mfma_f32_16x16x32_bf16 v[20:23], v[164:167], v[196:199], v[20:23]
	v_mfma_f32_16x16x32_bf16 v[16:19], v[172:175], v[196:199], v[16:19]
	v_mfma_f32_16x16x32_bf16 v[4:7], v[164:167], v[206:209], v[4:7]
	v_mfma_f32_16x16x32_bf16 v[0:3], v[172:175], v[206:209], v[0:3]
	v_mfma_f32_16x16x32_bf16 v[52:55], v[168:171], v[184:187], v[52:55]
	v_mfma_f32_16x16x32_bf16 v[48:51], v[176:179], v[184:187], v[48:51]
	v_mfma_f32_16x16x32_bf16 v[36:39], v[168:171], v[192:195], v[36:39]
	v_mfma_f32_16x16x32_bf16 v[32:35], v[176:179], v[192:195], v[32:35]
	v_mfma_f32_16x16x32_bf16 v[20:23], v[168:171], v[202:205], v[20:23]
	v_mfma_f32_16x16x32_bf16 v[16:19], v[176:179], v[202:205], v[16:19]
	v_mfma_f32_16x16x32_bf16 v[4:7], v[168:171], v[210:213], v[4:7]
	v_mfma_f32_16x16x32_bf16 v[0:3], v[176:179], v[210:213], v[0:3]
	s_waitcnt vmcnt(4)
	s_barrier
	v_add_u32_e32 v147, s52, v145
	s_add_i32 s63, 0, 0x1c000
	ds_read_b128 v[148:151], v147
	ds_read_b128 v[152:155], v147 offset:1024
	ds_read_b128 v[156:159], v147 offset:2048
	ds_read_b128 v[160:163], v147 offset:3072
	v_add_u32_e32 v147, s63, v145
	ds_read_b128 v[164:167], v147
	ds_read_b128 v[168:171], v147 offset:1024
	ds_read_b128 v[172:175], v147 offset:2048
	ds_read_b128 v[176:179], v147 offset:3072
	s_add_u32 s98, s26, s96
	s_addc_u32 s99, s27, s97
	s_add_i32 m0, s85, 0
	v_lshl_add_u64 v[222:223], s[98:99], 0, v[134:135]
	ds_read_b128 v[180:183], v146 offset:32768
	ds_read_b128 v[184:187], v146 offset:33792
	ds_read_b128 v[188:191], v146 offset:34816
	ds_read_b128 v[192:195], v146 offset:35840
	ds_read_b128 v[196:199], v146 offset:36864
	ds_read_b128 v[202:205], v146 offset:37888
	ds_read_b128 v[206:209], v146 offset:38912
	ds_read_b128 v[210:213], v146 offset:39936
	global_load_lds_dwordx4 v[222:223], off
	s_add_u32 s98, s98, 0x80000
	s_addc_u32 s99, s99, 0
	s_add_i32 m0, s85, 0x1000
	v_lshl_add_u64 v[222:223], s[98:99], 0, v[134:135]
	global_load_lds_dwordx4 v[222:223], off
	s_add_u32 s98, s98, 0x80000
	s_addc_u32 s99, s99, 0
	s_add_i32 m0, s85, 0x2000
	v_lshl_add_u64 v[222:223], s[98:99], 0, v[134:135]
	global_load_lds_dwordx4 v[222:223], off
	s_add_u32 s98, s98, 0x80000
	s_addc_u32 s99, s99, 0
	s_add_i32 m0, s85, 0x3000
	v_lshl_add_u64 v[222:223], s[98:99], 0, v[134:135]
	global_load_lds_dwordx4 v[222:223], off
	s_waitcnt vmcnt(8)
	s_waitcnt lgkmcnt(0)
	s_barrier
	s_waitcnt lgkmcnt(0)
	v_mfma_f32_16x16x32_bf16 v[124:127], v[148:151], v[180:183], v[124:127]
	v_mfma_f32_16x16x32_bf16 v[120:123], v[156:159], v[180:183], v[120:123]
	v_mfma_f32_16x16x32_bf16 v[108:111], v[148:151], v[188:191], v[108:111]
	v_mfma_f32_16x16x32_bf16 v[104:107], v[156:159], v[188:191], v[104:107]
	v_mfma_f32_16x16x32_bf16 v[92:95], v[148:151], v[196:199], v[92:95]
	v_mfma_f32_16x16x32_bf16 v[88:91], v[156:159], v[196:199], v[88:91]
	v_mfma_f32_16x16x32_bf16 v[76:79], v[148:151], v[206:209], v[76:79]
	v_mfma_f32_16x16x32_bf16 v[72:75], v[156:159], v[206:209], v[72:75]
	v_mfma_f32_16x16x32_bf16 v[124:127], v[152:155], v[184:187], v[124:127]
	v_mfma_f32_16x16x32_bf16 v[120:123], v[160:163], v[184:187], v[120:123]
	v_mfma_f32_16x16x32_bf16 v[108:111], v[152:155], v[192:195], v[108:111]
	v_mfma_f32_16x16x32_bf16 v[104:107], v[160:163], v[192:195], v[104:107]
	v_mfma_f32_16x16x32_bf16 v[92:95], v[152:155], v[202:205], v[92:95]
	v_mfma_f32_16x16x32_bf16 v[88:91], v[160:163], v[202:205], v[88:91]
	v_mfma_f32_16x16x32_bf16 v[76:79], v[152:155], v[210:213], v[76:79]
	v_mfma_f32_16x16x32_bf16 v[72:75], v[160:163], v[210:213], v[72:75]
	v_mfma_f32_16x16x32_bf16 v[116:119], v[164:167], v[180:183], v[116:119]
	v_mfma_f32_16x16x32_bf16 v[112:115], v[172:175], v[180:183], v[112:115]
	v_mfma_f32_16x16x32_bf16 v[100:103], v[164:167], v[188:191], v[100:103]
	v_mfma_f32_16x16x32_bf16 v[96:99], v[172:175], v[188:191], v[96:99]
	v_mfma_f32_16x16x32_bf16 v[84:87], v[164:167], v[196:199], v[84:87]
	v_mfma_f32_16x16x32_bf16 v[80:83], v[172:175], v[196:199], v[80:83]
	v_mfma_f32_16x16x32_bf16 v[68:71], v[164:167], v[206:209], v[68:71]
	v_mfma_f32_16x16x32_bf16 v[64:67], v[172:175], v[206:209], v[64:67]
	v_mfma_f32_16x16x32_bf16 v[116:119], v[168:171], v[184:187], v[116:119]
	v_mfma_f32_16x16x32_bf16 v[112:115], v[176:179], v[184:187], v[112:115]
	v_mfma_f32_16x16x32_bf16 v[100:103], v[168:171], v[192:195], v[100:103]
	v_mfma_f32_16x16x32_bf16 v[96:99], v[176:179], v[192:195], v[96:99]
	v_mfma_f32_16x16x32_bf16 v[84:87], v[168:171], v[202:205], v[84:87]
	v_mfma_f32_16x16x32_bf16 v[80:83], v[176:179], v[202:205], v[80:83]
	v_mfma_f32_16x16x32_bf16 v[68:71], v[168:171], v[210:213], v[68:71]
	v_mfma_f32_16x16x32_bf16 v[64:67], v[176:179], v[210:213], v[64:67]
	s_barrier
	s_add_i32 s26, s52, s38
	v_lshl_add_u64 v[214:215], v[214:215], 0, s[8:9]
	s_mov_b32 m0, s26
	ds_read_b128 v[180:183], v146 offset:49152
	ds_read_b128 v[184:187], v146 offset:50176
	ds_read_b128 v[188:191], v146 offset:51200
	ds_read_b128 v[192:195], v146 offset:52224
	ds_read_b128 v[196:199], v146 offset:53248
	ds_read_b128 v[202:205], v146 offset:54272
	ds_read_b128 v[206:209], v146 offset:55296
	ds_read_b128 v[210:213], v146 offset:56320
	global_load_lds_dwordx4 v[214:215], off
	s_add_i32 m0, s26, 0x2000
	s_add_u32 s24, s24, 0x200080
	v_lshl_add_u64 v[214:215], v[216:217], 0, s[8:9]
	s_addc_u32 s25, s25, 0
	s_add_i32 s26, s63, s38
	global_load_lds_dwordx4 v[214:215], off
	v_lshl_add_u64 v[214:215], s[24:25], 0, v[132:133]
	s_mov_b32 m0, s26
	s_nop 0
	global_load_lds_dwordx4 v[214:215], off
	v_lshl_add_u64 v[214:215], s[24:25], 0, v[128:129]
	s_add_i32 m0, s26, 0x2000
	s_nop 0
	global_load_lds_dwordx4 v[214:215], off
	s_waitcnt vmcnt(8)
	s_waitcnt lgkmcnt(0)
	s_barrier
	s_waitcnt lgkmcnt(0)
	v_mfma_f32_16x16x32_bf16 v[60:63], v[148:151], v[180:183], v[60:63]
	v_mfma_f32_16x16x32_bf16 v[56:59], v[156:159], v[180:183], v[56:59]
	v_mfma_f32_16x16x32_bf16 v[44:47], v[148:151], v[188:191], v[44:47]
	v_mfma_f32_16x16x32_bf16 v[40:43], v[156:159], v[188:191], v[40:43]
	v_mfma_f32_16x16x32_bf16 v[28:31], v[148:151], v[196:199], v[28:31]
	v_mfma_f32_16x16x32_bf16 v[24:27], v[156:159], v[196:199], v[24:27]
	v_mfma_f32_16x16x32_bf16 v[12:15], v[148:151], v[206:209], v[12:15]
	v_mfma_f32_16x16x32_bf16 v[8:11], v[156:159], v[206:209], v[8:11]
	v_mfma_f32_16x16x32_bf16 v[60:63], v[152:155], v[184:187], v[60:63]
	v_mfma_f32_16x16x32_bf16 v[56:59], v[160:163], v[184:187], v[56:59]
	v_mfma_f32_16x16x32_bf16 v[44:47], v[152:155], v[192:195], v[44:47]
	v_mfma_f32_16x16x32_bf16 v[40:43], v[160:163], v[192:195], v[40:43]
	v_mfma_f32_16x16x32_bf16 v[28:31], v[152:155], v[202:205], v[28:31]
	v_mfma_f32_16x16x32_bf16 v[24:27], v[160:163], v[202:205], v[24:27]
	v_mfma_f32_16x16x32_bf16 v[12:15], v[152:155], v[210:213], v[12:15]
	v_mfma_f32_16x16x32_bf16 v[8:11], v[160:163], v[210:213], v[8:11]
	v_mfma_f32_16x16x32_bf16 v[52:55], v[164:167], v[180:183], v[52:55]
	v_mfma_f32_16x16x32_bf16 v[48:51], v[172:175], v[180:183], v[48:51]
	v_mfma_f32_16x16x32_bf16 v[36:39], v[164:167], v[188:191], v[36:39]
	v_mfma_f32_16x16x32_bf16 v[32:35], v[172:175], v[188:191], v[32:35]
	v_mfma_f32_16x16x32_bf16 v[20:23], v[164:167], v[196:199], v[20:23]
	v_mfma_f32_16x16x32_bf16 v[16:19], v[172:175], v[196:199], v[16:19]
	v_mfma_f32_16x16x32_bf16 v[4:7], v[164:167], v[206:209], v[4:7]
	v_mfma_f32_16x16x32_bf16 v[0:3], v[172:175], v[206:209], v[0:3]
	v_mfma_f32_16x16x32_bf16 v[52:55], v[168:171], v[184:187], v[52:55]
	v_mfma_f32_16x16x32_bf16 v[48:51], v[176:179], v[184:187], v[48:51]
	v_mfma_f32_16x16x32_bf16 v[36:39], v[168:171], v[192:195], v[36:39]
	v_mfma_f32_16x16x32_bf16 v[32:35], v[176:179], v[192:195], v[32:35]
	v_mfma_f32_16x16x32_bf16 v[20:23], v[168:171], v[202:205], v[20:23]
	v_mfma_f32_16x16x32_bf16 v[16:19], v[176:179], v[202:205], v[16:19]
	v_mfma_f32_16x16x32_bf16 v[4:7], v[168:171], v[210:213], v[4:7]
	v_mfma_f32_16x16x32_bf16 v[0:3], v[176:179], v[210:213], v[0:3]
	s_waitcnt vmcnt(4)
	s_barrier
	s_add_i32 s62, s62, 2
	s_add_u32 s22, s22, 0x100
	s_addc_u32 s23, s23, 0
	s_cmpk_gt_u32 s62, 0x7d
	s_cbranch_scc0 .LBB0_2063
	s_setprio 0
	s_and_b64 vcc, exec, s[10:11]
	s_cbranch_vccz .LBB0_2066
	s_barrier
